# gdn_prep triangular solve: software-pipelined LDS reads (rhs reads one row ahead, 7 A-row buffers in flight, next row's first reads issued before the reduction); same FMA order
# speedup vs baseline: 1.0215x; 1.0117x over previous
.LBB0_807:
	s_or_b64 exec, exec, s[0:1]
	v_lshl_add_u32 v11, v1, 2, s76
	ds_read_u16 v238, v18 offset:544
	ds_read_b32 v239, v16 offset:8
	ds_read_b32 v254, v15 offset:8
	ds_read_b128 v[240:243], v11 offset:256
	s_waitcnt lgkmcnt(0)
	v_fma_f32 v4, v2, v240, 0
	ds_read_b128 v[240:243], v11 offset:512
	v_sub_f32_e32 v3, v3, v4
	v_lshlrev_b32_e32 v4, 16, v238
	v_mul_f32_e32 v4, v239, v4
	s_and_saveexec_b64 s[0:1], s[16:17]
	s_cbranch_execz .LBB0_809
	v_mul_f32_e32 v4, v4, v254
.LBB0_809:
	s_or_b64 exec, exec, s[0:1]
	ds_read_u16 v238, v18 offset:816
	ds_read_b32 v239, v16 offset:12
	ds_read_b32 v254, v15 offset:12
	s_waitcnt lgkmcnt(3)
	v_fma_f32 v5, v2, v240, 0
	v_fma_f32 v6, v3, v241, 0
	ds_read_b128 v[240:243], v11 offset:768
	v_add_f32_e32 v5, v5, v6
	v_sub_f32_e32 v4, v4, v5
	s_waitcnt lgkmcnt(1)
	v_lshlrev_b32_e32 v5, 16, v238
	v_mul_f32_e32 v5, v239, v5
	s_and_saveexec_b64 s[0:1], s[16:17]
	s_cbranch_execz .LBB0_811
	v_mul_f32_e32 v5, v5, v254
.LBB0_811:
	s_or_b64 exec, exec, s[0:1]
	ds_read_u16 v238, v18 offset:1088
	ds_read_b32 v239, v16 offset:16
	ds_read_b32 v254, v15 offset:16
	s_waitcnt lgkmcnt(3)
	v_fma_f32 v6, v2, v240, 0
	v_fma_f32 v7, v3, v241, 0
	v_fma_f32 v8, v4, v242, 0
	ds_read_b128 v[240:243], v11 offset:1024
	v_add_f32_e32 v6, v6, v7
	v_add_f32_e32 v6, v8, v6
	v_sub_f32_e32 v5, v5, v6
	s_waitcnt lgkmcnt(1)
	v_lshlrev_b32_e32 v6, 16, v238
	v_mul_f32_e32 v6, v239, v6
	s_and_saveexec_b64 s[0:1], s[16:17]
	s_cbranch_execz .LBB0_813
	v_mul_f32_e32 v6, v6, v254
.LBB0_813:
	s_or_b64 exec, exec, s[0:1]
	ds_read_u16 v238, v18 offset:1360
	ds_read_b32 v239, v16 offset:20
	ds_read_b32 v254, v15 offset:20
	s_waitcnt lgkmcnt(3)
	v_fma_f32 v7, v2, v240, 0
	v_fma_f32 v8, v3, v241, 0
	v_fma_f32 v9, v4, v242, 0
	v_fma_f32 v10, v5, v243, 0
	ds_read_b128 v[240:243], v11 offset:1280
	ds_read_b128 v[244:247], v11 offset:1296
	v_add_f32_e32 v7, v7, v8
	v_add_f32_e32 v8, v9, v10
	v_add_f32_e32 v7, v7, v8
	v_sub_f32_e32 v6, v6, v7
	s_waitcnt lgkmcnt(2)
	v_lshlrev_b32_e32 v7, 16, v238
	v_mul_f32_e32 v7, v239, v7
	s_and_saveexec_b64 s[0:1], s[16:17]
	s_cbranch_execz .LBB0_815
	v_mul_f32_e32 v7, v7, v254
.LBB0_815:
	s_or_b64 exec, exec, s[0:1]
	ds_read_u16 v238, v18 offset:1632
	ds_read_b32 v239, v16 offset:24
	ds_read_b32 v254, v15 offset:24
	s_waitcnt lgkmcnt(4)
	v_fma_f32 v8, v2, v240, 0
	v_fma_f32 v9, v3, v241, 0
	v_fma_f32 v10, v4, v242, 0
	v_fma_f32 v12, v5, v243, 0
	s_waitcnt lgkmcnt(3)
	v_fmac_f32_e32 v8, v6, v244
	ds_read_b128 v[240:243], v11 offset:1536
	ds_read_b128 v[244:247], v11 offset:1552
	v_add_f32_e32 v8, v9, v8
	v_add_f32_e32 v9, v10, v12
	v_add_f32_e32 v8, v9, v8
	v_sub_f32_e32 v7, v7, v8
	s_waitcnt lgkmcnt(2)
	v_lshlrev_b32_e32 v8, 16, v238
	v_mul_f32_e32 v8, v239, v8
	s_and_saveexec_b64 s[0:1], s[16:17]
	s_cbranch_execz .LBB0_817
	v_mul_f32_e32 v8, v8, v254
.LBB0_817:
	s_or_b64 exec, exec, s[0:1]
	ds_read_u16 v238, v18 offset:1904
	ds_read_b32 v239, v16 offset:28
	ds_read_b32 v254, v15 offset:28
	s_waitcnt lgkmcnt(4)
	v_fma_f32 v9, v2, v240, 0
	v_fma_f32 v10, v3, v241, 0
	v_fma_f32 v12, v4, v242, 0
	v_fma_f32 v13, v5, v243, 0
	s_waitcnt lgkmcnt(3)
	v_fmac_f32_e32 v9, v6, v244
	v_fmac_f32_e32 v10, v7, v245
	ds_read_b128 v[240:243], v11 offset:1792
	ds_read_b128 v[244:247], v11 offset:1808
	v_add_f32_e32 v9, v9, v10
	v_add_f32_e32 v10, v12, v13
	v_add_f32_e32 v9, v10, v9
	v_sub_f32_e32 v8, v8, v9
	s_waitcnt lgkmcnt(2)
	v_lshlrev_b32_e32 v9, 16, v238
	v_mul_f32_e32 v9, v239, v9
	s_and_saveexec_b64 s[0:1], s[16:17]
	s_cbranch_execz .LBB0_819
	v_mul_f32_e32 v9, v9, v254
.LBB0_819:
	s_or_b64 exec, exec, s[0:1]
	ds_read_u16 v238, v18 offset:2176
	ds_read_b32 v239, v16 offset:32
	ds_read_b32 v254, v15 offset:32
	s_waitcnt lgkmcnt(4)
	v_fma_f32 v10, v2, v240, 0
	v_fma_f32 v12, v3, v241, 0
	v_fma_f32 v13, v4, v242, 0
	v_fma_f32 v14, v5, v243, 0
	s_waitcnt lgkmcnt(3)
	v_fmac_f32_e32 v10, v6, v244
	v_fmac_f32_e32 v12, v7, v245
	v_fmac_f32_e32 v13, v8, v246
	ds_read_b128 v[240:243], v11 offset:2048
	ds_read_b128 v[244:247], v11 offset:2064
	v_add_f32_e32 v10, v10, v12
	v_add_f32_e32 v12, v14, v13
	v_add_f32_e32 v10, v10, v12
	v_sub_f32_e32 v9, v9, v10
	s_waitcnt lgkmcnt(2)
	v_lshlrev_b32_e32 v10, 16, v238
	v_mul_f32_e32 v10, v239, v10
	s_and_saveexec_b64 s[0:1], s[16:17]
	s_cbranch_execz .LBB0_821
	v_mul_f32_e32 v10, v10, v254
.LBB0_821:
	s_or_b64 exec, exec, s[0:1]
	ds_read_u16 v238, v18 offset:2448
	ds_read_b32 v239, v16 offset:36
	ds_read_b32 v254, v15 offset:36
	s_waitcnt lgkmcnt(4)
	v_fma_f32 v12, v2, v240, 0
	v_fma_f32 v13, v3, v241, 0
	v_fma_f32 v14, v4, v242, 0
	v_fma_f32 v17, v5, v243, 0
	s_waitcnt lgkmcnt(3)
	v_fmac_f32_e32 v12, v6, v244
	v_fmac_f32_e32 v13, v7, v245
	v_fmac_f32_e32 v14, v8, v246
	v_fmac_f32_e32 v17, v9, v247
	ds_read_b128 v[240:243], v11 offset:2304
	ds_read_b128 v[244:247], v11 offset:2320
	ds_read_b128 v[248:251], v11 offset:2336
	v_add_f32_e32 v12, v12, v13
	v_add_f32_e32 v13, v14, v17
	v_add_f32_e32 v12, v12, v13
	v_sub_f32_e32 v10, v10, v12
	s_waitcnt lgkmcnt(3)
	v_lshlrev_b32_e32 v12, 16, v238
	v_mul_f32_e32 v12, v239, v12
	s_and_saveexec_b64 s[0:1], s[16:17]
	s_cbranch_execz .LBB0_823
	v_mul_f32_e32 v12, v12, v254
.LBB0_823:
	s_or_b64 exec, exec, s[0:1]
	ds_read_u16 v238, v18 offset:2720
	ds_read_b32 v239, v16 offset:40
	ds_read_b32 v254, v15 offset:40
	s_waitcnt lgkmcnt(5)
	v_fma_f32 v13, v2, v240, 0
	v_fma_f32 v14, v3, v241, 0
	v_fma_f32 v17, v4, v242, 0
	v_fma_f32 v19, v5, v243, 0
	s_waitcnt lgkmcnt(4)
	v_fmac_f32_e32 v13, v6, v244
	v_fmac_f32_e32 v14, v7, v245
	v_fmac_f32_e32 v17, v8, v246
	v_fmac_f32_e32 v19, v9, v247
	s_waitcnt lgkmcnt(3)
	v_fmac_f32_e32 v13, v10, v248
	ds_read_b128 v[240:243], v11 offset:2560
	ds_read_b128 v[244:247], v11 offset:2576
	ds_read_b128 v[248:251], v11 offset:2592
	v_add_f32_e32 v13, v14, v13
	v_add_f32_e32 v14, v17, v19
	v_add_f32_e32 v13, v14, v13
	v_sub_f32_e32 v12, v12, v13
	s_waitcnt lgkmcnt(3)
	v_lshlrev_b32_e32 v13, 16, v238
	v_mul_f32_e32 v13, v239, v13
	s_and_saveexec_b64 s[0:1], s[16:17]
	s_cbranch_execz .LBB0_825
	v_mul_f32_e32 v13, v13, v254
.LBB0_825:
	s_or_b64 exec, exec, s[0:1]
	ds_read_u16 v238, v18 offset:2992
	ds_read_b32 v239, v16 offset:44
	ds_read_b32 v254, v15 offset:44
	s_waitcnt lgkmcnt(5)
	v_fma_f32 v14, v2, v240, 0
	v_fma_f32 v17, v3, v241, 0
	v_fma_f32 v19, v4, v242, 0
	v_fma_f32 v28, v5, v243, 0
	s_waitcnt lgkmcnt(4)
	v_fmac_f32_e32 v14, v6, v244
	v_fmac_f32_e32 v17, v7, v245
	v_fmac_f32_e32 v19, v8, v246
	v_fmac_f32_e32 v28, v9, v247
	s_waitcnt lgkmcnt(3)
	v_fmac_f32_e32 v14, v10, v248
	v_fmac_f32_e32 v17, v12, v249
	ds_read_b128 v[240:243], v11 offset:2816
	ds_read_b128 v[244:247], v11 offset:2832
	ds_read_b128 v[248:251], v11 offset:2848
	v_add_f32_e32 v14, v14, v17
	v_add_f32_e32 v17, v19, v28
	v_add_f32_e32 v14, v17, v14
	v_sub_f32_e32 v13, v13, v14
	s_waitcnt lgkmcnt(3)
	v_lshlrev_b32_e32 v14, 16, v238
	v_mul_f32_e32 v14, v239, v14
	s_and_saveexec_b64 s[0:1], s[16:17]
	s_cbranch_execz .LBB0_827
	v_mul_f32_e32 v14, v14, v254
.LBB0_827:
	s_or_b64 exec, exec, s[0:1]
	ds_read_u16 v238, v18 offset:3264
	ds_read_b32 v239, v16 offset:48
	ds_read_b32 v254, v15 offset:48
	s_waitcnt lgkmcnt(5)
	v_fma_f32 v17, v2, v240, 0
	v_fma_f32 v19, v3, v241, 0
	v_fma_f32 v28, v4, v242, 0
	v_fma_f32 v35, v5, v243, 0
	s_waitcnt lgkmcnt(4)
	v_fmac_f32_e32 v17, v6, v244
	v_fmac_f32_e32 v19, v7, v245
	v_fmac_f32_e32 v28, v8, v246
	v_fmac_f32_e32 v35, v9, v247
	s_waitcnt lgkmcnt(3)
	v_fmac_f32_e32 v17, v10, v248
	v_fmac_f32_e32 v19, v12, v249
	v_fmac_f32_e32 v28, v13, v250
	ds_read_b128 v[240:243], v11 offset:3072
	ds_read_b128 v[244:247], v11 offset:3088
	ds_read_b128 v[248:251], v11 offset:3104
	v_add_f32_e32 v17, v17, v19
	v_add_f32_e32 v19, v35, v28
	v_add_f32_e32 v17, v17, v19
	v_sub_f32_e32 v14, v14, v17
	s_waitcnt lgkmcnt(3)
	v_lshlrev_b32_e32 v17, 16, v238
	v_mul_f32_e32 v17, v239, v17
	s_and_saveexec_b64 s[0:1], s[16:17]
	s_cbranch_execz .LBB0_829
	v_mul_f32_e32 v17, v17, v254
.LBB0_829:
	s_or_b64 exec, exec, s[0:1]
	ds_read_u16 v238, v18 offset:3536
	ds_read_b32 v239, v16 offset:52
	ds_read_b32 v254, v15 offset:52
	s_waitcnt lgkmcnt(5)
	v_fma_f32 v19, v2, v240, 0
	v_fma_f32 v28, v3, v241, 0
	v_fma_f32 v35, v4, v242, 0
	v_fma_f32 v36, v5, v243, 0
	s_waitcnt lgkmcnt(4)
	v_fmac_f32_e32 v19, v6, v244
	v_fmac_f32_e32 v28, v7, v245
	v_fmac_f32_e32 v35, v8, v246
	v_fmac_f32_e32 v36, v9, v247
	s_waitcnt lgkmcnt(3)
	v_fmac_f32_e32 v19, v10, v248
	v_fmac_f32_e32 v28, v12, v249
	v_fmac_f32_e32 v35, v13, v250
	v_fmac_f32_e32 v36, v14, v251
	ds_read_b128 v[240:243], v11 offset:3328
	ds_read_b128 v[244:247], v11 offset:3344
	ds_read_b128 v[248:251], v11 offset:3360
	v_add_f32_e32 v19, v19, v28
	v_add_f32_e32 v28, v35, v36
	v_add_f32_e32 v19, v19, v28
	v_sub_f32_e32 v17, v17, v19
	s_waitcnt lgkmcnt(3)
	v_lshlrev_b32_e32 v19, 16, v238
	v_mul_f32_e32 v19, v239, v19
	s_and_saveexec_b64 s[0:1], s[16:17]
	s_cbranch_execz .LBB0_831
	v_mul_f32_e32 v19, v19, v254
.LBB0_831:
	s_or_b64 exec, exec, s[0:1]
	ds_read_u16 v238, v18 offset:3808
	ds_read_b32 v239, v16 offset:56
	ds_read_b32 v254, v15 offset:56
	ds_read_b128 v[40:43], v11 offset:3376
	s_waitcnt lgkmcnt(6)
	v_fma_f32 v28, v2, v240, 0
	v_fma_f32 v35, v3, v241, 0
	v_fma_f32 v36, v4, v242, 0
	v_fma_f32 v37, v5, v243, 0
	s_waitcnt lgkmcnt(5)
	v_fmac_f32_e32 v28, v6, v244
	v_fmac_f32_e32 v35, v7, v245
	v_fmac_f32_e32 v36, v8, v246
	v_fmac_f32_e32 v37, v9, v247
	s_waitcnt lgkmcnt(4)
	v_fmac_f32_e32 v28, v10, v248
	v_fmac_f32_e32 v35, v12, v249
	v_fmac_f32_e32 v36, v13, v250
	v_fmac_f32_e32 v37, v14, v251
	s_waitcnt lgkmcnt(0)
	v_fmac_f32_e32 v28, v17, v40
	ds_read_b128 v[240:243], v11 offset:3584
	ds_read_b128 v[244:247], v11 offset:3600
	ds_read_b128 v[248:251], v11 offset:3616
	v_add_f32_e32 v28, v35, v28
	v_add_f32_e32 v35, v36, v37
	v_add_f32_e32 v28, v35, v28
	v_sub_f32_e32 v19, v19, v28
	v_lshlrev_b32_e32 v28, 16, v238
	v_mul_f32_e32 v28, v239, v28
	s_and_saveexec_b64 s[0:1], s[16:17]
	s_cbranch_execz .LBB0_833
	v_mul_f32_e32 v28, v28, v254
.LBB0_833:
	s_or_b64 exec, exec, s[0:1]
	ds_read_u16 v238, v18 offset:4080
	ds_read_b32 v239, v16 offset:60
	ds_read_b32 v254, v15 offset:60
	ds_read_b128 v[40:43], v11 offset:3632
	s_waitcnt lgkmcnt(6)
	v_fma_f32 v35, v2, v240, 0
	v_fma_f32 v36, v3, v241, 0
	v_fma_f32 v37, v4, v242, 0
	v_fma_f32 v38, v5, v243, 0
	s_waitcnt lgkmcnt(5)
	v_fmac_f32_e32 v35, v6, v244
	v_fmac_f32_e32 v36, v7, v245
	v_fmac_f32_e32 v37, v8, v246
	v_fmac_f32_e32 v38, v9, v247
	s_waitcnt lgkmcnt(4)
	v_fmac_f32_e32 v35, v10, v248
	v_fmac_f32_e32 v36, v12, v249
	v_fmac_f32_e32 v37, v13, v250
	v_fmac_f32_e32 v38, v14, v251
	s_waitcnt lgkmcnt(0)
	v_fmac_f32_e32 v35, v17, v40
	v_fmac_f32_e32 v36, v19, v41
	ds_read_b128 v[240:243], v11 offset:3840
	ds_read_b128 v[244:247], v11 offset:3856
	ds_read_b128 v[248:251], v11 offset:3872
	v_add_f32_e32 v35, v35, v36
	v_add_f32_e32 v36, v37, v38
	v_add_f32_e32 v35, v36, v35
	v_sub_f32_e32 v28, v28, v35
	v_lshlrev_b32_e32 v35, 16, v238
	v_mul_f32_e32 v35, v239, v35
	s_and_saveexec_b64 s[0:1], s[16:17]
	s_cbranch_execz .LBB0_835
	v_mul_f32_e32 v35, v35, v254
.LBB0_835:
	s_or_b64 exec, exec, s[0:1]
	ds_read_u16 v238, v18 offset:4352
	ds_read_b32 v239, v16 offset:64
	ds_read_b32 v254, v15 offset:64
	ds_read_b128 v[40:43], v11 offset:3888
	s_waitcnt lgkmcnt(6)
	v_fma_f32 v36, v2, v240, 0
	v_fma_f32 v37, v3, v241, 0
	v_fma_f32 v38, v4, v242, 0
	v_fma_f32 v39, v5, v243, 0
	s_waitcnt lgkmcnt(5)
	v_fmac_f32_e32 v36, v6, v244
	v_fmac_f32_e32 v37, v7, v245
	v_fmac_f32_e32 v38, v8, v246
	v_fmac_f32_e32 v39, v9, v247
	s_waitcnt lgkmcnt(4)
	v_fmac_f32_e32 v36, v10, v248
	v_fmac_f32_e32 v37, v12, v249
	v_fmac_f32_e32 v38, v13, v250
	v_fmac_f32_e32 v39, v14, v251
	s_waitcnt lgkmcnt(0)
	v_fmac_f32_e32 v36, v17, v40
	v_fmac_f32_e32 v37, v19, v41
	v_fmac_f32_e32 v38, v28, v42
	ds_read_b128 v[240:243], v11 offset:4096
	ds_read_b128 v[244:247], v11 offset:4112
	ds_read_b128 v[248:251], v11 offset:4128
	v_add_f32_e32 v36, v36, v37
	v_add_f32_e32 v37, v39, v38
	v_add_f32_e32 v36, v36, v37
	v_sub_f32_e32 v35, v35, v36
	v_lshlrev_b32_e32 v36, 16, v238
	v_mul_f32_e32 v36, v239, v36
	s_and_saveexec_b64 s[0:1], s[16:17]
	s_cbranch_execz .LBB0_837
	v_mul_f32_e32 v36, v36, v254
.LBB0_837:
	s_or_b64 exec, exec, s[0:1]
	ds_read_u16 v238, v18 offset:4624
	ds_read_b32 v239, v16 offset:68
	ds_read_b32 v254, v15 offset:68
	ds_read_b128 v[42:45], v11 offset:4144
	s_waitcnt lgkmcnt(6)
	v_fma_f32 v37, v2, v240, 0
	v_fma_f32 v38, v3, v241, 0
	v_fma_f32 v39, v4, v242, 0
	v_fma_f32 v40, v5, v243, 0
	s_waitcnt lgkmcnt(5)
	v_fmac_f32_e32 v37, v6, v244
	v_fmac_f32_e32 v38, v7, v245
	v_fmac_f32_e32 v39, v8, v246
	v_fmac_f32_e32 v40, v9, v247
	s_waitcnt lgkmcnt(4)
	v_fmac_f32_e32 v37, v10, v248
	v_fmac_f32_e32 v38, v12, v249
	v_fmac_f32_e32 v39, v13, v250
	v_fmac_f32_e32 v40, v14, v251
	s_waitcnt lgkmcnt(0)
	v_fmac_f32_e32 v37, v17, v42
	v_fmac_f32_e32 v38, v19, v43
	v_fmac_f32_e32 v39, v28, v44
	v_fmac_f32_e32 v40, v35, v45
	ds_read_b128 v[240:243], v11 offset:4352
	ds_read_b128 v[244:247], v11 offset:4368
	ds_read_b128 v[248:251], v11 offset:4384
	v_add_f32_e32 v37, v37, v38
	v_add_f32_e32 v38, v39, v40
	v_add_f32_e32 v37, v37, v38
	v_sub_f32_e32 v36, v36, v37
	v_lshlrev_b32_e32 v37, 16, v238
	v_mul_f32_e32 v37, v239, v37
	s_and_saveexec_b64 s[0:1], s[16:17]
	s_cbranch_execz .LBB0_839
	v_mul_f32_e32 v37, v37, v254
.LBB0_839:
	s_or_b64 exec, exec, s[0:1]
	ds_read_u16 v238, v18 offset:4896
	ds_read_b32 v239, v16 offset:72
	ds_read_b32 v254, v15 offset:72
	ds_read_b128 v[38:41], v11 offset:4400
	ds_read_b128 v[42:45], v11 offset:4416
	s_waitcnt lgkmcnt(7)
	v_fma_f32 v54, v2, v240, 0
	v_fma_f32 v55, v3, v241, 0
	v_fma_f32 v56, v4, v242, 0
	v_fma_f32 v57, v5, v243, 0
	s_waitcnt lgkmcnt(6)
	v_fmac_f32_e32 v54, v6, v244
	v_fmac_f32_e32 v55, v7, v245
	v_fmac_f32_e32 v56, v8, v246
	v_fmac_f32_e32 v57, v9, v247
	s_waitcnt lgkmcnt(5)
	v_fmac_f32_e32 v54, v10, v248
	v_fmac_f32_e32 v55, v12, v249
	v_fmac_f32_e32 v56, v13, v250
	v_fmac_f32_e32 v57, v14, v251
	s_waitcnt lgkmcnt(1)
	v_fmac_f32_e32 v54, v17, v38
	v_fmac_f32_e32 v55, v19, v39
	v_fmac_f32_e32 v56, v28, v40
	v_fmac_f32_e32 v57, v35, v41
	s_waitcnt lgkmcnt(0)
	v_fmac_f32_e32 v54, v36, v42
	ds_read_b128 v[240:243], v11 offset:4608
	ds_read_b128 v[244:247], v11 offset:4624
	ds_read_b128 v[248:251], v11 offset:4640
	v_add_f32_e32 v38, v55, v54
	v_add_f32_e32 v39, v56, v57
	v_add_f32_e32 v38, v39, v38
	v_sub_f32_e32 v37, v37, v38
	v_lshlrev_b32_e32 v38, 16, v238
	v_mul_f32_e32 v38, v239, v38
	s_and_saveexec_b64 s[0:1], s[16:17]
	s_cbranch_execz .LBB0_841
	v_mul_f32_e32 v38, v38, v254
.LBB0_841:
	s_or_b64 exec, exec, s[0:1]
	ds_read_u16 v238, v18 offset:5168
	ds_read_b32 v239, v16 offset:76
	ds_read_b32 v254, v15 offset:76
	ds_read_b128 v[40:43], v11 offset:4656
	ds_read_b128 v[44:47], v11 offset:4672
	s_waitcnt lgkmcnt(7)
	v_fma_f32 v39, v2, v240, 0
	v_fma_f32 v56, v3, v241, 0
	v_fma_f32 v57, v4, v242, 0
	v_fma_f32 v58, v5, v243, 0
	s_waitcnt lgkmcnt(6)
	v_fmac_f32_e32 v39, v6, v244
	v_fmac_f32_e32 v56, v7, v245
	v_fmac_f32_e32 v57, v8, v246
	v_fmac_f32_e32 v58, v9, v247
	s_waitcnt lgkmcnt(5)
	v_fmac_f32_e32 v39, v10, v248
	v_fmac_f32_e32 v56, v12, v249
	v_fmac_f32_e32 v57, v13, v250
	v_fmac_f32_e32 v58, v14, v251
	s_waitcnt lgkmcnt(1)
	v_fmac_f32_e32 v39, v17, v40
	v_fmac_f32_e32 v56, v19, v41
	v_fmac_f32_e32 v57, v28, v42
	v_fmac_f32_e32 v58, v35, v43
	s_waitcnt lgkmcnt(0)
	v_fmac_f32_e32 v39, v36, v44
	v_fmac_f32_e32 v56, v37, v45
	ds_read_b128 v[240:243], v11 offset:4864
	ds_read_b128 v[244:247], v11 offset:4880
	ds_read_b128 v[248:251], v11 offset:4896
	v_add_f32_e32 v39, v39, v56
	v_add_f32_e32 v40, v57, v58
	v_add_f32_e32 v39, v40, v39
	v_sub_f32_e32 v38, v38, v39
	v_lshlrev_b32_e32 v39, 16, v238
	v_mul_f32_e32 v39, v239, v39
	s_and_saveexec_b64 s[0:1], s[16:17]
	s_cbranch_execz .LBB0_843
	v_mul_f32_e32 v39, v39, v254
.LBB0_843:
	s_or_b64 exec, exec, s[0:1]
	ds_read_u16 v238, v18 offset:5440
	ds_read_b32 v239, v16 offset:80
	ds_read_b32 v254, v15 offset:80
	ds_read_b128 v[40:43], v11 offset:4912
	ds_read_b128 v[44:47], v11 offset:4928
	s_waitcnt lgkmcnt(7)
	v_fma_f32 v56, v2, v240, 0
	v_fma_f32 v57, v3, v241, 0
	v_fma_f32 v58, v4, v242, 0
	v_fma_f32 v59, v5, v243, 0
	s_waitcnt lgkmcnt(6)
	v_fmac_f32_e32 v56, v6, v244
	v_fmac_f32_e32 v57, v7, v245
	v_fmac_f32_e32 v58, v8, v246
	v_fmac_f32_e32 v59, v9, v247
	s_waitcnt lgkmcnt(5)
	v_fmac_f32_e32 v56, v10, v248
	v_fmac_f32_e32 v57, v12, v249
	v_fmac_f32_e32 v58, v13, v250
	v_fmac_f32_e32 v59, v14, v251
	s_waitcnt lgkmcnt(1)
	v_fmac_f32_e32 v56, v17, v40
	v_fmac_f32_e32 v57, v19, v41
	v_fmac_f32_e32 v58, v28, v42
	v_fmac_f32_e32 v59, v35, v43
	s_waitcnt lgkmcnt(0)
	v_fmac_f32_e32 v56, v36, v44
	v_fmac_f32_e32 v57, v37, v45
	v_fmac_f32_e32 v58, v38, v46
	ds_read_b128 v[240:243], v11 offset:5120
	ds_read_b128 v[244:247], v11 offset:5136
	ds_read_b128 v[248:251], v11 offset:5152
	v_add_f32_e32 v40, v56, v57
	v_add_f32_e32 v41, v59, v58
	v_add_f32_e32 v40, v40, v41
	v_sub_f32_e32 v39, v39, v40
	v_lshlrev_b32_e32 v40, 16, v238
	v_mul_f32_e32 v40, v239, v40
	s_and_saveexec_b64 s[0:1], s[16:17]
	s_cbranch_execz .LBB0_845
	v_mul_f32_e32 v40, v40, v254
.LBB0_845:
	s_or_b64 exec, exec, s[0:1]
	ds_read_u16 v238, v18 offset:5712
	ds_read_b32 v239, v16 offset:84
	ds_read_b32 v254, v15 offset:84
	ds_read_b128 v[42:45], v11 offset:5168
	ds_read_b128 v[46:49], v11 offset:5184
	s_waitcnt lgkmcnt(7)
	v_fma_f32 v41, v2, v240, 0
	v_fma_f32 v58, v3, v241, 0
	v_fma_f32 v59, v4, v242, 0
	v_fma_f32 v60, v5, v243, 0
	s_waitcnt lgkmcnt(6)
	v_fmac_f32_e32 v41, v6, v244
	v_fmac_f32_e32 v58, v7, v245
	v_fmac_f32_e32 v59, v8, v246
	v_fmac_f32_e32 v60, v9, v247
	s_waitcnt lgkmcnt(5)
	v_fmac_f32_e32 v41, v10, v248
	v_fmac_f32_e32 v58, v12, v249
	v_fmac_f32_e32 v59, v13, v250
	v_fmac_f32_e32 v60, v14, v251
	s_waitcnt lgkmcnt(1)
	v_fmac_f32_e32 v41, v17, v42
	v_fmac_f32_e32 v58, v19, v43
	v_fmac_f32_e32 v59, v28, v44
	v_fmac_f32_e32 v60, v35, v45
	s_waitcnt lgkmcnt(0)
	v_fmac_f32_e32 v41, v36, v46
	v_fmac_f32_e32 v58, v37, v47
	v_fmac_f32_e32 v59, v38, v48
	v_fmac_f32_e32 v60, v39, v49
	ds_read_b128 v[240:243], v11 offset:5376
	ds_read_b128 v[244:247], v11 offset:5392
	ds_read_b128 v[248:251], v11 offset:5408
	v_add_f32_e32 v41, v41, v58
	v_add_f32_e32 v42, v59, v60
	v_add_f32_e32 v41, v41, v42
	v_sub_f32_e32 v40, v40, v41
	v_lshlrev_b32_e32 v41, 16, v238
	v_mul_f32_e32 v41, v239, v41
	s_and_saveexec_b64 s[0:1], s[16:17]
	s_cbranch_execz .LBB0_847
	v_mul_f32_e32 v41, v41, v254
.LBB0_847:
	s_or_b64 exec, exec, s[0:1]
	ds_read_u16 v238, v18 offset:5984
	ds_read_b32 v239, v16 offset:88
	ds_read_b32 v254, v15 offset:88
	ds_read_b128 v[42:45], v11 offset:5424
	ds_read_b128 v[46:49], v11 offset:5440
	ds_read_b128 v[50:53], v11 offset:5456
	s_waitcnt lgkmcnt(8)
	v_fma_f32 v58, v2, v240, 0
	v_fma_f32 v59, v3, v241, 0
	v_fma_f32 v60, v4, v242, 0
	v_fma_f32 v61, v5, v243, 0
	s_waitcnt lgkmcnt(7)
	v_fmac_f32_e32 v58, v6, v244
	v_fmac_f32_e32 v59, v7, v245
	v_fmac_f32_e32 v60, v8, v246
	v_fmac_f32_e32 v61, v9, v247
	s_waitcnt lgkmcnt(6)
	v_fmac_f32_e32 v58, v10, v248
	v_fmac_f32_e32 v59, v12, v249
	v_fmac_f32_e32 v60, v13, v250
	v_fmac_f32_e32 v61, v14, v251
	s_waitcnt lgkmcnt(2)
	v_fmac_f32_e32 v58, v17, v42
	v_fmac_f32_e32 v59, v19, v43
	v_fmac_f32_e32 v60, v28, v44
	v_fmac_f32_e32 v61, v35, v45
	s_waitcnt lgkmcnt(1)
	v_fmac_f32_e32 v58, v36, v46
	v_fmac_f32_e32 v59, v37, v47
	v_fmac_f32_e32 v60, v38, v48
	v_fmac_f32_e32 v61, v39, v49
	s_waitcnt lgkmcnt(0)
	v_fmac_f32_e32 v58, v40, v50
	ds_read_b128 v[240:243], v11 offset:5632
	ds_read_b128 v[244:247], v11 offset:5648
	ds_read_b128 v[248:251], v11 offset:5664
	v_add_f32_e32 v42, v59, v58
	v_add_f32_e32 v43, v60, v61
	v_add_f32_e32 v42, v43, v42
	v_sub_f32_e32 v41, v41, v42
	v_lshlrev_b32_e32 v42, 16, v238
	v_mul_f32_e32 v42, v239, v42
	s_and_saveexec_b64 s[0:1], s[16:17]
	s_cbranch_execz .LBB0_849
	v_mul_f32_e32 v42, v42, v254
.LBB0_849:
	s_or_b64 exec, exec, s[0:1]
	ds_read_u16 v238, v18 offset:6256
	ds_read_b32 v239, v16 offset:92
	ds_read_b32 v254, v15 offset:92
	ds_read_b128 v[44:47], v11 offset:5680
	ds_read_b128 v[48:51], v11 offset:5696
	ds_read_b128 v[52:55], v11 offset:5712
	s_waitcnt lgkmcnt(8)
	v_fma_f32 v43, v2, v240, 0
	v_fma_f32 v60, v3, v241, 0
	v_fma_f32 v61, v4, v242, 0
	v_fma_f32 v62, v5, v243, 0
	s_waitcnt lgkmcnt(7)
	v_fmac_f32_e32 v43, v6, v244
	v_fmac_f32_e32 v60, v7, v245
	v_fmac_f32_e32 v61, v8, v246
	v_fmac_f32_e32 v62, v9, v247
	s_waitcnt lgkmcnt(6)
	v_fmac_f32_e32 v43, v10, v248
	v_fmac_f32_e32 v60, v12, v249
	v_fmac_f32_e32 v61, v13, v250
	v_fmac_f32_e32 v62, v14, v251
	s_waitcnt lgkmcnt(2)
	v_fmac_f32_e32 v43, v17, v44
	v_fmac_f32_e32 v60, v19, v45
	v_fmac_f32_e32 v61, v28, v46
	v_fmac_f32_e32 v62, v35, v47
	s_waitcnt lgkmcnt(1)
	v_fmac_f32_e32 v43, v36, v48
	v_fmac_f32_e32 v60, v37, v49
	v_fmac_f32_e32 v61, v38, v50
	v_fmac_f32_e32 v62, v39, v51
	s_waitcnt lgkmcnt(0)
	v_fmac_f32_e32 v43, v40, v52
	v_fmac_f32_e32 v60, v41, v53
	ds_read_b128 v[240:243], v11 offset:5888
	ds_read_b128 v[244:247], v11 offset:5904
	ds_read_b128 v[248:251], v11 offset:5920
	v_add_f32_e32 v43, v43, v60
	v_add_f32_e32 v44, v61, v62
	v_add_f32_e32 v43, v44, v43
	v_sub_f32_e32 v42, v42, v43
	v_lshlrev_b32_e32 v43, 16, v238
	v_mul_f32_e32 v43, v239, v43
	s_and_saveexec_b64 s[0:1], s[16:17]
	s_cbranch_execz .LBB0_851
	v_mul_f32_e32 v43, v43, v254
.LBB0_851:
	s_or_b64 exec, exec, s[0:1]
	ds_read_u16 v238, v18 offset:6528
	ds_read_b32 v239, v16 offset:96
	ds_read_b32 v254, v15 offset:96
	ds_read_b128 v[44:47], v11 offset:5936
	ds_read_b128 v[48:51], v11 offset:5952
	ds_read_b128 v[52:55], v11 offset:5968
	s_waitcnt lgkmcnt(8)
	v_fma_f32 v60, v2, v240, 0
	v_fma_f32 v61, v3, v241, 0
	v_fma_f32 v62, v4, v242, 0
	v_fma_f32 v63, v5, v243, 0
	s_waitcnt lgkmcnt(7)
	v_fmac_f32_e32 v60, v6, v244
	v_fmac_f32_e32 v61, v7, v245
	v_fmac_f32_e32 v62, v8, v246
	v_fmac_f32_e32 v63, v9, v247
	s_waitcnt lgkmcnt(6)
	v_fmac_f32_e32 v60, v10, v248
	v_fmac_f32_e32 v61, v12, v249
	v_fmac_f32_e32 v62, v13, v250
	v_fmac_f32_e32 v63, v14, v251
	s_waitcnt lgkmcnt(2)
	v_fmac_f32_e32 v60, v17, v44
	v_fmac_f32_e32 v61, v19, v45
	v_fmac_f32_e32 v62, v28, v46
	v_fmac_f32_e32 v63, v35, v47
	s_waitcnt lgkmcnt(1)
	v_fmac_f32_e32 v60, v36, v48
	v_fmac_f32_e32 v61, v37, v49
	v_fmac_f32_e32 v62, v38, v50
	v_fmac_f32_e32 v63, v39, v51
	s_waitcnt lgkmcnt(0)
	v_fmac_f32_e32 v60, v40, v52
	v_fmac_f32_e32 v61, v41, v53
	v_fmac_f32_e32 v62, v42, v54
	ds_read_b128 v[240:243], v11 offset:6144
	ds_read_b128 v[244:247], v11 offset:6160
	ds_read_b128 v[248:251], v11 offset:6176
	v_add_f32_e32 v44, v60, v61
	v_add_f32_e32 v45, v63, v62
	v_add_f32_e32 v44, v44, v45
	v_sub_f32_e32 v43, v43, v44
	v_lshlrev_b32_e32 v44, 16, v238
	v_mul_f32_e32 v44, v239, v44
	s_and_saveexec_b64 s[0:1], s[16:17]
	s_cbranch_execz .LBB0_853
	v_mul_f32_e32 v44, v44, v254
.LBB0_853:
	s_or_b64 exec, exec, s[0:1]
	ds_read_u16 v238, v18 offset:6800
	ds_read_b32 v239, v16 offset:100
	ds_read_b32 v254, v15 offset:100
	ds_read_b128 v[46:49], v11 offset:6192
	ds_read_b128 v[50:53], v11 offset:6208
	ds_read_b128 v[54:57], v11 offset:6224
	s_waitcnt lgkmcnt(8)
	v_fma_f32 v45, v2, v240, 0
	v_fma_f32 v62, v3, v241, 0
	v_fma_f32 v63, v4, v242, 0
	v_fma_f32 v64, v5, v243, 0
	s_waitcnt lgkmcnt(7)
	v_fmac_f32_e32 v45, v6, v244
	v_fmac_f32_e32 v62, v7, v245
	v_fmac_f32_e32 v63, v8, v246
	v_fmac_f32_e32 v64, v9, v247
	s_waitcnt lgkmcnt(6)
	v_fmac_f32_e32 v45, v10, v248
	v_fmac_f32_e32 v62, v12, v249
	v_fmac_f32_e32 v63, v13, v250
	v_fmac_f32_e32 v64, v14, v251
	s_waitcnt lgkmcnt(2)
	v_fmac_f32_e32 v45, v17, v46
	v_fmac_f32_e32 v62, v19, v47
	v_fmac_f32_e32 v63, v28, v48
	v_fmac_f32_e32 v64, v35, v49
	s_waitcnt lgkmcnt(1)
	v_fmac_f32_e32 v45, v36, v50
	v_fmac_f32_e32 v62, v37, v51
	v_fmac_f32_e32 v63, v38, v52
	v_fmac_f32_e32 v64, v39, v53
	s_waitcnt lgkmcnt(0)
	v_fmac_f32_e32 v45, v40, v54
	v_fmac_f32_e32 v62, v41, v55
	v_fmac_f32_e32 v63, v42, v56
	v_fmac_f32_e32 v64, v43, v57
	ds_read_b128 v[240:243], v11 offset:6400
	ds_read_b128 v[244:247], v11 offset:6416
	ds_read_b128 v[248:251], v11 offset:6432
	v_add_f32_e32 v45, v45, v62
	v_add_f32_e32 v46, v63, v64
	v_add_f32_e32 v45, v45, v46
	v_sub_f32_e32 v44, v44, v45
	v_lshlrev_b32_e32 v45, 16, v238
	v_mul_f32_e32 v45, v239, v45
	s_and_saveexec_b64 s[0:1], s[16:17]
	s_cbranch_execz .LBB0_855
	v_mul_f32_e32 v45, v45, v254
.LBB0_855:
	s_or_b64 exec, exec, s[0:1]
	ds_read_u16 v238, v18 offset:7072
	ds_read_b32 v239, v16 offset:104
	ds_read_b32 v254, v15 offset:104
	ds_read_b128 v[46:49], v11 offset:6448
	ds_read_b128 v[50:53], v11 offset:6464
	ds_read_b128 v[54:57], v11 offset:6480
	ds_read_b128 v[58:61], v11 offset:6496
	s_waitcnt lgkmcnt(9)
	v_fma_f32 v62, v2, v240, 0
	v_fma_f32 v63, v3, v241, 0
	v_fma_f32 v64, v4, v242, 0
	v_fma_f32 v65, v5, v243, 0
	s_waitcnt lgkmcnt(8)
	v_fmac_f32_e32 v62, v6, v244
	v_fmac_f32_e32 v63, v7, v245
	v_fmac_f32_e32 v64, v8, v246
	v_fmac_f32_e32 v65, v9, v247
	s_waitcnt lgkmcnt(7)
	v_fmac_f32_e32 v62, v10, v248
	v_fmac_f32_e32 v63, v12, v249
	v_fmac_f32_e32 v64, v13, v250
	v_fmac_f32_e32 v65, v14, v251
	s_waitcnt lgkmcnt(3)
	v_fmac_f32_e32 v62, v17, v46
	v_fmac_f32_e32 v63, v19, v47
	v_fmac_f32_e32 v64, v28, v48
	v_fmac_f32_e32 v65, v35, v49
	s_waitcnt lgkmcnt(2)
	v_fmac_f32_e32 v62, v36, v50
	v_fmac_f32_e32 v63, v37, v51
	v_fmac_f32_e32 v64, v38, v52
	v_fmac_f32_e32 v65, v39, v53
	s_waitcnt lgkmcnt(1)
	v_fmac_f32_e32 v62, v40, v54
	v_fmac_f32_e32 v63, v41, v55
	v_fmac_f32_e32 v64, v42, v56
	v_fmac_f32_e32 v65, v43, v57
	s_waitcnt lgkmcnt(0)
	v_fmac_f32_e32 v62, v44, v58
	ds_read_b128 v[240:243], v11 offset:6656
	ds_read_b128 v[244:247], v11 offset:6672
	ds_read_b128 v[248:251], v11 offset:6688
	v_add_f32_e32 v46, v63, v62
	v_add_f32_e32 v47, v64, v65
	v_add_f32_e32 v46, v47, v46
	v_sub_f32_e32 v45, v45, v46
	v_lshlrev_b32_e32 v46, 16, v238
	v_mul_f32_e32 v46, v239, v46
	s_and_saveexec_b64 s[0:1], s[16:17]
	s_cbranch_execz .LBB0_857
	v_mul_f32_e32 v46, v46, v254
.LBB0_857:
	s_or_b64 exec, exec, s[0:1]
	ds_read_u16 v238, v18 offset:7344
	ds_read_b32 v239, v16 offset:108
	ds_read_b32 v254, v15 offset:108
	ds_read_b128 v[48:51], v11 offset:6704
	ds_read_b128 v[52:55], v11 offset:6720
	ds_read_b128 v[56:59], v11 offset:6736
	ds_read_b128 v[60:63], v11 offset:6752
	s_waitcnt lgkmcnt(9)
	v_fma_f32 v47, v2, v240, 0
	v_fma_f32 v64, v3, v241, 0
	v_fma_f32 v65, v4, v242, 0
	v_fma_f32 v66, v5, v243, 0
	s_waitcnt lgkmcnt(8)
	v_fmac_f32_e32 v47, v6, v244
	v_fmac_f32_e32 v64, v7, v245
	v_fmac_f32_e32 v65, v8, v246
	v_fmac_f32_e32 v66, v9, v247
	s_waitcnt lgkmcnt(7)
	v_fmac_f32_e32 v47, v10, v248
	v_fmac_f32_e32 v64, v12, v249
	v_fmac_f32_e32 v65, v13, v250
	v_fmac_f32_e32 v66, v14, v251
	s_waitcnt lgkmcnt(3)
	v_fmac_f32_e32 v47, v17, v48
	v_fmac_f32_e32 v64, v19, v49
	v_fmac_f32_e32 v65, v28, v50
	v_fmac_f32_e32 v66, v35, v51
	s_waitcnt lgkmcnt(2)
	v_fmac_f32_e32 v47, v36, v52
	v_fmac_f32_e32 v64, v37, v53
	v_fmac_f32_e32 v65, v38, v54
	v_fmac_f32_e32 v66, v39, v55
	s_waitcnt lgkmcnt(1)
	v_fmac_f32_e32 v47, v40, v56
	v_fmac_f32_e32 v64, v41, v57
	v_fmac_f32_e32 v65, v42, v58
	v_fmac_f32_e32 v66, v43, v59
	s_waitcnt lgkmcnt(0)
	v_fmac_f32_e32 v47, v44, v60
	v_fmac_f32_e32 v64, v45, v61
	ds_read_b128 v[240:243], v11 offset:6912
	ds_read_b128 v[244:247], v11 offset:6928
	ds_read_b128 v[248:251], v11 offset:6944
	v_add_f32_e32 v47, v47, v64
	v_add_f32_e32 v48, v65, v66
	v_add_f32_e32 v47, v48, v47
	v_sub_f32_e32 v46, v46, v47
	v_lshlrev_b32_e32 v47, 16, v238
	v_mul_f32_e32 v47, v239, v47
	s_and_saveexec_b64 s[0:1], s[16:17]
	s_cbranch_execz .LBB0_859
	v_mul_f32_e32 v47, v47, v254
.LBB0_859:
	s_or_b64 exec, exec, s[0:1]
	ds_read_u16 v238, v18 offset:7616
	ds_read_b32 v239, v16 offset:112
	ds_read_b32 v254, v15 offset:112
	ds_read_b128 v[48:51], v11 offset:6960
	ds_read_b128 v[52:55], v11 offset:6976
	ds_read_b128 v[56:59], v11 offset:6992
	ds_read_b128 v[60:63], v11 offset:7008
	s_waitcnt lgkmcnt(9)
	v_fma_f32 v64, v2, v240, 0
	v_fma_f32 v65, v3, v241, 0
	v_fma_f32 v66, v4, v242, 0
	v_fma_f32 v67, v5, v243, 0
	s_waitcnt lgkmcnt(8)
	v_fmac_f32_e32 v64, v6, v244
	v_fmac_f32_e32 v65, v7, v245
	v_fmac_f32_e32 v66, v8, v246
	v_fmac_f32_e32 v67, v9, v247
	s_waitcnt lgkmcnt(7)
	v_fmac_f32_e32 v64, v10, v248
	v_fmac_f32_e32 v65, v12, v249
	v_fmac_f32_e32 v66, v13, v250
	v_fmac_f32_e32 v67, v14, v251
	s_waitcnt lgkmcnt(3)
	v_fmac_f32_e32 v64, v17, v48
	v_fmac_f32_e32 v65, v19, v49
	v_fmac_f32_e32 v66, v28, v50
	v_fmac_f32_e32 v67, v35, v51
	s_waitcnt lgkmcnt(2)
	v_fmac_f32_e32 v64, v36, v52
	v_fmac_f32_e32 v65, v37, v53
	v_fmac_f32_e32 v66, v38, v54
	v_fmac_f32_e32 v67, v39, v55
	s_waitcnt lgkmcnt(1)
	v_fmac_f32_e32 v64, v40, v56
	v_fmac_f32_e32 v65, v41, v57
	v_fmac_f32_e32 v66, v42, v58
	v_fmac_f32_e32 v67, v43, v59
	s_waitcnt lgkmcnt(0)
	v_fmac_f32_e32 v64, v44, v60
	v_fmac_f32_e32 v65, v45, v61
	v_fmac_f32_e32 v66, v46, v62
	ds_read_b128 v[240:243], v11 offset:7168
	ds_read_b128 v[244:247], v11 offset:7184
	ds_read_b128 v[248:251], v11 offset:7200
	v_add_f32_e32 v48, v64, v65
	v_add_f32_e32 v49, v67, v66
	v_add_f32_e32 v48, v48, v49
	v_sub_f32_e32 v47, v47, v48
	v_lshlrev_b32_e32 v48, 16, v238
	v_mul_f32_e32 v48, v239, v48
	s_and_saveexec_b64 s[0:1], s[16:17]
	s_cbranch_execz .LBB0_861
	v_mul_f32_e32 v48, v48, v254
.LBB0_861:
	s_or_b64 exec, exec, s[0:1]
	ds_read_u16 v238, v18 offset:7888
	ds_read_b32 v239, v16 offset:116
	ds_read_b32 v254, v15 offset:116
	ds_read_b128 v[50:53], v11 offset:7216
	ds_read_b128 v[54:57], v11 offset:7232
	ds_read_b128 v[58:61], v11 offset:7248
	ds_read_b128 v[62:65], v11 offset:7264
	s_waitcnt lgkmcnt(9)
	v_fma_f32 v49, v2, v240, 0
	v_fma_f32 v66, v3, v241, 0
	v_fma_f32 v67, v4, v242, 0
	v_fma_f32 v68, v5, v243, 0
	s_waitcnt lgkmcnt(8)
	v_fmac_f32_e32 v49, v6, v244
	v_fmac_f32_e32 v66, v7, v245
	v_fmac_f32_e32 v67, v8, v246
	v_fmac_f32_e32 v68, v9, v247
	s_waitcnt lgkmcnt(7)
	v_fmac_f32_e32 v49, v10, v248
	v_fmac_f32_e32 v66, v12, v249
	v_fmac_f32_e32 v67, v13, v250
	v_fmac_f32_e32 v68, v14, v251
	s_waitcnt lgkmcnt(3)
	v_fmac_f32_e32 v49, v17, v50
	v_fmac_f32_e32 v66, v19, v51
	v_fmac_f32_e32 v67, v28, v52
	v_fmac_f32_e32 v68, v35, v53
	s_waitcnt lgkmcnt(2)
	v_fmac_f32_e32 v49, v36, v54
	v_fmac_f32_e32 v66, v37, v55
	v_fmac_f32_e32 v67, v38, v56
	v_fmac_f32_e32 v68, v39, v57
	s_waitcnt lgkmcnt(1)
	v_fmac_f32_e32 v49, v40, v58
	v_fmac_f32_e32 v66, v41, v59
	v_fmac_f32_e32 v67, v42, v60
	v_fmac_f32_e32 v68, v43, v61
	s_waitcnt lgkmcnt(0)
	v_fmac_f32_e32 v49, v44, v62
	v_fmac_f32_e32 v66, v45, v63
	v_fmac_f32_e32 v67, v46, v64
	v_fmac_f32_e32 v68, v47, v65
	ds_read_b128 v[240:243], v11 offset:7424
	ds_read_b128 v[244:247], v11 offset:7440
	ds_read_b128 v[248:251], v11 offset:7456
	v_add_f32_e32 v49, v49, v66
	v_add_f32_e32 v50, v67, v68
	v_add_f32_e32 v49, v49, v50
	v_sub_f32_e32 v48, v48, v49
	v_lshlrev_b32_e32 v49, 16, v238
	v_mul_f32_e32 v49, v239, v49
	s_and_saveexec_b64 s[0:1], s[16:17]
	s_cbranch_execz .LBB0_863
	v_mul_f32_e32 v49, v49, v254
.LBB0_863:
	s_or_b64 exec, exec, s[0:1]
	ds_read_u16 v238, v18 offset:8160
	ds_read_b32 v239, v16 offset:120
	ds_read_b32 v254, v15 offset:120
	ds_read_b128 v[50:53], v11 offset:7472
	ds_read_b128 v[54:57], v11 offset:7488
	ds_read_b128 v[58:61], v11 offset:7504
	ds_read_b128 v[62:65], v11 offset:7520
	s_waitcnt lgkmcnt(9)
	v_fma_f32 v66, v2, v240, 0
	v_fma_f32 v67, v3, v241, 0
	v_fma_f32 v68, v4, v242, 0
	v_fma_f32 v69, v5, v243, 0
	ds_read_b128 v[240:243], v11 offset:7536
	s_waitcnt lgkmcnt(9)
	v_fmac_f32_e32 v66, v6, v244
	v_fmac_f32_e32 v67, v7, v245
	v_fmac_f32_e32 v68, v8, v246
	v_fmac_f32_e32 v69, v9, v247
	s_waitcnt lgkmcnt(8)
	v_fmac_f32_e32 v66, v10, v248
	v_fmac_f32_e32 v67, v12, v249
	v_fmac_f32_e32 v68, v13, v250
	v_fmac_f32_e32 v69, v14, v251
	s_waitcnt lgkmcnt(4)
	v_fmac_f32_e32 v66, v17, v50
	v_fmac_f32_e32 v67, v19, v51
	v_fmac_f32_e32 v68, v28, v52
	v_fmac_f32_e32 v69, v35, v53
	s_waitcnt lgkmcnt(3)
	v_fmac_f32_e32 v66, v36, v54
	v_fmac_f32_e32 v67, v37, v55
	v_fmac_f32_e32 v68, v38, v56
	v_fmac_f32_e32 v69, v39, v57
	s_waitcnt lgkmcnt(2)
	v_fmac_f32_e32 v66, v40, v58
	v_fmac_f32_e32 v67, v41, v59
	v_fmac_f32_e32 v68, v42, v60
	v_fmac_f32_e32 v69, v43, v61
	s_waitcnt lgkmcnt(1)
	v_fmac_f32_e32 v66, v44, v62
	v_fmac_f32_e32 v67, v45, v63
	v_fmac_f32_e32 v68, v46, v64
	v_fmac_f32_e32 v69, v47, v65
	s_waitcnt lgkmcnt(0)
	v_fmac_f32_e32 v66, v48, v240
	ds_read_b128 v[240:243], v11 offset:7680
	ds_read_b128 v[244:247], v11 offset:7696
	ds_read_b128 v[248:251], v11 offset:7712
	v_add_f32_e32 v50, v67, v66
	v_add_f32_e32 v51, v68, v69
	v_add_f32_e32 v50, v51, v50
	v_sub_f32_e32 v49, v49, v50
	v_lshlrev_b32_e32 v50, 16, v238
	v_mul_f32_e32 v50, v239, v50
	s_and_saveexec_b64 s[0:1], s[16:17]
	s_cbranch_execz .LBB0_865
	v_mul_f32_e32 v50, v50, v254
.LBB0_865:
	s_or_b64 exec, exec, s[0:1]
	ds_read_u16 v238, v18 offset:8432
	ds_read_b32 v239, v16 offset:124
	ds_read_b32 v254, v15 offset:124
	ds_read_b128 v[52:55], v11 offset:7728
	ds_read_b128 v[56:59], v11 offset:7744
	ds_read_b128 v[60:63], v11 offset:7760
	ds_read_b128 v[64:67], v11 offset:7776
	s_waitcnt lgkmcnt(9)
	v_fma_f32 v51, v2, v240, 0
	v_fma_f32 v68, v3, v241, 0
	v_fma_f32 v69, v4, v242, 0
	v_fma_f32 v70, v5, v243, 0
	ds_read_b128 v[240:243], v11 offset:7792
	s_waitcnt lgkmcnt(9)
	v_fmac_f32_e32 v51, v6, v244
	v_fmac_f32_e32 v68, v7, v245
	v_fmac_f32_e32 v69, v8, v246
	v_fmac_f32_e32 v70, v9, v247
	s_waitcnt lgkmcnt(8)
	v_fmac_f32_e32 v51, v10, v248
	v_fmac_f32_e32 v68, v12, v249
	v_fmac_f32_e32 v69, v13, v250
	v_fmac_f32_e32 v70, v14, v251
	s_waitcnt lgkmcnt(4)
	v_fmac_f32_e32 v51, v17, v52
	v_fmac_f32_e32 v68, v19, v53
	v_fmac_f32_e32 v69, v28, v54
	v_fmac_f32_e32 v70, v35, v55
	s_waitcnt lgkmcnt(3)
	v_fmac_f32_e32 v51, v36, v56
	v_fmac_f32_e32 v68, v37, v57
	v_fmac_f32_e32 v69, v38, v58
	v_fmac_f32_e32 v70, v39, v59
	s_waitcnt lgkmcnt(2)
	v_fmac_f32_e32 v51, v40, v60
	v_fmac_f32_e32 v68, v41, v61
	v_fmac_f32_e32 v69, v42, v62
	v_fmac_f32_e32 v70, v43, v63
	s_waitcnt lgkmcnt(1)
	v_fmac_f32_e32 v51, v44, v64
	v_fmac_f32_e32 v68, v45, v65
	v_fmac_f32_e32 v69, v46, v66
	v_fmac_f32_e32 v70, v47, v67
	s_waitcnt lgkmcnt(0)
	v_fmac_f32_e32 v51, v48, v240
	v_fmac_f32_e32 v68, v49, v241
	ds_read_b128 v[240:243], v11 offset:7936
	ds_read_b128 v[244:247], v11 offset:7952
	ds_read_b128 v[248:251], v11 offset:7968
	v_add_f32_e32 v51, v51, v68
	v_add_f32_e32 v52, v69, v70
	v_add_f32_e32 v51, v52, v51
	v_sub_f32_e32 v50, v50, v51
	v_lshlrev_b32_e32 v51, 16, v238
	v_mul_f32_e32 v51, v239, v51
	s_and_saveexec_b64 s[0:1], s[16:17]
	s_cbranch_execz .LBB0_867
	v_mul_f32_e32 v51, v51, v254
.LBB0_867:
	s_or_b64 exec, exec, s[0:1]
	ds_read_u16 v238, v18 offset:8704
	ds_read_b32 v239, v16 offset:128
	ds_read_b32 v254, v15 offset:128
	ds_read_b128 v[52:55], v11 offset:7984
	ds_read_b128 v[56:59], v11 offset:8000
	ds_read_b128 v[60:63], v11 offset:8016
	ds_read_b128 v[64:67], v11 offset:8032
	s_waitcnt lgkmcnt(9)
	v_fma_f32 v68, v2, v240, 0
	v_fma_f32 v69, v3, v241, 0
	v_fma_f32 v70, v4, v242, 0
	v_fma_f32 v71, v5, v243, 0
	ds_read_b128 v[240:243], v11 offset:8048
	s_waitcnt lgkmcnt(9)
	v_fmac_f32_e32 v68, v6, v244
	v_fmac_f32_e32 v69, v7, v245
	v_fmac_f32_e32 v70, v8, v246
	v_fmac_f32_e32 v71, v9, v247
	s_waitcnt lgkmcnt(8)
	v_fmac_f32_e32 v68, v10, v248
	v_fmac_f32_e32 v69, v12, v249
	v_fmac_f32_e32 v70, v13, v250
	v_fmac_f32_e32 v71, v14, v251
	s_waitcnt lgkmcnt(4)
	v_fmac_f32_e32 v68, v17, v52
	v_fmac_f32_e32 v69, v19, v53
	v_fmac_f32_e32 v70, v28, v54
	v_fmac_f32_e32 v71, v35, v55
	s_waitcnt lgkmcnt(3)
	v_fmac_f32_e32 v68, v36, v56
	v_fmac_f32_e32 v69, v37, v57
	v_fmac_f32_e32 v70, v38, v58
	v_fmac_f32_e32 v71, v39, v59
	s_waitcnt lgkmcnt(2)
	v_fmac_f32_e32 v68, v40, v60
	v_fmac_f32_e32 v69, v41, v61
	v_fmac_f32_e32 v70, v42, v62
	v_fmac_f32_e32 v71, v43, v63
	s_waitcnt lgkmcnt(1)
	v_fmac_f32_e32 v68, v44, v64
	v_fmac_f32_e32 v69, v45, v65
	v_fmac_f32_e32 v70, v46, v66
	v_fmac_f32_e32 v71, v47, v67
	s_waitcnt lgkmcnt(0)
	v_fmac_f32_e32 v68, v48, v240
	v_fmac_f32_e32 v69, v49, v241
	v_fmac_f32_e32 v70, v50, v242
	ds_read_b128 v[240:243], v11 offset:8192
	ds_read_b128 v[244:247], v11 offset:8208
	ds_read_b128 v[248:251], v11 offset:8224
	v_add_f32_e32 v52, v68, v69
	v_add_f32_e32 v53, v71, v70
	v_add_f32_e32 v52, v52, v53
	v_sub_f32_e32 v51, v51, v52
	v_lshlrev_b32_e32 v52, 16, v238
	v_mul_f32_e32 v52, v239, v52
	s_and_saveexec_b64 s[0:1], s[16:17]
	s_cbranch_execz .LBB0_869
	v_mul_f32_e32 v52, v52, v254
.LBB0_869:
	s_or_b64 exec, exec, s[0:1]
	ds_read_u16 v238, v18 offset:8976
	ds_read_b32 v239, v16 offset:132
	ds_read_b32 v254, v15 offset:132
	ds_read_b128 v[54:57], v11 offset:8240
	ds_read_b128 v[58:61], v11 offset:8256
	ds_read_b128 v[62:65], v11 offset:8272
	ds_read_b128 v[66:69], v11 offset:8288
	s_waitcnt lgkmcnt(9)
	v_fma_f32 v53, v2, v240, 0
	v_fma_f32 v70, v3, v241, 0
	v_fma_f32 v71, v4, v242, 0
	v_fma_f32 v72, v5, v243, 0
	ds_read_b128 v[240:243], v11 offset:8304
	s_waitcnt lgkmcnt(9)
	v_fmac_f32_e32 v53, v6, v244
	v_fmac_f32_e32 v70, v7, v245
	v_fmac_f32_e32 v71, v8, v246
	v_fmac_f32_e32 v72, v9, v247
	s_waitcnt lgkmcnt(8)
	v_fmac_f32_e32 v53, v10, v248
	v_fmac_f32_e32 v70, v12, v249
	v_fmac_f32_e32 v71, v13, v250
	v_fmac_f32_e32 v72, v14, v251
	s_waitcnt lgkmcnt(4)
	v_fmac_f32_e32 v53, v17, v54
	v_fmac_f32_e32 v70, v19, v55
	v_fmac_f32_e32 v71, v28, v56
	v_fmac_f32_e32 v72, v35, v57
	s_waitcnt lgkmcnt(3)
	v_fmac_f32_e32 v53, v36, v58
	v_fmac_f32_e32 v70, v37, v59
	v_fmac_f32_e32 v71, v38, v60
	v_fmac_f32_e32 v72, v39, v61
	s_waitcnt lgkmcnt(2)
	v_fmac_f32_e32 v53, v40, v62
	v_fmac_f32_e32 v70, v41, v63
	v_fmac_f32_e32 v71, v42, v64
	v_fmac_f32_e32 v72, v43, v65
	s_waitcnt lgkmcnt(1)
	v_fmac_f32_e32 v53, v44, v66
	v_fmac_f32_e32 v70, v45, v67
	v_fmac_f32_e32 v71, v46, v68
	v_fmac_f32_e32 v72, v47, v69
	s_waitcnt lgkmcnt(0)
	v_fmac_f32_e32 v53, v48, v240
	v_fmac_f32_e32 v70, v49, v241
	v_fmac_f32_e32 v71, v50, v242
	v_fmac_f32_e32 v72, v51, v243
	ds_read_b128 v[240:243], v11 offset:8448
	ds_read_b128 v[244:247], v11 offset:8464
	ds_read_b128 v[248:251], v11 offset:8480
	v_add_f32_e32 v53, v53, v70
	v_add_f32_e32 v54, v71, v72
	v_add_f32_e32 v53, v53, v54
	v_sub_f32_e32 v52, v52, v53
	v_lshlrev_b32_e32 v53, 16, v238
	v_mul_f32_e32 v53, v239, v53
	s_and_saveexec_b64 s[0:1], s[16:17]
	s_cbranch_execz .LBB0_871
	v_mul_f32_e32 v53, v53, v254
.LBB0_871:
	s_or_b64 exec, exec, s[0:1]
	ds_read_u16 v238, v18 offset:9248
	ds_read_b32 v239, v16 offset:136
	ds_read_b32 v254, v15 offset:136
	ds_read_b128 v[54:57], v11 offset:8496
	ds_read_b128 v[58:61], v11 offset:8512
	ds_read_b128 v[62:65], v11 offset:8528
	ds_read_b128 v[66:69], v11 offset:8544
	s_waitcnt lgkmcnt(9)
	v_fma_f32 v70, v2, v240, 0
	v_fma_f32 v71, v3, v241, 0
	v_fma_f32 v72, v4, v242, 0
	v_fma_f32 v73, v5, v243, 0
	ds_read_b128 v[240:243], v11 offset:8560
	s_waitcnt lgkmcnt(9)
	v_fmac_f32_e32 v70, v6, v244
	v_fmac_f32_e32 v71, v7, v245
	v_fmac_f32_e32 v72, v8, v246
	v_fmac_f32_e32 v73, v9, v247
	ds_read_b128 v[244:247], v11 offset:8576
	s_waitcnt lgkmcnt(9)
	v_fmac_f32_e32 v70, v10, v248
	v_fmac_f32_e32 v71, v12, v249
	v_fmac_f32_e32 v72, v13, v250
	v_fmac_f32_e32 v73, v14, v251
	s_waitcnt lgkmcnt(5)
	v_fmac_f32_e32 v70, v17, v54
	v_fmac_f32_e32 v71, v19, v55
	v_fmac_f32_e32 v72, v28, v56
	v_fmac_f32_e32 v73, v35, v57
	s_waitcnt lgkmcnt(4)
	v_fmac_f32_e32 v70, v36, v58
	v_fmac_f32_e32 v71, v37, v59
	v_fmac_f32_e32 v72, v38, v60
	v_fmac_f32_e32 v73, v39, v61
	s_waitcnt lgkmcnt(3)
	v_fmac_f32_e32 v70, v40, v62
	v_fmac_f32_e32 v71, v41, v63
	v_fmac_f32_e32 v72, v42, v64
	v_fmac_f32_e32 v73, v43, v65
	s_waitcnt lgkmcnt(2)
	v_fmac_f32_e32 v70, v44, v66
	v_fmac_f32_e32 v71, v45, v67
	v_fmac_f32_e32 v72, v46, v68
	v_fmac_f32_e32 v73, v47, v69
	s_waitcnt lgkmcnt(1)
	v_fmac_f32_e32 v70, v48, v240
	v_fmac_f32_e32 v71, v49, v241
	v_fmac_f32_e32 v72, v50, v242
	v_fmac_f32_e32 v73, v51, v243
	s_waitcnt lgkmcnt(0)
	v_fmac_f32_e32 v70, v52, v244
	ds_read_b128 v[240:243], v11 offset:8704
	ds_read_b128 v[244:247], v11 offset:8720
	ds_read_b128 v[248:251], v11 offset:8736
	v_add_f32_e32 v54, v71, v70
	v_add_f32_e32 v55, v72, v73
	v_add_f32_e32 v54, v55, v54
	v_sub_f32_e32 v53, v53, v54
	v_lshlrev_b32_e32 v54, 16, v238
	v_mul_f32_e32 v54, v239, v54
	s_and_saveexec_b64 s[0:1], s[16:17]
	s_cbranch_execz .LBB0_873
	v_mul_f32_e32 v54, v54, v254
.LBB0_873:
	s_or_b64 exec, exec, s[0:1]
	ds_read_u16 v238, v18 offset:9520
	ds_read_b32 v239, v16 offset:140
	ds_read_b32 v254, v15 offset:140
	ds_read_b128 v[56:59], v11 offset:8752
	ds_read_b128 v[60:63], v11 offset:8768
	ds_read_b128 v[64:67], v11 offset:8784
	ds_read_b128 v[68:71], v11 offset:8800
	s_waitcnt lgkmcnt(9)
	v_fma_f32 v55, v2, v240, 0
	v_fma_f32 v72, v3, v241, 0
	v_fma_f32 v73, v4, v242, 0
	v_fma_f32 v74, v5, v243, 0
	ds_read_b128 v[240:243], v11 offset:8816
	s_waitcnt lgkmcnt(9)
	v_fmac_f32_e32 v55, v6, v244
	v_fmac_f32_e32 v72, v7, v245
	v_fmac_f32_e32 v73, v8, v246
	v_fmac_f32_e32 v74, v9, v247
	ds_read_b128 v[244:247], v11 offset:8832
	s_waitcnt lgkmcnt(9)
	v_fmac_f32_e32 v55, v10, v248
	v_fmac_f32_e32 v72, v12, v249
	v_fmac_f32_e32 v73, v13, v250
	v_fmac_f32_e32 v74, v14, v251
	s_waitcnt lgkmcnt(5)
	v_fmac_f32_e32 v55, v17, v56
	v_fmac_f32_e32 v72, v19, v57
	v_fmac_f32_e32 v73, v28, v58
	v_fmac_f32_e32 v74, v35, v59
	s_waitcnt lgkmcnt(4)
	v_fmac_f32_e32 v55, v36, v60
	v_fmac_f32_e32 v72, v37, v61
	v_fmac_f32_e32 v73, v38, v62
	v_fmac_f32_e32 v74, v39, v63
	s_waitcnt lgkmcnt(3)
	v_fmac_f32_e32 v55, v40, v64
	v_fmac_f32_e32 v72, v41, v65
	v_fmac_f32_e32 v73, v42, v66
	v_fmac_f32_e32 v74, v43, v67
	s_waitcnt lgkmcnt(2)
	v_fmac_f32_e32 v55, v44, v68
	v_fmac_f32_e32 v72, v45, v69
	v_fmac_f32_e32 v73, v46, v70
	v_fmac_f32_e32 v74, v47, v71
	s_waitcnt lgkmcnt(1)
	v_fmac_f32_e32 v55, v48, v240
	v_fmac_f32_e32 v72, v49, v241
	v_fmac_f32_e32 v73, v50, v242
	v_fmac_f32_e32 v74, v51, v243
	s_waitcnt lgkmcnt(0)
	v_fmac_f32_e32 v55, v52, v244
	v_fmac_f32_e32 v72, v53, v245
	ds_read_b128 v[240:243], v11 offset:8960
	ds_read_b128 v[244:247], v11 offset:8976
	ds_read_b128 v[248:251], v11 offset:8992
	v_add_f32_e32 v55, v55, v72
	v_add_f32_e32 v56, v73, v74
	v_add_f32_e32 v55, v56, v55
	v_sub_f32_e32 v54, v54, v55
	v_lshlrev_b32_e32 v55, 16, v238
	v_mul_f32_e32 v55, v239, v55
	s_and_saveexec_b64 s[0:1], s[16:17]
	s_cbranch_execz .LBB0_875
	v_mul_f32_e32 v55, v55, v254
.LBB0_875:
	s_or_b64 exec, exec, s[0:1]
	ds_read_u16 v238, v18 offset:9792
	ds_read_b32 v239, v16 offset:144
	ds_read_b32 v254, v15 offset:144
	ds_read_b128 v[56:59], v11 offset:9008
	ds_read_b128 v[60:63], v11 offset:9024
	ds_read_b128 v[64:67], v11 offset:9040
	ds_read_b128 v[68:71], v11 offset:9056
	s_waitcnt lgkmcnt(9)
	v_fma_f32 v72, v2, v240, 0
	v_fma_f32 v73, v3, v241, 0
	v_fma_f32 v74, v4, v242, 0
	v_fma_f32 v75, v5, v243, 0
	ds_read_b128 v[240:243], v11 offset:9072
	s_waitcnt lgkmcnt(9)
	v_fmac_f32_e32 v72, v6, v244
	v_fmac_f32_e32 v73, v7, v245
	v_fmac_f32_e32 v74, v8, v246
	v_fmac_f32_e32 v75, v9, v247
	ds_read_b128 v[244:247], v11 offset:9088
	s_waitcnt lgkmcnt(9)
	v_fmac_f32_e32 v72, v10, v248
	v_fmac_f32_e32 v73, v12, v249
	v_fmac_f32_e32 v74, v13, v250
	v_fmac_f32_e32 v75, v14, v251
	s_waitcnt lgkmcnt(5)
	v_fmac_f32_e32 v72, v17, v56
	v_fmac_f32_e32 v73, v19, v57
	v_fmac_f32_e32 v74, v28, v58
	v_fmac_f32_e32 v75, v35, v59
	s_waitcnt lgkmcnt(4)
	v_fmac_f32_e32 v72, v36, v60
	v_fmac_f32_e32 v73, v37, v61
	v_fmac_f32_e32 v74, v38, v62
	v_fmac_f32_e32 v75, v39, v63
	s_waitcnt lgkmcnt(3)
	v_fmac_f32_e32 v72, v40, v64
	v_fmac_f32_e32 v73, v41, v65
	v_fmac_f32_e32 v74, v42, v66
	v_fmac_f32_e32 v75, v43, v67
	s_waitcnt lgkmcnt(2)
	v_fmac_f32_e32 v72, v44, v68
	v_fmac_f32_e32 v73, v45, v69
	v_fmac_f32_e32 v74, v46, v70
	v_fmac_f32_e32 v75, v47, v71
	s_waitcnt lgkmcnt(1)
	v_fmac_f32_e32 v72, v48, v240
	v_fmac_f32_e32 v73, v49, v241
	v_fmac_f32_e32 v74, v50, v242
	v_fmac_f32_e32 v75, v51, v243
	s_waitcnt lgkmcnt(0)
	v_fmac_f32_e32 v72, v52, v244
	v_fmac_f32_e32 v73, v53, v245
	v_fmac_f32_e32 v74, v54, v246
	ds_read_b128 v[240:243], v11 offset:9216
	ds_read_b128 v[244:247], v11 offset:9232
	ds_read_b128 v[248:251], v11 offset:9248
	v_add_f32_e32 v56, v72, v73
	v_add_f32_e32 v57, v75, v74
	v_add_f32_e32 v56, v56, v57
	v_sub_f32_e32 v55, v55, v56
	v_lshlrev_b32_e32 v56, 16, v238
	v_mul_f32_e32 v56, v239, v56
	s_and_saveexec_b64 s[0:1], s[16:17]
	s_cbranch_execz .LBB0_877
	v_mul_f32_e32 v56, v56, v254
.LBB0_877:
	s_or_b64 exec, exec, s[0:1]
	ds_read_u16 v238, v18 offset:10064
	ds_read_b32 v239, v16 offset:148
	ds_read_b32 v254, v15 offset:148
	ds_read_b128 v[58:61], v11 offset:9264
	ds_read_b128 v[62:65], v11 offset:9280
	ds_read_b128 v[66:69], v11 offset:9296
	ds_read_b128 v[70:73], v11 offset:9312
	s_waitcnt lgkmcnt(9)
	v_fma_f32 v57, v2, v240, 0
	v_fma_f32 v74, v3, v241, 0
	v_fma_f32 v75, v4, v242, 0
	v_fma_f32 v76, v5, v243, 0
	ds_read_b128 v[240:243], v11 offset:9328
	s_waitcnt lgkmcnt(9)
	v_fmac_f32_e32 v57, v6, v244
	v_fmac_f32_e32 v74, v7, v245
	v_fmac_f32_e32 v75, v8, v246
	v_fmac_f32_e32 v76, v9, v247
	ds_read_b128 v[244:247], v11 offset:9344
	s_waitcnt lgkmcnt(9)
	v_fmac_f32_e32 v57, v10, v248
	v_fmac_f32_e32 v74, v12, v249
	v_fmac_f32_e32 v75, v13, v250
	v_fmac_f32_e32 v76, v14, v251
	s_waitcnt lgkmcnt(5)
	v_fmac_f32_e32 v57, v17, v58
	v_fmac_f32_e32 v74, v19, v59
	v_fmac_f32_e32 v75, v28, v60
	v_fmac_f32_e32 v76, v35, v61
	s_waitcnt lgkmcnt(4)
	v_fmac_f32_e32 v57, v36, v62
	v_fmac_f32_e32 v74, v37, v63
	v_fmac_f32_e32 v75, v38, v64
	v_fmac_f32_e32 v76, v39, v65
	s_waitcnt lgkmcnt(3)
	v_fmac_f32_e32 v57, v40, v66
	v_fmac_f32_e32 v74, v41, v67
	v_fmac_f32_e32 v75, v42, v68
	v_fmac_f32_e32 v76, v43, v69
	s_waitcnt lgkmcnt(2)
	v_fmac_f32_e32 v57, v44, v70
	v_fmac_f32_e32 v74, v45, v71
	v_fmac_f32_e32 v75, v46, v72
	v_fmac_f32_e32 v76, v47, v73
	s_waitcnt lgkmcnt(1)
	v_fmac_f32_e32 v57, v48, v240
	v_fmac_f32_e32 v74, v49, v241
	v_fmac_f32_e32 v75, v50, v242
	v_fmac_f32_e32 v76, v51, v243
	s_waitcnt lgkmcnt(0)
	v_fmac_f32_e32 v57, v52, v244
	v_fmac_f32_e32 v74, v53, v245
	v_fmac_f32_e32 v75, v54, v246
	v_fmac_f32_e32 v76, v55, v247
	ds_read_b128 v[240:243], v11 offset:9472
	ds_read_b128 v[244:247], v11 offset:9488
	ds_read_b128 v[248:251], v11 offset:9504
	v_add_f32_e32 v57, v57, v74
	v_add_f32_e32 v58, v75, v76
	v_add_f32_e32 v57, v57, v58
	v_sub_f32_e32 v56, v56, v57
	v_lshlrev_b32_e32 v57, 16, v238
	v_mul_f32_e32 v57, v239, v57
	s_and_saveexec_b64 s[0:1], s[16:17]
	s_cbranch_execz .LBB0_879
	v_mul_f32_e32 v57, v57, v254
.LBB0_879:
	s_or_b64 exec, exec, s[0:1]
	ds_read_u16 v238, v18 offset:10336
	ds_read_b32 v239, v16 offset:152
	ds_read_b32 v254, v15 offset:152
	ds_read_b128 v[58:61], v11 offset:9520
	ds_read_b128 v[62:65], v11 offset:9536
	ds_read_b128 v[66:69], v11 offset:9552
	ds_read_b128 v[70:73], v11 offset:9568
	s_waitcnt lgkmcnt(9)
	v_fma_f32 v74, v2, v240, 0
	v_fma_f32 v75, v3, v241, 0
	v_fma_f32 v76, v4, v242, 0
	v_fma_f32 v77, v5, v243, 0
	ds_read_b128 v[240:243], v11 offset:9584
	s_waitcnt lgkmcnt(9)
	v_fmac_f32_e32 v74, v6, v244
	v_fmac_f32_e32 v75, v7, v245
	v_fmac_f32_e32 v76, v8, v246
	v_fmac_f32_e32 v77, v9, v247
	ds_read_b128 v[244:247], v11 offset:9600
	s_waitcnt lgkmcnt(9)
	v_fmac_f32_e32 v74, v10, v248
	v_fmac_f32_e32 v75, v12, v249
	v_fmac_f32_e32 v76, v13, v250
	v_fmac_f32_e32 v77, v14, v251
	ds_read_b128 v[248:251], v11 offset:9616
	s_waitcnt lgkmcnt(6)
	v_fmac_f32_e32 v74, v17, v58
	v_fmac_f32_e32 v75, v19, v59
	v_fmac_f32_e32 v76, v28, v60
	v_fmac_f32_e32 v77, v35, v61
	s_waitcnt lgkmcnt(5)
	v_fmac_f32_e32 v74, v36, v62
	v_fmac_f32_e32 v75, v37, v63
	v_fmac_f32_e32 v76, v38, v64
	v_fmac_f32_e32 v77, v39, v65
	s_waitcnt lgkmcnt(4)
	v_fmac_f32_e32 v74, v40, v66
	v_fmac_f32_e32 v75, v41, v67
	v_fmac_f32_e32 v76, v42, v68
	v_fmac_f32_e32 v77, v43, v69
	s_waitcnt lgkmcnt(3)
	v_fmac_f32_e32 v74, v44, v70
	v_fmac_f32_e32 v75, v45, v71
	v_fmac_f32_e32 v76, v46, v72
	v_fmac_f32_e32 v77, v47, v73
	s_waitcnt lgkmcnt(2)
	v_fmac_f32_e32 v74, v48, v240
	v_fmac_f32_e32 v75, v49, v241
	v_fmac_f32_e32 v76, v50, v242
	v_fmac_f32_e32 v77, v51, v243
	s_waitcnt lgkmcnt(1)
	v_fmac_f32_e32 v74, v52, v244
	v_fmac_f32_e32 v75, v53, v245
	v_fmac_f32_e32 v76, v54, v246
	v_fmac_f32_e32 v77, v55, v247
	s_waitcnt lgkmcnt(0)
	v_fmac_f32_e32 v74, v56, v248
	ds_read_b128 v[240:243], v11 offset:9728
	ds_read_b128 v[244:247], v11 offset:9744
	ds_read_b128 v[248:251], v11 offset:9760
	v_add_f32_e32 v58, v75, v74
	v_add_f32_e32 v59, v76, v77
	v_add_f32_e32 v58, v59, v58
	v_sub_f32_e32 v57, v57, v58
	v_lshlrev_b32_e32 v58, 16, v238
	v_mul_f32_e32 v58, v239, v58
	s_and_saveexec_b64 s[0:1], s[16:17]
	s_cbranch_execz .LBB0_881
	v_mul_f32_e32 v58, v58, v254
.LBB0_881:
	s_or_b64 exec, exec, s[0:1]
	ds_read_u16 v238, v18 offset:10608
	ds_read_b32 v239, v16 offset:156
	ds_read_b32 v254, v15 offset:156
	ds_read_b128 v[60:63], v11 offset:9776
	ds_read_b128 v[64:67], v11 offset:9792
	ds_read_b128 v[68:71], v11 offset:9808
	ds_read_b128 v[72:75], v11 offset:9824
	s_waitcnt lgkmcnt(9)
	v_fma_f32 v59, v2, v240, 0
	v_fma_f32 v76, v3, v241, 0
	v_fma_f32 v77, v4, v242, 0
	v_fma_f32 v78, v5, v243, 0
	ds_read_b128 v[240:243], v11 offset:9840
	s_waitcnt lgkmcnt(9)
	v_fmac_f32_e32 v59, v6, v244
	v_fmac_f32_e32 v76, v7, v245
	v_fmac_f32_e32 v77, v8, v246
	v_fmac_f32_e32 v78, v9, v247
	ds_read_b128 v[244:247], v11 offset:9856
	s_waitcnt lgkmcnt(9)
	v_fmac_f32_e32 v59, v10, v248
	v_fmac_f32_e32 v76, v12, v249
	v_fmac_f32_e32 v77, v13, v250
	v_fmac_f32_e32 v78, v14, v251
	ds_read_b128 v[248:251], v11 offset:9872
	s_waitcnt lgkmcnt(6)
	v_fmac_f32_e32 v59, v17, v60
	v_fmac_f32_e32 v76, v19, v61
	v_fmac_f32_e32 v77, v28, v62
	v_fmac_f32_e32 v78, v35, v63
	s_waitcnt lgkmcnt(5)
	v_fmac_f32_e32 v59, v36, v64
	v_fmac_f32_e32 v76, v37, v65
	v_fmac_f32_e32 v77, v38, v66
	v_fmac_f32_e32 v78, v39, v67
	s_waitcnt lgkmcnt(4)
	v_fmac_f32_e32 v59, v40, v68
	v_fmac_f32_e32 v76, v41, v69
	v_fmac_f32_e32 v77, v42, v70
	v_fmac_f32_e32 v78, v43, v71
	s_waitcnt lgkmcnt(3)
	v_fmac_f32_e32 v59, v44, v72
	v_fmac_f32_e32 v76, v45, v73
	v_fmac_f32_e32 v77, v46, v74
	v_fmac_f32_e32 v78, v47, v75
	s_waitcnt lgkmcnt(2)
	v_fmac_f32_e32 v59, v48, v240
	v_fmac_f32_e32 v76, v49, v241
	v_fmac_f32_e32 v77, v50, v242
	v_fmac_f32_e32 v78, v51, v243
	s_waitcnt lgkmcnt(1)
	v_fmac_f32_e32 v59, v52, v244
	v_fmac_f32_e32 v76, v53, v245
	v_fmac_f32_e32 v77, v54, v246
	v_fmac_f32_e32 v78, v55, v247
	s_waitcnt lgkmcnt(0)
	v_fmac_f32_e32 v59, v56, v248
	v_fmac_f32_e32 v76, v57, v249
	ds_read_b128 v[240:243], v11 offset:9984
	ds_read_b128 v[244:247], v11 offset:10000
	ds_read_b128 v[248:251], v11 offset:10016
	v_add_f32_e32 v59, v59, v76
	v_add_f32_e32 v60, v77, v78
	v_add_f32_e32 v59, v60, v59
	v_sub_f32_e32 v58, v58, v59
	v_lshlrev_b32_e32 v59, 16, v238
	v_mul_f32_e32 v59, v239, v59
	s_and_saveexec_b64 s[0:1], s[16:17]
	s_cbranch_execz .LBB0_883
	v_mul_f32_e32 v59, v59, v254
.LBB0_883:
	s_or_b64 exec, exec, s[0:1]
	ds_read_u16 v238, v18 offset:10880
	ds_read_b32 v239, v16 offset:160
	ds_read_b32 v254, v15 offset:160
	ds_read_b128 v[60:63], v11 offset:10032
	ds_read_b128 v[64:67], v11 offset:10048
	ds_read_b128 v[68:71], v11 offset:10064
	ds_read_b128 v[72:75], v11 offset:10080
	s_waitcnt lgkmcnt(9)
	v_fma_f32 v76, v2, v240, 0
	v_fma_f32 v77, v3, v241, 0
	v_fma_f32 v78, v4, v242, 0
	v_fma_f32 v79, v5, v243, 0
	ds_read_b128 v[240:243], v11 offset:10096
	s_waitcnt lgkmcnt(9)
	v_fmac_f32_e32 v76, v6, v244
	v_fmac_f32_e32 v77, v7, v245
	v_fmac_f32_e32 v78, v8, v246
	v_fmac_f32_e32 v79, v9, v247
	ds_read_b128 v[244:247], v11 offset:10112
	s_waitcnt lgkmcnt(9)
	v_fmac_f32_e32 v76, v10, v248
	v_fmac_f32_e32 v77, v12, v249
	v_fmac_f32_e32 v78, v13, v250
	v_fmac_f32_e32 v79, v14, v251
	ds_read_b128 v[248:251], v11 offset:10128
	s_waitcnt lgkmcnt(6)
	v_fmac_f32_e32 v76, v17, v60
	v_fmac_f32_e32 v77, v19, v61
	v_fmac_f32_e32 v78, v28, v62
	v_fmac_f32_e32 v79, v35, v63
	s_waitcnt lgkmcnt(5)
	v_fmac_f32_e32 v76, v36, v64
	v_fmac_f32_e32 v77, v37, v65
	v_fmac_f32_e32 v78, v38, v66
	v_fmac_f32_e32 v79, v39, v67
	s_waitcnt lgkmcnt(4)
	v_fmac_f32_e32 v76, v40, v68
	v_fmac_f32_e32 v77, v41, v69
	v_fmac_f32_e32 v78, v42, v70
	v_fmac_f32_e32 v79, v43, v71
	s_waitcnt lgkmcnt(3)
	v_fmac_f32_e32 v76, v44, v72
	v_fmac_f32_e32 v77, v45, v73
	v_fmac_f32_e32 v78, v46, v74
	v_fmac_f32_e32 v79, v47, v75
	s_waitcnt lgkmcnt(2)
	v_fmac_f32_e32 v76, v48, v240
	v_fmac_f32_e32 v77, v49, v241
	v_fmac_f32_e32 v78, v50, v242
	v_fmac_f32_e32 v79, v51, v243
	s_waitcnt lgkmcnt(1)
	v_fmac_f32_e32 v76, v52, v244
	v_fmac_f32_e32 v77, v53, v245
	v_fmac_f32_e32 v78, v54, v246
	v_fmac_f32_e32 v79, v55, v247
	s_waitcnt lgkmcnt(0)
	v_fmac_f32_e32 v76, v56, v248
	v_fmac_f32_e32 v77, v57, v249
	v_fmac_f32_e32 v78, v58, v250
	ds_read_b128 v[240:243], v11 offset:10240
	ds_read_b128 v[244:247], v11 offset:10256
	ds_read_b128 v[248:251], v11 offset:10272
	v_add_f32_e32 v60, v76, v77
	v_add_f32_e32 v61, v79, v78
	v_add_f32_e32 v60, v60, v61
	v_sub_f32_e32 v59, v59, v60
	v_lshlrev_b32_e32 v60, 16, v238
	v_mul_f32_e32 v60, v239, v60
	s_and_saveexec_b64 s[0:1], s[16:17]
	s_cbranch_execz .LBB0_885
	v_mul_f32_e32 v60, v60, v254
.LBB0_885:
	s_or_b64 exec, exec, s[0:1]
	ds_read_u16 v238, v18 offset:11152
	ds_read_b32 v239, v16 offset:164
	ds_read_b32 v254, v15 offset:164
	ds_read_b128 v[62:65], v11 offset:10288
	ds_read_b128 v[66:69], v11 offset:10304
	ds_read_b128 v[70:73], v11 offset:10320
	ds_read_b128 v[74:77], v11 offset:10336
	s_waitcnt lgkmcnt(9)
	v_fma_f32 v61, v2, v240, 0
	v_fma_f32 v78, v3, v241, 0
	v_fma_f32 v79, v4, v242, 0
	v_fma_f32 v80, v5, v243, 0
	ds_read_b128 v[240:243], v11 offset:10352
	s_waitcnt lgkmcnt(9)
	v_fmac_f32_e32 v61, v6, v244
	v_fmac_f32_e32 v78, v7, v245
	v_fmac_f32_e32 v79, v8, v246
	v_fmac_f32_e32 v80, v9, v247
	ds_read_b128 v[244:247], v11 offset:10368
	s_waitcnt lgkmcnt(9)
	v_fmac_f32_e32 v61, v10, v248
	v_fmac_f32_e32 v78, v12, v249
	v_fmac_f32_e32 v79, v13, v250
	v_fmac_f32_e32 v80, v14, v251
	ds_read_b128 v[248:251], v11 offset:10384
	s_waitcnt lgkmcnt(6)
	v_fmac_f32_e32 v61, v17, v62
	v_fmac_f32_e32 v78, v19, v63
	v_fmac_f32_e32 v79, v28, v64
	v_fmac_f32_e32 v80, v35, v65
	s_waitcnt lgkmcnt(5)
	v_fmac_f32_e32 v61, v36, v66
	v_fmac_f32_e32 v78, v37, v67
	v_fmac_f32_e32 v79, v38, v68
	v_fmac_f32_e32 v80, v39, v69
	s_waitcnt lgkmcnt(4)
	v_fmac_f32_e32 v61, v40, v70
	v_fmac_f32_e32 v78, v41, v71
	v_fmac_f32_e32 v79, v42, v72
	v_fmac_f32_e32 v80, v43, v73
	s_waitcnt lgkmcnt(3)
	v_fmac_f32_e32 v61, v44, v74
	v_fmac_f32_e32 v78, v45, v75
	v_fmac_f32_e32 v79, v46, v76
	v_fmac_f32_e32 v80, v47, v77
	s_waitcnt lgkmcnt(2)
	v_fmac_f32_e32 v61, v48, v240
	v_fmac_f32_e32 v78, v49, v241
	v_fmac_f32_e32 v79, v50, v242
	v_fmac_f32_e32 v80, v51, v243
	s_waitcnt lgkmcnt(1)
	v_fmac_f32_e32 v61, v52, v244
	v_fmac_f32_e32 v78, v53, v245
	v_fmac_f32_e32 v79, v54, v246
	v_fmac_f32_e32 v80, v55, v247
	s_waitcnt lgkmcnt(0)
	v_fmac_f32_e32 v61, v56, v248
	v_fmac_f32_e32 v78, v57, v249
	v_fmac_f32_e32 v79, v58, v250
	v_fmac_f32_e32 v80, v59, v251
	ds_read_b128 v[240:243], v11 offset:10496
	ds_read_b128 v[244:247], v11 offset:10512
	ds_read_b128 v[248:251], v11 offset:10528
	v_add_f32_e32 v61, v61, v78
	v_add_f32_e32 v62, v79, v80
	v_add_f32_e32 v61, v61, v62
	v_sub_f32_e32 v60, v60, v61
	v_lshlrev_b32_e32 v61, 16, v238
	v_mul_f32_e32 v61, v239, v61
	s_and_saveexec_b64 s[0:1], s[16:17]
	s_cbranch_execz .LBB0_887
	v_mul_f32_e32 v61, v61, v254
.LBB0_887:
	s_or_b64 exec, exec, s[0:1]
	ds_read_u16 v238, v18 offset:11424
	ds_read_b32 v239, v16 offset:168
	ds_read_b32 v254, v15 offset:168
	ds_read_b128 v[62:65], v11 offset:10544
	ds_read_b128 v[66:69], v11 offset:10560
	ds_read_b128 v[70:73], v11 offset:10576
	ds_read_b128 v[74:77], v11 offset:10592
	s_waitcnt lgkmcnt(9)
	v_fma_f32 v78, v2, v240, 0
	v_fma_f32 v79, v3, v241, 0
	v_fma_f32 v80, v4, v242, 0
	v_fma_f32 v81, v5, v243, 0
	ds_read_b128 v[240:243], v11 offset:10608
	s_waitcnt lgkmcnt(9)
	v_fmac_f32_e32 v78, v6, v244
	v_fmac_f32_e32 v79, v7, v245
	v_fmac_f32_e32 v80, v8, v246
	v_fmac_f32_e32 v81, v9, v247
	ds_read_b128 v[244:247], v11 offset:10624
	s_waitcnt lgkmcnt(9)
	v_fmac_f32_e32 v78, v10, v248
	v_fmac_f32_e32 v79, v12, v249
	v_fmac_f32_e32 v80, v13, v250
	v_fmac_f32_e32 v81, v14, v251
	ds_read_b128 v[248:251], v11 offset:10640
	s_waitcnt lgkmcnt(6)
	v_fmac_f32_e32 v78, v17, v62
	v_fmac_f32_e32 v79, v19, v63
	v_fmac_f32_e32 v80, v28, v64
	v_fmac_f32_e32 v81, v35, v65
	ds_read_b128 v[62:65], v11 offset:10656
	s_waitcnt lgkmcnt(6)
	v_fmac_f32_e32 v78, v36, v66
	v_fmac_f32_e32 v79, v37, v67
	v_fmac_f32_e32 v80, v38, v68
	v_fmac_f32_e32 v81, v39, v69
	s_waitcnt lgkmcnt(5)
	v_fmac_f32_e32 v78, v40, v70
	v_fmac_f32_e32 v79, v41, v71
	v_fmac_f32_e32 v80, v42, v72
	v_fmac_f32_e32 v81, v43, v73
	s_waitcnt lgkmcnt(4)
	v_fmac_f32_e32 v78, v44, v74
	v_fmac_f32_e32 v79, v45, v75
	v_fmac_f32_e32 v80, v46, v76
	v_fmac_f32_e32 v81, v47, v77
	s_waitcnt lgkmcnt(3)
	v_fmac_f32_e32 v78, v48, v240
	v_fmac_f32_e32 v79, v49, v241
	v_fmac_f32_e32 v80, v50, v242
	v_fmac_f32_e32 v81, v51, v243
	s_waitcnt lgkmcnt(2)
	v_fmac_f32_e32 v78, v52, v244
	v_fmac_f32_e32 v79, v53, v245
	v_fmac_f32_e32 v80, v54, v246
	v_fmac_f32_e32 v81, v55, v247
	s_waitcnt lgkmcnt(1)
	v_fmac_f32_e32 v78, v56, v248
	v_fmac_f32_e32 v79, v57, v249
	v_fmac_f32_e32 v80, v58, v250
	v_fmac_f32_e32 v81, v59, v251
	s_waitcnt lgkmcnt(0)
	v_fmac_f32_e32 v78, v60, v62
	ds_read_b128 v[240:243], v11 offset:10752
	ds_read_b128 v[244:247], v11 offset:10768
	ds_read_b128 v[248:251], v11 offset:10784
	v_add_f32_e32 v62, v79, v78
	v_add_f32_e32 v63, v80, v81
	v_add_f32_e32 v62, v63, v62
	v_sub_f32_e32 v61, v61, v62
	v_lshlrev_b32_e32 v62, 16, v238
	v_mul_f32_e32 v62, v239, v62
	s_and_saveexec_b64 s[0:1], s[16:17]
	s_cbranch_execz .LBB0_889
	v_mul_f32_e32 v62, v62, v254
.LBB0_889:
	s_or_b64 exec, exec, s[0:1]
	ds_read_u16 v238, v18 offset:11696
	ds_read_b32 v239, v16 offset:172
	ds_read_b32 v254, v15 offset:172
	ds_read_b128 v[64:67], v11 offset:10800
	ds_read_b128 v[68:71], v11 offset:10816
	ds_read_b128 v[72:75], v11 offset:10832
	ds_read_b128 v[76:79], v11 offset:10848
	s_waitcnt lgkmcnt(9)
	v_fma_f32 v63, v2, v240, 0
	v_fma_f32 v80, v3, v241, 0
	v_fma_f32 v81, v4, v242, 0
	v_fma_f32 v82, v5, v243, 0
	ds_read_b128 v[240:243], v11 offset:10864
	s_waitcnt lgkmcnt(9)
	v_fmac_f32_e32 v63, v6, v244
	v_fmac_f32_e32 v80, v7, v245
	v_fmac_f32_e32 v81, v8, v246
	v_fmac_f32_e32 v82, v9, v247
	ds_read_b128 v[244:247], v11 offset:10880
	s_waitcnt lgkmcnt(9)
	v_fmac_f32_e32 v63, v10, v248
	v_fmac_f32_e32 v80, v12, v249
	v_fmac_f32_e32 v81, v13, v250
	v_fmac_f32_e32 v82, v14, v251
	ds_read_b128 v[248:251], v11 offset:10896
	s_waitcnt lgkmcnt(6)
	v_fmac_f32_e32 v63, v17, v64
	v_fmac_f32_e32 v80, v19, v65
	v_fmac_f32_e32 v81, v28, v66
	v_fmac_f32_e32 v82, v35, v67
	ds_read_b128 v[64:67], v11 offset:10912
	s_waitcnt lgkmcnt(6)
	v_fmac_f32_e32 v63, v36, v68
	v_fmac_f32_e32 v80, v37, v69
	v_fmac_f32_e32 v81, v38, v70
	v_fmac_f32_e32 v82, v39, v71
	s_waitcnt lgkmcnt(5)
	v_fmac_f32_e32 v63, v40, v72
	v_fmac_f32_e32 v80, v41, v73
	v_fmac_f32_e32 v81, v42, v74
	v_fmac_f32_e32 v82, v43, v75
	s_waitcnt lgkmcnt(4)
	v_fmac_f32_e32 v63, v44, v76
	v_fmac_f32_e32 v80, v45, v77
	v_fmac_f32_e32 v81, v46, v78
	v_fmac_f32_e32 v82, v47, v79
	s_waitcnt lgkmcnt(3)
	v_fmac_f32_e32 v63, v48, v240
	v_fmac_f32_e32 v80, v49, v241
	v_fmac_f32_e32 v81, v50, v242
	v_fmac_f32_e32 v82, v51, v243
	s_waitcnt lgkmcnt(2)
	v_fmac_f32_e32 v63, v52, v244
	v_fmac_f32_e32 v80, v53, v245
	v_fmac_f32_e32 v81, v54, v246
	v_fmac_f32_e32 v82, v55, v247
	s_waitcnt lgkmcnt(1)
	v_fmac_f32_e32 v63, v56, v248
	v_fmac_f32_e32 v80, v57, v249
	v_fmac_f32_e32 v81, v58, v250
	v_fmac_f32_e32 v82, v59, v251
	s_waitcnt lgkmcnt(0)
	v_fmac_f32_e32 v63, v60, v64
	v_fmac_f32_e32 v80, v61, v65
	ds_read_b128 v[240:243], v11 offset:11008
	ds_read_b128 v[244:247], v11 offset:11024
	ds_read_b128 v[248:251], v11 offset:11040
	v_add_f32_e32 v63, v63, v80
	v_add_f32_e32 v64, v81, v82
	v_add_f32_e32 v63, v64, v63
	v_sub_f32_e32 v62, v62, v63
	v_lshlrev_b32_e32 v63, 16, v238
	v_mul_f32_e32 v63, v239, v63
	s_and_saveexec_b64 s[0:1], s[16:17]
	s_cbranch_execz .LBB0_891
	v_mul_f32_e32 v63, v63, v254
.LBB0_891:
	s_or_b64 exec, exec, s[0:1]
	ds_read_u16 v238, v18 offset:11968
	ds_read_b32 v239, v16 offset:176
	ds_read_b32 v254, v15 offset:176
	ds_read_b128 v[64:67], v11 offset:11056
	ds_read_b128 v[68:71], v11 offset:11072
	ds_read_b128 v[72:75], v11 offset:11088
	ds_read_b128 v[76:79], v11 offset:11104
	s_waitcnt lgkmcnt(9)
	v_fma_f32 v80, v2, v240, 0
	v_fma_f32 v81, v3, v241, 0
	v_fma_f32 v82, v4, v242, 0
	v_fma_f32 v83, v5, v243, 0
	ds_read_b128 v[240:243], v11 offset:11120
	s_waitcnt lgkmcnt(9)
	v_fmac_f32_e32 v80, v6, v244
	v_fmac_f32_e32 v81, v7, v245
	v_fmac_f32_e32 v82, v8, v246
	v_fmac_f32_e32 v83, v9, v247
	ds_read_b128 v[244:247], v11 offset:11136
	s_waitcnt lgkmcnt(9)
	v_fmac_f32_e32 v80, v10, v248
	v_fmac_f32_e32 v81, v12, v249
	v_fmac_f32_e32 v82, v13, v250
	v_fmac_f32_e32 v83, v14, v251
	ds_read_b128 v[248:251], v11 offset:11152
	s_waitcnt lgkmcnt(6)
	v_fmac_f32_e32 v80, v17, v64
	v_fmac_f32_e32 v81, v19, v65
	v_fmac_f32_e32 v82, v28, v66
	v_fmac_f32_e32 v83, v35, v67
	ds_read_b128 v[64:67], v11 offset:11168
	s_waitcnt lgkmcnt(6)
	v_fmac_f32_e32 v80, v36, v68
	v_fmac_f32_e32 v81, v37, v69
	v_fmac_f32_e32 v82, v38, v70
	v_fmac_f32_e32 v83, v39, v71
	s_waitcnt lgkmcnt(5)
	v_fmac_f32_e32 v80, v40, v72
	v_fmac_f32_e32 v81, v41, v73
	v_fmac_f32_e32 v82, v42, v74
	v_fmac_f32_e32 v83, v43, v75
	s_waitcnt lgkmcnt(4)
	v_fmac_f32_e32 v80, v44, v76
	v_fmac_f32_e32 v81, v45, v77
	v_fmac_f32_e32 v82, v46, v78
	v_fmac_f32_e32 v83, v47, v79
	s_waitcnt lgkmcnt(3)
	v_fmac_f32_e32 v80, v48, v240
	v_fmac_f32_e32 v81, v49, v241
	v_fmac_f32_e32 v82, v50, v242
	v_fmac_f32_e32 v83, v51, v243
	s_waitcnt lgkmcnt(2)
	v_fmac_f32_e32 v80, v52, v244
	v_fmac_f32_e32 v81, v53, v245
	v_fmac_f32_e32 v82, v54, v246
	v_fmac_f32_e32 v83, v55, v247
	s_waitcnt lgkmcnt(1)
	v_fmac_f32_e32 v80, v56, v248
	v_fmac_f32_e32 v81, v57, v249
	v_fmac_f32_e32 v82, v58, v250
	v_fmac_f32_e32 v83, v59, v251
	s_waitcnt lgkmcnt(0)
	v_fmac_f32_e32 v80, v60, v64
	v_fmac_f32_e32 v81, v61, v65
	v_fmac_f32_e32 v82, v62, v66
	ds_read_b128 v[240:243], v11 offset:11264
	ds_read_b128 v[244:247], v11 offset:11280
	ds_read_b128 v[248:251], v11 offset:11296
	v_add_f32_e32 v64, v80, v81
	v_add_f32_e32 v65, v83, v82
	v_add_f32_e32 v64, v64, v65
	v_sub_f32_e32 v63, v63, v64
	v_lshlrev_b32_e32 v64, 16, v238
	v_mul_f32_e32 v64, v239, v64
	s_and_saveexec_b64 s[0:1], s[16:17]
	s_cbranch_execz .LBB0_893
	v_mul_f32_e32 v64, v64, v254
.LBB0_893:
	s_or_b64 exec, exec, s[0:1]
	ds_read_u16 v238, v18 offset:12240
	ds_read_b32 v239, v16 offset:180
	ds_read_b32 v254, v15 offset:180
	ds_read_b128 v[66:69], v11 offset:11312
	ds_read_b128 v[70:73], v11 offset:11328
	ds_read_b128 v[74:77], v11 offset:11344
	ds_read_b128 v[78:81], v11 offset:11360
	s_waitcnt lgkmcnt(9)
	v_fma_f32 v65, v2, v240, 0
	v_fma_f32 v82, v3, v241, 0
	v_fma_f32 v83, v4, v242, 0
	v_fma_f32 v84, v5, v243, 0
	ds_read_b128 v[240:243], v11 offset:11376
	s_waitcnt lgkmcnt(9)
	v_fmac_f32_e32 v65, v6, v244
	v_fmac_f32_e32 v82, v7, v245
	v_fmac_f32_e32 v83, v8, v246
	v_fmac_f32_e32 v84, v9, v247
	ds_read_b128 v[244:247], v11 offset:11392
	s_waitcnt lgkmcnt(9)
	v_fmac_f32_e32 v65, v10, v248
	v_fmac_f32_e32 v82, v12, v249
	v_fmac_f32_e32 v83, v13, v250
	v_fmac_f32_e32 v84, v14, v251
	ds_read_b128 v[248:251], v11 offset:11408
	s_waitcnt lgkmcnt(6)
	v_fmac_f32_e32 v65, v17, v66
	v_fmac_f32_e32 v82, v19, v67
	v_fmac_f32_e32 v83, v28, v68
	v_fmac_f32_e32 v84, v35, v69
	ds_read_b128 v[66:69], v11 offset:11424
	s_waitcnt lgkmcnt(6)
	v_fmac_f32_e32 v65, v36, v70
	v_fmac_f32_e32 v82, v37, v71
	v_fmac_f32_e32 v83, v38, v72
	v_fmac_f32_e32 v84, v39, v73
	s_waitcnt lgkmcnt(5)
	v_fmac_f32_e32 v65, v40, v74
	v_fmac_f32_e32 v82, v41, v75
	v_fmac_f32_e32 v83, v42, v76
	v_fmac_f32_e32 v84, v43, v77
	s_waitcnt lgkmcnt(4)
	v_fmac_f32_e32 v65, v44, v78
	v_fmac_f32_e32 v82, v45, v79
	v_fmac_f32_e32 v83, v46, v80
	v_fmac_f32_e32 v84, v47, v81
	s_waitcnt lgkmcnt(3)
	v_fmac_f32_e32 v65, v48, v240
	v_fmac_f32_e32 v82, v49, v241
	v_fmac_f32_e32 v83, v50, v242
	v_fmac_f32_e32 v84, v51, v243
	s_waitcnt lgkmcnt(2)
	v_fmac_f32_e32 v65, v52, v244
	v_fmac_f32_e32 v82, v53, v245
	v_fmac_f32_e32 v83, v54, v246
	v_fmac_f32_e32 v84, v55, v247
	s_waitcnt lgkmcnt(1)
	v_fmac_f32_e32 v65, v56, v248
	v_fmac_f32_e32 v82, v57, v249
	v_fmac_f32_e32 v83, v58, v250
	v_fmac_f32_e32 v84, v59, v251
	s_waitcnt lgkmcnt(0)
	v_fmac_f32_e32 v65, v60, v66
	v_fmac_f32_e32 v82, v61, v67
	v_fmac_f32_e32 v83, v62, v68
	v_fmac_f32_e32 v84, v63, v69
	ds_read_b128 v[240:243], v11 offset:11520
	ds_read_b128 v[244:247], v11 offset:11536
	ds_read_b128 v[248:251], v11 offset:11552
	v_add_f32_e32 v65, v65, v82
	v_add_f32_e32 v66, v83, v84
	v_add_f32_e32 v65, v65, v66
	v_sub_f32_e32 v64, v64, v65
	v_lshlrev_b32_e32 v65, 16, v238
	v_mul_f32_e32 v65, v239, v65
	s_and_saveexec_b64 s[0:1], s[16:17]
	s_cbranch_execz .LBB0_895
	v_mul_f32_e32 v65, v65, v254
.LBB0_895:
	s_or_b64 exec, exec, s[0:1]
	ds_read_u16 v238, v18 offset:12512
	ds_read_b32 v239, v16 offset:184
	ds_read_b32 v254, v15 offset:184
	ds_read_b128 v[66:69], v11 offset:11568
	ds_read_b128 v[70:73], v11 offset:11584
	ds_read_b128 v[74:77], v11 offset:11600
	ds_read_b128 v[78:81], v11 offset:11616
	s_waitcnt lgkmcnt(9)
	v_fma_f32 v82, v2, v240, 0
	v_fma_f32 v83, v3, v241, 0
	v_fma_f32 v84, v4, v242, 0
	v_fma_f32 v85, v5, v243, 0
	ds_read_b128 v[240:243], v11 offset:11632
	s_waitcnt lgkmcnt(9)
	v_fmac_f32_e32 v82, v6, v244
	v_fmac_f32_e32 v83, v7, v245
	v_fmac_f32_e32 v84, v8, v246
	v_fmac_f32_e32 v85, v9, v247
	ds_read_b128 v[244:247], v11 offset:11648
	s_waitcnt lgkmcnt(9)
	v_fmac_f32_e32 v82, v10, v248
	v_fmac_f32_e32 v83, v12, v249
	v_fmac_f32_e32 v84, v13, v250
	v_fmac_f32_e32 v85, v14, v251
	ds_read_b128 v[248:251], v11 offset:11664
	s_waitcnt lgkmcnt(6)
	v_fmac_f32_e32 v82, v17, v66
	v_fmac_f32_e32 v83, v19, v67
	v_fmac_f32_e32 v84, v28, v68
	v_fmac_f32_e32 v85, v35, v69
	ds_read_b128 v[66:69], v11 offset:11680
	s_waitcnt lgkmcnt(6)
	v_fmac_f32_e32 v82, v36, v70
	v_fmac_f32_e32 v83, v37, v71
	v_fmac_f32_e32 v84, v38, v72
	v_fmac_f32_e32 v85, v39, v73
	ds_read_b128 v[70:73], v11 offset:11696
	s_waitcnt lgkmcnt(6)
	v_fmac_f32_e32 v82, v40, v74
	v_fmac_f32_e32 v83, v41, v75
	v_fmac_f32_e32 v84, v42, v76
	v_fmac_f32_e32 v85, v43, v77
	s_waitcnt lgkmcnt(5)
	v_fmac_f32_e32 v82, v44, v78
	v_fmac_f32_e32 v83, v45, v79
	v_fmac_f32_e32 v84, v46, v80
	v_fmac_f32_e32 v85, v47, v81
	s_waitcnt lgkmcnt(4)
	v_fmac_f32_e32 v82, v48, v240
	v_fmac_f32_e32 v83, v49, v241
	v_fmac_f32_e32 v84, v50, v242
	v_fmac_f32_e32 v85, v51, v243
	s_waitcnt lgkmcnt(3)
	v_fmac_f32_e32 v82, v52, v244
	v_fmac_f32_e32 v83, v53, v245
	v_fmac_f32_e32 v84, v54, v246
	v_fmac_f32_e32 v85, v55, v247
	s_waitcnt lgkmcnt(2)
	v_fmac_f32_e32 v82, v56, v248
	v_fmac_f32_e32 v83, v57, v249
	v_fmac_f32_e32 v84, v58, v250
	v_fmac_f32_e32 v85, v59, v251
	s_waitcnt lgkmcnt(1)
	v_fmac_f32_e32 v82, v60, v66
	v_fmac_f32_e32 v83, v61, v67
	v_fmac_f32_e32 v84, v62, v68
	v_fmac_f32_e32 v85, v63, v69
	s_waitcnt lgkmcnt(0)
	v_fmac_f32_e32 v82, v64, v70
	ds_read_b128 v[240:243], v11 offset:11776
	ds_read_b128 v[244:247], v11 offset:11792
	ds_read_b128 v[248:251], v11 offset:11808
	v_add_f32_e32 v66, v83, v82
	v_add_f32_e32 v67, v84, v85
	v_add_f32_e32 v66, v67, v66
	v_sub_f32_e32 v65, v65, v66
	v_lshlrev_b32_e32 v66, 16, v238
	v_mul_f32_e32 v66, v239, v66
	s_and_saveexec_b64 s[0:1], s[16:17]
	s_cbranch_execz .LBB0_897
	v_mul_f32_e32 v66, v66, v254
.LBB0_897:
	s_or_b64 exec, exec, s[0:1]
	ds_read_u16 v238, v18 offset:12784
	ds_read_b32 v239, v16 offset:188
	ds_read_b32 v254, v15 offset:188
	ds_read_b128 v[68:71], v11 offset:11824
	ds_read_b128 v[72:75], v11 offset:11840
	ds_read_b128 v[76:79], v11 offset:11856
	ds_read_b128 v[80:83], v11 offset:11872
	s_waitcnt lgkmcnt(9)
	v_fma_f32 v67, v2, v240, 0
	v_fma_f32 v84, v3, v241, 0
	v_fma_f32 v85, v4, v242, 0
	v_fma_f32 v86, v5, v243, 0
	ds_read_b128 v[240:243], v11 offset:11888
	s_waitcnt lgkmcnt(9)
	v_fmac_f32_e32 v67, v6, v244
	v_fmac_f32_e32 v84, v7, v245
	v_fmac_f32_e32 v85, v8, v246
	v_fmac_f32_e32 v86, v9, v247
	ds_read_b128 v[244:247], v11 offset:11904
	s_waitcnt lgkmcnt(9)
	v_fmac_f32_e32 v67, v10, v248
	v_fmac_f32_e32 v84, v12, v249
	v_fmac_f32_e32 v85, v13, v250
	v_fmac_f32_e32 v86, v14, v251
	ds_read_b128 v[248:251], v11 offset:11920
	s_waitcnt lgkmcnt(6)
	v_fmac_f32_e32 v67, v17, v68
	v_fmac_f32_e32 v84, v19, v69
	v_fmac_f32_e32 v85, v28, v70
	v_fmac_f32_e32 v86, v35, v71
	ds_read_b128 v[68:71], v11 offset:11936
	s_waitcnt lgkmcnt(6)
	v_fmac_f32_e32 v67, v36, v72
	v_fmac_f32_e32 v84, v37, v73
	v_fmac_f32_e32 v85, v38, v74
	v_fmac_f32_e32 v86, v39, v75
	ds_read_b128 v[72:75], v11 offset:11952
	s_waitcnt lgkmcnt(6)
	v_fmac_f32_e32 v67, v40, v76
	v_fmac_f32_e32 v84, v41, v77
	v_fmac_f32_e32 v85, v42, v78
	v_fmac_f32_e32 v86, v43, v79
	s_waitcnt lgkmcnt(5)
	v_fmac_f32_e32 v67, v44, v80
	v_fmac_f32_e32 v84, v45, v81
	v_fmac_f32_e32 v85, v46, v82
	v_fmac_f32_e32 v86, v47, v83
	s_waitcnt lgkmcnt(4)
	v_fmac_f32_e32 v67, v48, v240
	v_fmac_f32_e32 v84, v49, v241
	v_fmac_f32_e32 v85, v50, v242
	v_fmac_f32_e32 v86, v51, v243
	s_waitcnt lgkmcnt(3)
	v_fmac_f32_e32 v67, v52, v244
	v_fmac_f32_e32 v84, v53, v245
	v_fmac_f32_e32 v85, v54, v246
	v_fmac_f32_e32 v86, v55, v247
	s_waitcnt lgkmcnt(2)
	v_fmac_f32_e32 v67, v56, v248
	v_fmac_f32_e32 v84, v57, v249
	v_fmac_f32_e32 v85, v58, v250
	v_fmac_f32_e32 v86, v59, v251
	s_waitcnt lgkmcnt(1)
	v_fmac_f32_e32 v67, v60, v68
	v_fmac_f32_e32 v84, v61, v69
	v_fmac_f32_e32 v85, v62, v70
	v_fmac_f32_e32 v86, v63, v71
	s_waitcnt lgkmcnt(0)
	v_fmac_f32_e32 v67, v64, v72
	v_fmac_f32_e32 v84, v65, v73
	ds_read_b128 v[240:243], v11 offset:12032
	ds_read_b128 v[244:247], v11 offset:12048
	ds_read_b128 v[248:251], v11 offset:12064
	v_add_f32_e32 v67, v67, v84
	v_add_f32_e32 v68, v85, v86
	v_add_f32_e32 v67, v68, v67
	v_sub_f32_e32 v66, v66, v67
	v_lshlrev_b32_e32 v67, 16, v238
	v_mul_f32_e32 v67, v239, v67
	s_and_saveexec_b64 s[0:1], s[16:17]
	s_cbranch_execz .LBB0_899
	v_mul_f32_e32 v67, v67, v254
.LBB0_899:
	s_or_b64 exec, exec, s[0:1]
	ds_read_u16 v238, v18 offset:13056
	ds_read_b32 v239, v16 offset:192
	ds_read_b32 v254, v15 offset:192
	ds_read_b128 v[68:71], v11 offset:12080
	ds_read_b128 v[72:75], v11 offset:12096
	ds_read_b128 v[76:79], v11 offset:12112
	ds_read_b128 v[80:83], v11 offset:12128
	s_waitcnt lgkmcnt(9)
	v_fma_f32 v84, v2, v240, 0
	v_fma_f32 v85, v3, v241, 0
	v_fma_f32 v86, v4, v242, 0
	v_fma_f32 v87, v5, v243, 0
	ds_read_b128 v[240:243], v11 offset:12144
	s_waitcnt lgkmcnt(9)
	v_fmac_f32_e32 v84, v6, v244
	v_fmac_f32_e32 v85, v7, v245
	v_fmac_f32_e32 v86, v8, v246
	v_fmac_f32_e32 v87, v9, v247
	ds_read_b128 v[244:247], v11 offset:12160
	s_waitcnt lgkmcnt(9)
	v_fmac_f32_e32 v84, v10, v248
	v_fmac_f32_e32 v85, v12, v249
	v_fmac_f32_e32 v86, v13, v250
	v_fmac_f32_e32 v87, v14, v251
	ds_read_b128 v[248:251], v11 offset:12176
	s_waitcnt lgkmcnt(6)
	v_fmac_f32_e32 v84, v17, v68
	v_fmac_f32_e32 v85, v19, v69
	v_fmac_f32_e32 v86, v28, v70
	v_fmac_f32_e32 v87, v35, v71
	ds_read_b128 v[68:71], v11 offset:12192
	s_waitcnt lgkmcnt(6)
	v_fmac_f32_e32 v84, v36, v72
	v_fmac_f32_e32 v85, v37, v73
	v_fmac_f32_e32 v86, v38, v74
	v_fmac_f32_e32 v87, v39, v75
	ds_read_b128 v[72:75], v11 offset:12208
	s_waitcnt lgkmcnt(6)
	v_fmac_f32_e32 v84, v40, v76
	v_fmac_f32_e32 v85, v41, v77
	v_fmac_f32_e32 v86, v42, v78
	v_fmac_f32_e32 v87, v43, v79
	s_waitcnt lgkmcnt(5)
	v_fmac_f32_e32 v84, v44, v80
	v_fmac_f32_e32 v85, v45, v81
	v_fmac_f32_e32 v86, v46, v82
	v_fmac_f32_e32 v87, v47, v83
	s_waitcnt lgkmcnt(4)
	v_fmac_f32_e32 v84, v48, v240
	v_fmac_f32_e32 v85, v49, v241
	v_fmac_f32_e32 v86, v50, v242
	v_fmac_f32_e32 v87, v51, v243
	s_waitcnt lgkmcnt(3)
	v_fmac_f32_e32 v84, v52, v244
	v_fmac_f32_e32 v85, v53, v245
	v_fmac_f32_e32 v86, v54, v246
	v_fmac_f32_e32 v87, v55, v247
	s_waitcnt lgkmcnt(2)
	v_fmac_f32_e32 v84, v56, v248
	v_fmac_f32_e32 v85, v57, v249
	v_fmac_f32_e32 v86, v58, v250
	v_fmac_f32_e32 v87, v59, v251
	s_waitcnt lgkmcnt(1)
	v_fmac_f32_e32 v84, v60, v68
	v_fmac_f32_e32 v85, v61, v69
	v_fmac_f32_e32 v86, v62, v70
	v_fmac_f32_e32 v87, v63, v71
	s_waitcnt lgkmcnt(0)
	v_fmac_f32_e32 v84, v64, v72
	v_fmac_f32_e32 v85, v65, v73
	v_fmac_f32_e32 v86, v66, v74
	ds_read_b128 v[240:243], v11 offset:12288
	ds_read_b128 v[244:247], v11 offset:12304
	ds_read_b128 v[248:251], v11 offset:12320
	v_add_f32_e32 v68, v84, v85
	v_add_f32_e32 v69, v87, v86
	v_add_f32_e32 v68, v68, v69
	v_sub_f32_e32 v67, v67, v68
	v_lshlrev_b32_e32 v68, 16, v238
	v_mul_f32_e32 v68, v239, v68
	s_and_saveexec_b64 s[0:1], s[16:17]
	s_cbranch_execz .LBB0_901
	v_mul_f32_e32 v68, v68, v254
.LBB0_901:
	s_or_b64 exec, exec, s[0:1]
	ds_read_u16 v238, v18 offset:13328
	ds_read_b32 v239, v16 offset:196
	ds_read_b32 v254, v15 offset:196
	ds_read_b128 v[70:73], v11 offset:12336
	ds_read_b128 v[74:77], v11 offset:12352
	ds_read_b128 v[78:81], v11 offset:12368
	ds_read_b128 v[82:85], v11 offset:12384
	s_waitcnt lgkmcnt(9)
	v_fma_f32 v69, v2, v240, 0
	v_fma_f32 v86, v3, v241, 0
	v_fma_f32 v87, v4, v242, 0
	v_fma_f32 v88, v5, v243, 0
	ds_read_b128 v[240:243], v11 offset:12400
	s_waitcnt lgkmcnt(9)
	v_fmac_f32_e32 v69, v6, v244
	v_fmac_f32_e32 v86, v7, v245
	v_fmac_f32_e32 v87, v8, v246
	v_fmac_f32_e32 v88, v9, v247
	ds_read_b128 v[244:247], v11 offset:12416
	s_waitcnt lgkmcnt(9)
	v_fmac_f32_e32 v69, v10, v248
	v_fmac_f32_e32 v86, v12, v249
	v_fmac_f32_e32 v87, v13, v250
	v_fmac_f32_e32 v88, v14, v251
	ds_read_b128 v[248:251], v11 offset:12432
	s_waitcnt lgkmcnt(6)
	v_fmac_f32_e32 v69, v17, v70
	v_fmac_f32_e32 v86, v19, v71
	v_fmac_f32_e32 v87, v28, v72
	v_fmac_f32_e32 v88, v35, v73
	ds_read_b128 v[70:73], v11 offset:12448
	s_waitcnt lgkmcnt(6)
	v_fmac_f32_e32 v69, v36, v74
	v_fmac_f32_e32 v86, v37, v75
	v_fmac_f32_e32 v87, v38, v76
	v_fmac_f32_e32 v88, v39, v77
	ds_read_b128 v[74:77], v11 offset:12464
	s_waitcnt lgkmcnt(6)
	v_fmac_f32_e32 v69, v40, v78
	v_fmac_f32_e32 v86, v41, v79
	v_fmac_f32_e32 v87, v42, v80
	v_fmac_f32_e32 v88, v43, v81
	s_waitcnt lgkmcnt(5)
	v_fmac_f32_e32 v69, v44, v82
	v_fmac_f32_e32 v86, v45, v83
	v_fmac_f32_e32 v87, v46, v84
	v_fmac_f32_e32 v88, v47, v85
	s_waitcnt lgkmcnt(4)
	v_fmac_f32_e32 v69, v48, v240
	v_fmac_f32_e32 v86, v49, v241
	v_fmac_f32_e32 v87, v50, v242
	v_fmac_f32_e32 v88, v51, v243
	s_waitcnt lgkmcnt(3)
	v_fmac_f32_e32 v69, v52, v244
	v_fmac_f32_e32 v86, v53, v245
	v_fmac_f32_e32 v87, v54, v246
	v_fmac_f32_e32 v88, v55, v247
	s_waitcnt lgkmcnt(2)
	v_fmac_f32_e32 v69, v56, v248
	v_fmac_f32_e32 v86, v57, v249
	v_fmac_f32_e32 v87, v58, v250
	v_fmac_f32_e32 v88, v59, v251
	s_waitcnt lgkmcnt(1)
	v_fmac_f32_e32 v69, v60, v70
	v_fmac_f32_e32 v86, v61, v71
	v_fmac_f32_e32 v87, v62, v72
	v_fmac_f32_e32 v88, v63, v73
	s_waitcnt lgkmcnt(0)
	v_fmac_f32_e32 v69, v64, v74
	v_fmac_f32_e32 v86, v65, v75
	v_fmac_f32_e32 v87, v66, v76
	v_fmac_f32_e32 v88, v67, v77
	ds_read_b128 v[240:243], v11 offset:12544
	ds_read_b128 v[244:247], v11 offset:12560
	ds_read_b128 v[248:251], v11 offset:12576
	v_add_f32_e32 v69, v69, v86
	v_add_f32_e32 v70, v87, v88
	v_add_f32_e32 v69, v69, v70
	v_sub_f32_e32 v68, v68, v69
	v_lshlrev_b32_e32 v69, 16, v238
	v_mul_f32_e32 v69, v239, v69
	s_and_saveexec_b64 s[0:1], s[16:17]
	s_cbranch_execz .LBB0_903
	v_mul_f32_e32 v69, v69, v254
.LBB0_903:
	s_or_b64 exec, exec, s[0:1]
	ds_read_u16 v238, v18 offset:13600
	ds_read_b32 v239, v16 offset:200
	ds_read_b32 v254, v15 offset:200
	ds_read_b128 v[70:73], v11 offset:12592
	ds_read_b128 v[74:77], v11 offset:12608
	ds_read_b128 v[78:81], v11 offset:12624
	ds_read_b128 v[82:85], v11 offset:12640
	s_waitcnt lgkmcnt(9)
	v_fma_f32 v86, v2, v240, 0
	v_fma_f32 v87, v3, v241, 0
	v_fma_f32 v88, v4, v242, 0
	v_fma_f32 v89, v5, v243, 0
	ds_read_b128 v[240:243], v11 offset:12656
	s_waitcnt lgkmcnt(9)
	v_fmac_f32_e32 v86, v6, v244
	v_fmac_f32_e32 v87, v7, v245
	v_fmac_f32_e32 v88, v8, v246
	v_fmac_f32_e32 v89, v9, v247
	ds_read_b128 v[244:247], v11 offset:12672
	s_waitcnt lgkmcnt(9)
	v_fmac_f32_e32 v86, v10, v248
	v_fmac_f32_e32 v87, v12, v249
	v_fmac_f32_e32 v88, v13, v250
	v_fmac_f32_e32 v89, v14, v251
	ds_read_b128 v[248:251], v11 offset:12688
	s_waitcnt lgkmcnt(6)
	v_fmac_f32_e32 v86, v17, v70
	v_fmac_f32_e32 v87, v19, v71
	v_fmac_f32_e32 v88, v28, v72
	v_fmac_f32_e32 v89, v35, v73
	ds_read_b128 v[70:73], v11 offset:12704
	s_waitcnt lgkmcnt(6)
	v_fmac_f32_e32 v86, v36, v74
	v_fmac_f32_e32 v87, v37, v75
	v_fmac_f32_e32 v88, v38, v76
	v_fmac_f32_e32 v89, v39, v77
	ds_read_b128 v[74:77], v11 offset:12720
	s_waitcnt lgkmcnt(6)
	v_fmac_f32_e32 v86, v40, v78
	v_fmac_f32_e32 v87, v41, v79
	v_fmac_f32_e32 v88, v42, v80
	v_fmac_f32_e32 v89, v43, v81
	ds_read_b128 v[78:81], v11 offset:12736
	s_waitcnt lgkmcnt(6)
	v_fmac_f32_e32 v86, v44, v82
	v_fmac_f32_e32 v87, v45, v83
	v_fmac_f32_e32 v88, v46, v84
	v_fmac_f32_e32 v89, v47, v85
	s_waitcnt lgkmcnt(5)
	v_fmac_f32_e32 v86, v48, v240
	v_fmac_f32_e32 v87, v49, v241
	v_fmac_f32_e32 v88, v50, v242
	v_fmac_f32_e32 v89, v51, v243
	s_waitcnt lgkmcnt(4)
	v_fmac_f32_e32 v86, v52, v244
	v_fmac_f32_e32 v87, v53, v245
	v_fmac_f32_e32 v88, v54, v246
	v_fmac_f32_e32 v89, v55, v247
	s_waitcnt lgkmcnt(3)
	v_fmac_f32_e32 v86, v56, v248
	v_fmac_f32_e32 v87, v57, v249
	v_fmac_f32_e32 v88, v58, v250
	v_fmac_f32_e32 v89, v59, v251
	s_waitcnt lgkmcnt(2)
	v_fmac_f32_e32 v86, v60, v70
	v_fmac_f32_e32 v87, v61, v71
	v_fmac_f32_e32 v88, v62, v72
	v_fmac_f32_e32 v89, v63, v73
	s_waitcnt lgkmcnt(1)
	v_fmac_f32_e32 v86, v64, v74
	v_fmac_f32_e32 v87, v65, v75
	v_fmac_f32_e32 v88, v66, v76
	v_fmac_f32_e32 v89, v67, v77
	s_waitcnt lgkmcnt(0)
	v_fmac_f32_e32 v86, v68, v78
	ds_read_b128 v[240:243], v11 offset:12800
	ds_read_b128 v[244:247], v11 offset:12816
	ds_read_b128 v[248:251], v11 offset:12832
	v_add_f32_e32 v70, v87, v86
	v_add_f32_e32 v71, v88, v89
	v_add_f32_e32 v70, v71, v70
	v_sub_f32_e32 v69, v69, v70
	v_lshlrev_b32_e32 v70, 16, v238
	v_mul_f32_e32 v70, v239, v70
	s_and_saveexec_b64 s[0:1], s[16:17]
	s_cbranch_execz .LBB0_905
	v_mul_f32_e32 v70, v70, v254
.LBB0_905:
	s_or_b64 exec, exec, s[0:1]
	ds_read_u16 v238, v18 offset:13872
	ds_read_b32 v239, v16 offset:204
	ds_read_b32 v254, v15 offset:204
	ds_read_b128 v[72:75], v11 offset:12848
	ds_read_b128 v[76:79], v11 offset:12864
	ds_read_b128 v[80:83], v11 offset:12880
	ds_read_b128 v[84:87], v11 offset:12896
	s_waitcnt lgkmcnt(9)
	v_fma_f32 v71, v2, v240, 0
	v_fma_f32 v88, v3, v241, 0
	v_fma_f32 v89, v4, v242, 0
	v_fma_f32 v90, v5, v243, 0
	ds_read_b128 v[240:243], v11 offset:12912
	s_waitcnt lgkmcnt(9)
	v_fmac_f32_e32 v71, v6, v244
	v_fmac_f32_e32 v88, v7, v245
	v_fmac_f32_e32 v89, v8, v246
	v_fmac_f32_e32 v90, v9, v247
	ds_read_b128 v[244:247], v11 offset:12928
	s_waitcnt lgkmcnt(9)
	v_fmac_f32_e32 v71, v10, v248
	v_fmac_f32_e32 v88, v12, v249
	v_fmac_f32_e32 v89, v13, v250
	v_fmac_f32_e32 v90, v14, v251
	ds_read_b128 v[248:251], v11 offset:12944
	s_waitcnt lgkmcnt(6)
	v_fmac_f32_e32 v71, v17, v72
	v_fmac_f32_e32 v88, v19, v73
	v_fmac_f32_e32 v89, v28, v74
	v_fmac_f32_e32 v90, v35, v75
	ds_read_b128 v[72:75], v11 offset:12960
	s_waitcnt lgkmcnt(6)
	v_fmac_f32_e32 v71, v36, v76
	v_fmac_f32_e32 v88, v37, v77
	v_fmac_f32_e32 v89, v38, v78
	v_fmac_f32_e32 v90, v39, v79
	ds_read_b128 v[76:79], v11 offset:12976
	s_waitcnt lgkmcnt(6)
	v_fmac_f32_e32 v71, v40, v80
	v_fmac_f32_e32 v88, v41, v81
	v_fmac_f32_e32 v89, v42, v82
	v_fmac_f32_e32 v90, v43, v83
	ds_read_b128 v[80:83], v11 offset:12992
	s_waitcnt lgkmcnt(6)
	v_fmac_f32_e32 v71, v44, v84
	v_fmac_f32_e32 v88, v45, v85
	v_fmac_f32_e32 v89, v46, v86
	v_fmac_f32_e32 v90, v47, v87
	s_waitcnt lgkmcnt(5)
	v_fmac_f32_e32 v71, v48, v240
	v_fmac_f32_e32 v88, v49, v241
	v_fmac_f32_e32 v89, v50, v242
	v_fmac_f32_e32 v90, v51, v243
	s_waitcnt lgkmcnt(4)
	v_fmac_f32_e32 v71, v52, v244
	v_fmac_f32_e32 v88, v53, v245
	v_fmac_f32_e32 v89, v54, v246
	v_fmac_f32_e32 v90, v55, v247
	s_waitcnt lgkmcnt(3)
	v_fmac_f32_e32 v71, v56, v248
	v_fmac_f32_e32 v88, v57, v249
	v_fmac_f32_e32 v89, v58, v250
	v_fmac_f32_e32 v90, v59, v251
	s_waitcnt lgkmcnt(2)
	v_fmac_f32_e32 v71, v60, v72
	v_fmac_f32_e32 v88, v61, v73
	v_fmac_f32_e32 v89, v62, v74
	v_fmac_f32_e32 v90, v63, v75
	s_waitcnt lgkmcnt(1)
	v_fmac_f32_e32 v71, v64, v76
	v_fmac_f32_e32 v88, v65, v77
	v_fmac_f32_e32 v89, v66, v78
	v_fmac_f32_e32 v90, v67, v79
	s_waitcnt lgkmcnt(0)
	v_fmac_f32_e32 v71, v68, v80
	v_fmac_f32_e32 v88, v69, v81
	ds_read_b128 v[240:243], v11 offset:13056
	ds_read_b128 v[244:247], v11 offset:13072
	ds_read_b128 v[248:251], v11 offset:13088
	v_add_f32_e32 v71, v71, v88
	v_add_f32_e32 v72, v89, v90
	v_add_f32_e32 v71, v72, v71
	v_sub_f32_e32 v70, v70, v71
	v_lshlrev_b32_e32 v71, 16, v238
	v_mul_f32_e32 v71, v239, v71
	s_and_saveexec_b64 s[0:1], s[16:17]
	s_cbranch_execz .LBB0_907
	v_mul_f32_e32 v71, v71, v254
.LBB0_907:
	s_or_b64 exec, exec, s[0:1]
	ds_read_u16 v238, v18 offset:14144
	ds_read_b32 v239, v16 offset:208
	ds_read_b32 v254, v15 offset:208
	ds_read_b128 v[72:75], v11 offset:13104
	ds_read_b128 v[76:79], v11 offset:13120
	ds_read_b128 v[80:83], v11 offset:13136
	ds_read_b128 v[84:87], v11 offset:13152
	s_waitcnt lgkmcnt(9)
	v_fma_f32 v88, v2, v240, 0
	v_fma_f32 v89, v3, v241, 0
	v_fma_f32 v90, v4, v242, 0
	v_fma_f32 v91, v5, v243, 0
	ds_read_b128 v[240:243], v11 offset:13168
	s_waitcnt lgkmcnt(9)
	v_fmac_f32_e32 v88, v6, v244
	v_fmac_f32_e32 v89, v7, v245
	v_fmac_f32_e32 v90, v8, v246
	v_fmac_f32_e32 v91, v9, v247
	ds_read_b128 v[244:247], v11 offset:13184
	s_waitcnt lgkmcnt(9)
	v_fmac_f32_e32 v88, v10, v248
	v_fmac_f32_e32 v89, v12, v249
	v_fmac_f32_e32 v90, v13, v250
	v_fmac_f32_e32 v91, v14, v251
	ds_read_b128 v[248:251], v11 offset:13200
	s_waitcnt lgkmcnt(6)
	v_fmac_f32_e32 v88, v17, v72
	v_fmac_f32_e32 v89, v19, v73
	v_fmac_f32_e32 v90, v28, v74
	v_fmac_f32_e32 v91, v35, v75
	ds_read_b128 v[72:75], v11 offset:13216
	s_waitcnt lgkmcnt(6)
	v_fmac_f32_e32 v88, v36, v76
	v_fmac_f32_e32 v89, v37, v77
	v_fmac_f32_e32 v90, v38, v78
	v_fmac_f32_e32 v91, v39, v79
	ds_read_b128 v[76:79], v11 offset:13232
	s_waitcnt lgkmcnt(6)
	v_fmac_f32_e32 v88, v40, v80
	v_fmac_f32_e32 v89, v41, v81
	v_fmac_f32_e32 v90, v42, v82
	v_fmac_f32_e32 v91, v43, v83
	ds_read_b128 v[80:83], v11 offset:13248
	s_waitcnt lgkmcnt(6)
	v_fmac_f32_e32 v88, v44, v84
	v_fmac_f32_e32 v89, v45, v85
	v_fmac_f32_e32 v90, v46, v86
	v_fmac_f32_e32 v91, v47, v87
	s_waitcnt lgkmcnt(5)
	v_fmac_f32_e32 v88, v48, v240
	v_fmac_f32_e32 v89, v49, v241
	v_fmac_f32_e32 v90, v50, v242
	v_fmac_f32_e32 v91, v51, v243
	s_waitcnt lgkmcnt(4)
	v_fmac_f32_e32 v88, v52, v244
	v_fmac_f32_e32 v89, v53, v245
	v_fmac_f32_e32 v90, v54, v246
	v_fmac_f32_e32 v91, v55, v247
	s_waitcnt lgkmcnt(3)
	v_fmac_f32_e32 v88, v56, v248
	v_fmac_f32_e32 v89, v57, v249
	v_fmac_f32_e32 v90, v58, v250
	v_fmac_f32_e32 v91, v59, v251
	s_waitcnt lgkmcnt(2)
	v_fmac_f32_e32 v88, v60, v72
	v_fmac_f32_e32 v89, v61, v73
	v_fmac_f32_e32 v90, v62, v74
	v_fmac_f32_e32 v91, v63, v75
	s_waitcnt lgkmcnt(1)
	v_fmac_f32_e32 v88, v64, v76
	v_fmac_f32_e32 v89, v65, v77
	v_fmac_f32_e32 v90, v66, v78
	v_fmac_f32_e32 v91, v67, v79
	s_waitcnt lgkmcnt(0)
	v_fmac_f32_e32 v88, v68, v80
	v_fmac_f32_e32 v89, v69, v81
	v_fmac_f32_e32 v90, v70, v82
	ds_read_b128 v[240:243], v11 offset:13312
	ds_read_b128 v[244:247], v11 offset:13328
	ds_read_b128 v[248:251], v11 offset:13344
	v_add_f32_e32 v72, v88, v89
	v_add_f32_e32 v73, v91, v90
	v_add_f32_e32 v72, v72, v73
	v_sub_f32_e32 v71, v71, v72
	v_lshlrev_b32_e32 v72, 16, v238
	v_mul_f32_e32 v72, v239, v72
	s_and_saveexec_b64 s[0:1], s[16:17]
	s_cbranch_execz .LBB0_909
	v_mul_f32_e32 v72, v72, v254
.LBB0_909:
	s_or_b64 exec, exec, s[0:1]
	ds_read_u16 v238, v18 offset:14416
	ds_read_b32 v239, v16 offset:212
	ds_read_b32 v254, v15 offset:212
	ds_read_b128 v[74:77], v11 offset:13360
	ds_read_b128 v[78:81], v11 offset:13376
	ds_read_b128 v[82:85], v11 offset:13392
	ds_read_b128 v[86:89], v11 offset:13408
	s_waitcnt lgkmcnt(9)
	v_fma_f32 v73, v2, v240, 0
	v_fma_f32 v90, v3, v241, 0
	v_fma_f32 v91, v4, v242, 0
	v_fma_f32 v92, v5, v243, 0
	ds_read_b128 v[240:243], v11 offset:13424
	s_waitcnt lgkmcnt(9)
	v_fmac_f32_e32 v73, v6, v244
	v_fmac_f32_e32 v90, v7, v245
	v_fmac_f32_e32 v91, v8, v246
	v_fmac_f32_e32 v92, v9, v247
	ds_read_b128 v[244:247], v11 offset:13440
	s_waitcnt lgkmcnt(9)
	v_fmac_f32_e32 v73, v10, v248
	v_fmac_f32_e32 v90, v12, v249
	v_fmac_f32_e32 v91, v13, v250
	v_fmac_f32_e32 v92, v14, v251
	ds_read_b128 v[248:251], v11 offset:13456
	s_waitcnt lgkmcnt(6)
	v_fmac_f32_e32 v73, v17, v74
	v_fmac_f32_e32 v90, v19, v75
	v_fmac_f32_e32 v91, v28, v76
	v_fmac_f32_e32 v92, v35, v77
	ds_read_b128 v[74:77], v11 offset:13472
	s_waitcnt lgkmcnt(6)
	v_fmac_f32_e32 v73, v36, v78
	v_fmac_f32_e32 v90, v37, v79
	v_fmac_f32_e32 v91, v38, v80
	v_fmac_f32_e32 v92, v39, v81
	ds_read_b128 v[78:81], v11 offset:13488
	s_waitcnt lgkmcnt(6)
	v_fmac_f32_e32 v73, v40, v82
	v_fmac_f32_e32 v90, v41, v83
	v_fmac_f32_e32 v91, v42, v84
	v_fmac_f32_e32 v92, v43, v85
	ds_read_b128 v[82:85], v11 offset:13504
	s_waitcnt lgkmcnt(6)
	v_fmac_f32_e32 v73, v44, v86
	v_fmac_f32_e32 v90, v45, v87
	v_fmac_f32_e32 v91, v46, v88
	v_fmac_f32_e32 v92, v47, v89
	s_waitcnt lgkmcnt(5)
	v_fmac_f32_e32 v73, v48, v240
	v_fmac_f32_e32 v90, v49, v241
	v_fmac_f32_e32 v91, v50, v242
	v_fmac_f32_e32 v92, v51, v243
	s_waitcnt lgkmcnt(4)
	v_fmac_f32_e32 v73, v52, v244
	v_fmac_f32_e32 v90, v53, v245
	v_fmac_f32_e32 v91, v54, v246
	v_fmac_f32_e32 v92, v55, v247
	s_waitcnt lgkmcnt(3)
	v_fmac_f32_e32 v73, v56, v248
	v_fmac_f32_e32 v90, v57, v249
	v_fmac_f32_e32 v91, v58, v250
	v_fmac_f32_e32 v92, v59, v251
	s_waitcnt lgkmcnt(2)
	v_fmac_f32_e32 v73, v60, v74
	v_fmac_f32_e32 v90, v61, v75
	v_fmac_f32_e32 v91, v62, v76
	v_fmac_f32_e32 v92, v63, v77
	s_waitcnt lgkmcnt(1)
	v_fmac_f32_e32 v73, v64, v78
	v_fmac_f32_e32 v90, v65, v79
	v_fmac_f32_e32 v91, v66, v80
	v_fmac_f32_e32 v92, v67, v81
	s_waitcnt lgkmcnt(0)
	v_fmac_f32_e32 v73, v68, v82
	v_fmac_f32_e32 v90, v69, v83
	v_fmac_f32_e32 v91, v70, v84
	v_fmac_f32_e32 v92, v71, v85
	ds_read_b128 v[240:243], v11 offset:13568
	ds_read_b128 v[244:247], v11 offset:13584
	ds_read_b128 v[248:251], v11 offset:13600
	v_add_f32_e32 v73, v73, v90
	v_add_f32_e32 v74, v91, v92
	v_add_f32_e32 v73, v73, v74
	v_sub_f32_e32 v72, v72, v73
	v_lshlrev_b32_e32 v73, 16, v238
	v_mul_f32_e32 v73, v239, v73
	s_and_saveexec_b64 s[0:1], s[16:17]
	s_cbranch_execz .LBB0_911
	v_mul_f32_e32 v73, v73, v254
.LBB0_911:
	s_or_b64 exec, exec, s[0:1]
	ds_read_u16 v238, v18 offset:14688
	ds_read_b32 v239, v16 offset:216
	ds_read_b32 v254, v15 offset:216
	ds_read_b128 v[74:77], v11 offset:13616
	ds_read_b128 v[78:81], v11 offset:13632
	ds_read_b128 v[82:85], v11 offset:13648
	ds_read_b128 v[86:89], v11 offset:13664
	s_waitcnt lgkmcnt(9)
	v_fma_f32 v90, v2, v240, 0
	v_fma_f32 v91, v3, v241, 0
	v_fma_f32 v92, v4, v242, 0
	v_fma_f32 v93, v5, v243, 0
	ds_read_b128 v[240:243], v11 offset:13680
	s_waitcnt lgkmcnt(9)
	v_fmac_f32_e32 v90, v6, v244
	v_fmac_f32_e32 v91, v7, v245
	v_fmac_f32_e32 v92, v8, v246
	v_fmac_f32_e32 v93, v9, v247
	ds_read_b128 v[244:247], v11 offset:13696
	s_waitcnt lgkmcnt(9)
	v_fmac_f32_e32 v90, v10, v248
	v_fmac_f32_e32 v91, v12, v249
	v_fmac_f32_e32 v92, v13, v250
	v_fmac_f32_e32 v93, v14, v251
	ds_read_b128 v[248:251], v11 offset:13712
	s_waitcnt lgkmcnt(6)
	v_fmac_f32_e32 v90, v17, v74
	v_fmac_f32_e32 v91, v19, v75
	v_fmac_f32_e32 v92, v28, v76
	v_fmac_f32_e32 v93, v35, v77
	ds_read_b128 v[74:77], v11 offset:13728
	s_waitcnt lgkmcnt(6)
	v_fmac_f32_e32 v90, v36, v78
	v_fmac_f32_e32 v91, v37, v79
	v_fmac_f32_e32 v92, v38, v80
	v_fmac_f32_e32 v93, v39, v81
	ds_read_b128 v[78:81], v11 offset:13744
	s_waitcnt lgkmcnt(6)
	v_fmac_f32_e32 v90, v40, v82
	v_fmac_f32_e32 v91, v41, v83
	v_fmac_f32_e32 v92, v42, v84
	v_fmac_f32_e32 v93, v43, v85
	ds_read_b128 v[82:85], v11 offset:13760
	s_waitcnt lgkmcnt(6)
	v_fmac_f32_e32 v90, v44, v86
	v_fmac_f32_e32 v91, v45, v87
	v_fmac_f32_e32 v92, v46, v88
	v_fmac_f32_e32 v93, v47, v89
	ds_read_b128 v[86:89], v11 offset:13776
	s_waitcnt lgkmcnt(6)
	v_fmac_f32_e32 v90, v48, v240
	v_fmac_f32_e32 v91, v49, v241
	v_fmac_f32_e32 v92, v50, v242
	v_fmac_f32_e32 v93, v51, v243
	s_waitcnt lgkmcnt(5)
	v_fmac_f32_e32 v90, v52, v244
	v_fmac_f32_e32 v91, v53, v245
	v_fmac_f32_e32 v92, v54, v246
	v_fmac_f32_e32 v93, v55, v247
	s_waitcnt lgkmcnt(4)
	v_fmac_f32_e32 v90, v56, v248
	v_fmac_f32_e32 v91, v57, v249
	v_fmac_f32_e32 v92, v58, v250
	v_fmac_f32_e32 v93, v59, v251
	s_waitcnt lgkmcnt(3)
	v_fmac_f32_e32 v90, v60, v74
	v_fmac_f32_e32 v91, v61, v75
	v_fmac_f32_e32 v92, v62, v76
	v_fmac_f32_e32 v93, v63, v77
	s_waitcnt lgkmcnt(2)
	v_fmac_f32_e32 v90, v64, v78
	v_fmac_f32_e32 v91, v65, v79
	v_fmac_f32_e32 v92, v66, v80
	v_fmac_f32_e32 v93, v67, v81
	s_waitcnt lgkmcnt(1)
	v_fmac_f32_e32 v90, v68, v82
	v_fmac_f32_e32 v91, v69, v83
	v_fmac_f32_e32 v92, v70, v84
	v_fmac_f32_e32 v93, v71, v85
	s_waitcnt lgkmcnt(0)
	v_fmac_f32_e32 v90, v72, v86
	ds_read_b128 v[240:243], v11 offset:13824
	ds_read_b128 v[244:247], v11 offset:13840
	ds_read_b128 v[248:251], v11 offset:13856
	v_add_f32_e32 v74, v91, v90
	v_add_f32_e32 v75, v92, v93
	v_add_f32_e32 v74, v75, v74
	v_sub_f32_e32 v73, v73, v74
	v_lshlrev_b32_e32 v74, 16, v238
	v_mul_f32_e32 v74, v239, v74
	s_and_saveexec_b64 s[0:1], s[16:17]
	s_cbranch_execz .LBB0_913
	v_mul_f32_e32 v74, v74, v254
.LBB0_913:
	s_or_b64 exec, exec, s[0:1]
	ds_read_u16 v238, v18 offset:14960
	ds_read_b32 v239, v16 offset:220
	ds_read_b32 v254, v15 offset:220
	ds_read_b128 v[76:79], v11 offset:13872
	ds_read_b128 v[80:83], v11 offset:13888
	ds_read_b128 v[84:87], v11 offset:13904
	ds_read_b128 v[88:91], v11 offset:13920
	s_waitcnt lgkmcnt(9)
	v_fma_f32 v75, v2, v240, 0
	v_fma_f32 v92, v3, v241, 0
	v_fma_f32 v93, v4, v242, 0
	v_fma_f32 v94, v5, v243, 0
	ds_read_b128 v[240:243], v11 offset:13936
	s_waitcnt lgkmcnt(9)
	v_fmac_f32_e32 v75, v6, v244
	v_fmac_f32_e32 v92, v7, v245
	v_fmac_f32_e32 v93, v8, v246
	v_fmac_f32_e32 v94, v9, v247
	ds_read_b128 v[244:247], v11 offset:13952
	s_waitcnt lgkmcnt(9)
	v_fmac_f32_e32 v75, v10, v248
	v_fmac_f32_e32 v92, v12, v249
	v_fmac_f32_e32 v93, v13, v250
	v_fmac_f32_e32 v94, v14, v251
	ds_read_b128 v[248:251], v11 offset:13968
	s_waitcnt lgkmcnt(6)
	v_fmac_f32_e32 v75, v17, v76
	v_fmac_f32_e32 v92, v19, v77
	v_fmac_f32_e32 v93, v28, v78
	v_fmac_f32_e32 v94, v35, v79
	ds_read_b128 v[76:79], v11 offset:13984
	s_waitcnt lgkmcnt(6)
	v_fmac_f32_e32 v75, v36, v80
	v_fmac_f32_e32 v92, v37, v81
	v_fmac_f32_e32 v93, v38, v82
	v_fmac_f32_e32 v94, v39, v83
	ds_read_b128 v[80:83], v11 offset:14000
	s_waitcnt lgkmcnt(6)
	v_fmac_f32_e32 v75, v40, v84
	v_fmac_f32_e32 v92, v41, v85
	v_fmac_f32_e32 v93, v42, v86
	v_fmac_f32_e32 v94, v43, v87
	ds_read_b128 v[84:87], v11 offset:14016
	s_waitcnt lgkmcnt(6)
	v_fmac_f32_e32 v75, v44, v88
	v_fmac_f32_e32 v92, v45, v89
	v_fmac_f32_e32 v93, v46, v90
	v_fmac_f32_e32 v94, v47, v91
	ds_read_b128 v[88:91], v11 offset:14032
	s_waitcnt lgkmcnt(6)
	v_fmac_f32_e32 v75, v48, v240
	v_fmac_f32_e32 v92, v49, v241
	v_fmac_f32_e32 v93, v50, v242
	v_fmac_f32_e32 v94, v51, v243
	s_waitcnt lgkmcnt(5)
	v_fmac_f32_e32 v75, v52, v244
	v_fmac_f32_e32 v92, v53, v245
	v_fmac_f32_e32 v93, v54, v246
	v_fmac_f32_e32 v94, v55, v247
	s_waitcnt lgkmcnt(4)
	v_fmac_f32_e32 v75, v56, v248
	v_fmac_f32_e32 v92, v57, v249
	v_fmac_f32_e32 v93, v58, v250
	v_fmac_f32_e32 v94, v59, v251
	s_waitcnt lgkmcnt(3)
	v_fmac_f32_e32 v75, v60, v76
	v_fmac_f32_e32 v92, v61, v77
	v_fmac_f32_e32 v93, v62, v78
	v_fmac_f32_e32 v94, v63, v79
	s_waitcnt lgkmcnt(2)
	v_fmac_f32_e32 v75, v64, v80
	v_fmac_f32_e32 v92, v65, v81
	v_fmac_f32_e32 v93, v66, v82
	v_fmac_f32_e32 v94, v67, v83
	s_waitcnt lgkmcnt(1)
	v_fmac_f32_e32 v75, v68, v84
	v_fmac_f32_e32 v92, v69, v85
	v_fmac_f32_e32 v93, v70, v86
	v_fmac_f32_e32 v94, v71, v87
	s_waitcnt lgkmcnt(0)
	v_fmac_f32_e32 v75, v72, v88
	v_fmac_f32_e32 v92, v73, v89
	ds_read_b128 v[240:243], v11 offset:14080
	ds_read_b128 v[244:247], v11 offset:14096
	ds_read_b128 v[248:251], v11 offset:14112
	v_add_f32_e32 v75, v75, v92
	v_add_f32_e32 v76, v93, v94
	v_add_f32_e32 v75, v76, v75
	v_sub_f32_e32 v74, v74, v75
	v_lshlrev_b32_e32 v75, 16, v238
	v_mul_f32_e32 v75, v239, v75
	s_and_saveexec_b64 s[0:1], s[16:17]
	s_cbranch_execz .LBB0_915
	v_mul_f32_e32 v75, v75, v254
.LBB0_915:
	s_or_b64 exec, exec, s[0:1]
	ds_read_u16 v238, v18 offset:15232
	ds_read_b32 v239, v16 offset:224
	ds_read_b32 v254, v15 offset:224
	ds_read_b128 v[76:79], v11 offset:14128
	ds_read_b128 v[80:83], v11 offset:14144
	ds_read_b128 v[84:87], v11 offset:14160
	ds_read_b128 v[88:91], v11 offset:14176
	s_waitcnt lgkmcnt(9)
	v_fma_f32 v92, v2, v240, 0
	v_fma_f32 v93, v3, v241, 0
	v_fma_f32 v94, v4, v242, 0
	v_fma_f32 v95, v5, v243, 0
	ds_read_b128 v[240:243], v11 offset:14192
	s_waitcnt lgkmcnt(9)
	v_fmac_f32_e32 v92, v6, v244
	v_fmac_f32_e32 v93, v7, v245
	v_fmac_f32_e32 v94, v8, v246
	v_fmac_f32_e32 v95, v9, v247
	ds_read_b128 v[244:247], v11 offset:14208
	s_waitcnt lgkmcnt(9)
	v_fmac_f32_e32 v92, v10, v248
	v_fmac_f32_e32 v93, v12, v249
	v_fmac_f32_e32 v94, v13, v250
	v_fmac_f32_e32 v95, v14, v251
	ds_read_b128 v[248:251], v11 offset:14224
	s_waitcnt lgkmcnt(6)
	v_fmac_f32_e32 v92, v17, v76
	v_fmac_f32_e32 v93, v19, v77
	v_fmac_f32_e32 v94, v28, v78
	v_fmac_f32_e32 v95, v35, v79
	ds_read_b128 v[76:79], v11 offset:14240
	s_waitcnt lgkmcnt(6)
	v_fmac_f32_e32 v92, v36, v80
	v_fmac_f32_e32 v93, v37, v81
	v_fmac_f32_e32 v94, v38, v82
	v_fmac_f32_e32 v95, v39, v83
	ds_read_b128 v[80:83], v11 offset:14256
	s_waitcnt lgkmcnt(6)
	v_fmac_f32_e32 v92, v40, v84
	v_fmac_f32_e32 v93, v41, v85
	v_fmac_f32_e32 v94, v42, v86
	v_fmac_f32_e32 v95, v43, v87
	ds_read_b128 v[84:87], v11 offset:14272
	s_waitcnt lgkmcnt(6)
	v_fmac_f32_e32 v92, v44, v88
	v_fmac_f32_e32 v93, v45, v89
	v_fmac_f32_e32 v94, v46, v90
	v_fmac_f32_e32 v95, v47, v91
	ds_read_b128 v[88:91], v11 offset:14288
	s_waitcnt lgkmcnt(6)
	v_fmac_f32_e32 v92, v48, v240
	v_fmac_f32_e32 v93, v49, v241
	v_fmac_f32_e32 v94, v50, v242
	v_fmac_f32_e32 v95, v51, v243
	s_waitcnt lgkmcnt(5)
	v_fmac_f32_e32 v92, v52, v244
	v_fmac_f32_e32 v93, v53, v245
	v_fmac_f32_e32 v94, v54, v246
	v_fmac_f32_e32 v95, v55, v247
	s_waitcnt lgkmcnt(4)
	v_fmac_f32_e32 v92, v56, v248
	v_fmac_f32_e32 v93, v57, v249
	v_fmac_f32_e32 v94, v58, v250
	v_fmac_f32_e32 v95, v59, v251
	s_waitcnt lgkmcnt(3)
	v_fmac_f32_e32 v92, v60, v76
	v_fmac_f32_e32 v93, v61, v77
	v_fmac_f32_e32 v94, v62, v78
	v_fmac_f32_e32 v95, v63, v79
	s_waitcnt lgkmcnt(2)
	v_fmac_f32_e32 v92, v64, v80
	v_fmac_f32_e32 v93, v65, v81
	v_fmac_f32_e32 v94, v66, v82
	v_fmac_f32_e32 v95, v67, v83
	s_waitcnt lgkmcnt(1)
	v_fmac_f32_e32 v92, v68, v84
	v_fmac_f32_e32 v93, v69, v85
	v_fmac_f32_e32 v94, v70, v86
	v_fmac_f32_e32 v95, v71, v87
	s_waitcnt lgkmcnt(0)
	v_fmac_f32_e32 v92, v72, v88
	v_fmac_f32_e32 v93, v73, v89
	v_fmac_f32_e32 v94, v74, v90
	ds_read_b128 v[240:243], v11 offset:14336
	ds_read_b128 v[244:247], v11 offset:14352
	ds_read_b128 v[248:251], v11 offset:14368
	v_add_f32_e32 v76, v92, v93
	v_add_f32_e32 v77, v95, v94
	v_add_f32_e32 v76, v76, v77
	v_sub_f32_e32 v75, v75, v76
	v_lshlrev_b32_e32 v76, 16, v238
	v_mul_f32_e32 v76, v239, v76
	s_and_saveexec_b64 s[0:1], s[16:17]
	s_cbranch_execz .LBB0_917
	v_mul_f32_e32 v76, v76, v254
.LBB0_917:
	s_or_b64 exec, exec, s[0:1]
	ds_read_u16 v238, v18 offset:15504
	ds_read_b32 v239, v16 offset:228
	ds_read_b32 v254, v15 offset:228
	ds_read_b128 v[78:81], v11 offset:14384
	ds_read_b128 v[82:85], v11 offset:14400
	ds_read_b128 v[86:89], v11 offset:14416
	ds_read_b128 v[90:93], v11 offset:14432
	s_waitcnt lgkmcnt(9)
	v_fma_f32 v77, v2, v240, 0
	v_fma_f32 v94, v3, v241, 0
	v_fma_f32 v95, v4, v242, 0
	v_fma_f32 v96, v5, v243, 0
	ds_read_b128 v[240:243], v11 offset:14448
	s_waitcnt lgkmcnt(9)
	v_fmac_f32_e32 v77, v6, v244
	v_fmac_f32_e32 v94, v7, v245
	v_fmac_f32_e32 v95, v8, v246
	v_fmac_f32_e32 v96, v9, v247
	ds_read_b128 v[244:247], v11 offset:14464
	s_waitcnt lgkmcnt(9)
	v_fmac_f32_e32 v77, v10, v248
	v_fmac_f32_e32 v94, v12, v249
	v_fmac_f32_e32 v95, v13, v250
	v_fmac_f32_e32 v96, v14, v251
	ds_read_b128 v[248:251], v11 offset:14480
	s_waitcnt lgkmcnt(6)
	v_fmac_f32_e32 v77, v17, v78
	v_fmac_f32_e32 v94, v19, v79
	v_fmac_f32_e32 v95, v28, v80
	v_fmac_f32_e32 v96, v35, v81
	ds_read_b128 v[78:81], v11 offset:14496
	s_waitcnt lgkmcnt(6)
	v_fmac_f32_e32 v77, v36, v82
	v_fmac_f32_e32 v94, v37, v83
	v_fmac_f32_e32 v95, v38, v84
	v_fmac_f32_e32 v96, v39, v85
	ds_read_b128 v[82:85], v11 offset:14512
	s_waitcnt lgkmcnt(6)
	v_fmac_f32_e32 v77, v40, v86
	v_fmac_f32_e32 v94, v41, v87
	v_fmac_f32_e32 v95, v42, v88
	v_fmac_f32_e32 v96, v43, v89
	ds_read_b128 v[86:89], v11 offset:14528
	s_waitcnt lgkmcnt(6)
	v_fmac_f32_e32 v77, v44, v90
	v_fmac_f32_e32 v94, v45, v91
	v_fmac_f32_e32 v95, v46, v92
	v_fmac_f32_e32 v96, v47, v93
	ds_read_b128 v[90:93], v11 offset:14544
	s_waitcnt lgkmcnt(6)
	v_fmac_f32_e32 v77, v48, v240
	v_fmac_f32_e32 v94, v49, v241
	v_fmac_f32_e32 v95, v50, v242
	v_fmac_f32_e32 v96, v51, v243
	s_waitcnt lgkmcnt(5)
	v_fmac_f32_e32 v77, v52, v244
	v_fmac_f32_e32 v94, v53, v245
	v_fmac_f32_e32 v95, v54, v246
	v_fmac_f32_e32 v96, v55, v247
	s_waitcnt lgkmcnt(4)
	v_fmac_f32_e32 v77, v56, v248
	v_fmac_f32_e32 v94, v57, v249
	v_fmac_f32_e32 v95, v58, v250
	v_fmac_f32_e32 v96, v59, v251
	s_waitcnt lgkmcnt(3)
	v_fmac_f32_e32 v77, v60, v78
	v_fmac_f32_e32 v94, v61, v79
	v_fmac_f32_e32 v95, v62, v80
	v_fmac_f32_e32 v96, v63, v81
	s_waitcnt lgkmcnt(2)
	v_fmac_f32_e32 v77, v64, v82
	v_fmac_f32_e32 v94, v65, v83
	v_fmac_f32_e32 v95, v66, v84
	v_fmac_f32_e32 v96, v67, v85
	s_waitcnt lgkmcnt(1)
	v_fmac_f32_e32 v77, v68, v86
	v_fmac_f32_e32 v94, v69, v87
	v_fmac_f32_e32 v95, v70, v88
	v_fmac_f32_e32 v96, v71, v89
	s_waitcnt lgkmcnt(0)
	v_fmac_f32_e32 v77, v72, v90
	v_fmac_f32_e32 v94, v73, v91
	v_fmac_f32_e32 v95, v74, v92
	v_fmac_f32_e32 v96, v75, v93
	ds_read_b128 v[240:243], v11 offset:14592
	ds_read_b128 v[244:247], v11 offset:14608
	ds_read_b128 v[248:251], v11 offset:14624
	v_add_f32_e32 v77, v77, v94
	v_add_f32_e32 v78, v95, v96
	v_add_f32_e32 v77, v77, v78
	v_sub_f32_e32 v76, v76, v77
	v_lshlrev_b32_e32 v77, 16, v238
	v_mul_f32_e32 v77, v239, v77
	s_and_saveexec_b64 s[0:1], s[16:17]
	s_cbranch_execz .LBB0_919
	v_mul_f32_e32 v77, v77, v254
.LBB0_919:
	s_or_b64 exec, exec, s[0:1]
	ds_read_u16 v238, v18 offset:15776
	ds_read_b32 v239, v16 offset:232
	ds_read_b32 v254, v15 offset:232
	ds_read_b128 v[78:81], v11 offset:14640
	ds_read_b128 v[82:85], v11 offset:14656
	ds_read_b128 v[86:89], v11 offset:14672
	ds_read_b128 v[90:93], v11 offset:14688
	s_waitcnt lgkmcnt(9)
	v_fma_f32 v94, v2, v240, 0
	v_fma_f32 v95, v3, v241, 0
	v_fma_f32 v96, v4, v242, 0
	v_fma_f32 v97, v5, v243, 0
	ds_read_b128 v[240:243], v11 offset:14704
	s_waitcnt lgkmcnt(9)
	v_fmac_f32_e32 v94, v6, v244
	v_fmac_f32_e32 v95, v7, v245
	v_fmac_f32_e32 v96, v8, v246
	v_fmac_f32_e32 v97, v9, v247
	ds_read_b128 v[244:247], v11 offset:14720
	s_waitcnt lgkmcnt(9)
	v_fmac_f32_e32 v94, v10, v248
	v_fmac_f32_e32 v95, v12, v249
	v_fmac_f32_e32 v96, v13, v250
	v_fmac_f32_e32 v97, v14, v251
	ds_read_b128 v[248:251], v11 offset:14736
	s_waitcnt lgkmcnt(6)
	v_fmac_f32_e32 v94, v17, v78
	v_fmac_f32_e32 v95, v19, v79
	v_fmac_f32_e32 v96, v28, v80
	v_fmac_f32_e32 v97, v35, v81
	ds_read_b128 v[78:81], v11 offset:14752
	s_waitcnt lgkmcnt(6)
	v_fmac_f32_e32 v94, v36, v82
	v_fmac_f32_e32 v95, v37, v83
	v_fmac_f32_e32 v96, v38, v84
	v_fmac_f32_e32 v97, v39, v85
	ds_read_b128 v[82:85], v11 offset:14768
	s_waitcnt lgkmcnt(6)
	v_fmac_f32_e32 v94, v40, v86
	v_fmac_f32_e32 v95, v41, v87
	v_fmac_f32_e32 v96, v42, v88
	v_fmac_f32_e32 v97, v43, v89
	ds_read_b128 v[86:89], v11 offset:14784
	s_waitcnt lgkmcnt(6)
	v_fmac_f32_e32 v94, v44, v90
	v_fmac_f32_e32 v95, v45, v91
	v_fmac_f32_e32 v96, v46, v92
	v_fmac_f32_e32 v97, v47, v93
	ds_read_b128 v[90:93], v11 offset:14800
	s_waitcnt lgkmcnt(6)
	v_fmac_f32_e32 v94, v48, v240
	v_fmac_f32_e32 v95, v49, v241
	v_fmac_f32_e32 v96, v50, v242
	v_fmac_f32_e32 v97, v51, v243
	ds_read_b128 v[240:243], v11 offset:14816
	s_waitcnt lgkmcnt(6)
	v_fmac_f32_e32 v94, v52, v244
	v_fmac_f32_e32 v95, v53, v245
	v_fmac_f32_e32 v96, v54, v246
	v_fmac_f32_e32 v97, v55, v247
	s_waitcnt lgkmcnt(5)
	v_fmac_f32_e32 v94, v56, v248
	v_fmac_f32_e32 v95, v57, v249
	v_fmac_f32_e32 v96, v58, v250
	v_fmac_f32_e32 v97, v59, v251
	s_waitcnt lgkmcnt(4)
	v_fmac_f32_e32 v94, v60, v78
	v_fmac_f32_e32 v95, v61, v79
	v_fmac_f32_e32 v96, v62, v80
	v_fmac_f32_e32 v97, v63, v81
	s_waitcnt lgkmcnt(3)
	v_fmac_f32_e32 v94, v64, v82
	v_fmac_f32_e32 v95, v65, v83
	v_fmac_f32_e32 v96, v66, v84
	v_fmac_f32_e32 v97, v67, v85
	s_waitcnt lgkmcnt(2)
	v_fmac_f32_e32 v94, v68, v86
	v_fmac_f32_e32 v95, v69, v87
	v_fmac_f32_e32 v96, v70, v88
	v_fmac_f32_e32 v97, v71, v89
	s_waitcnt lgkmcnt(1)
	v_fmac_f32_e32 v94, v72, v90
	v_fmac_f32_e32 v95, v73, v91
	v_fmac_f32_e32 v96, v74, v92
	v_fmac_f32_e32 v97, v75, v93
	s_waitcnt lgkmcnt(0)
	v_fmac_f32_e32 v94, v76, v240
	ds_read_b128 v[240:243], v11 offset:14848
	ds_read_b128 v[244:247], v11 offset:14864
	ds_read_b128 v[248:251], v11 offset:14880
	v_add_f32_e32 v78, v95, v94
	v_add_f32_e32 v79, v96, v97
	v_add_f32_e32 v78, v79, v78
	v_sub_f32_e32 v77, v77, v78
	v_lshlrev_b32_e32 v78, 16, v238
	v_mul_f32_e32 v78, v239, v78
	s_and_saveexec_b64 s[0:1], s[16:17]
	s_cbranch_execz .LBB0_921
	v_mul_f32_e32 v78, v78, v254
.LBB0_921:
	s_or_b64 exec, exec, s[0:1]
	ds_read_u16 v238, v18 offset:16048
	ds_read_b32 v239, v16 offset:236
	ds_read_b32 v254, v15 offset:236
	ds_read_b128 v[80:83], v11 offset:14896
	ds_read_b128 v[84:87], v11 offset:14912
	ds_read_b128 v[88:91], v11 offset:14928
	ds_read_b128 v[92:95], v11 offset:14944
	s_waitcnt lgkmcnt(9)
	v_fma_f32 v79, v2, v240, 0
	v_fma_f32 v96, v3, v241, 0
	v_fma_f32 v97, v4, v242, 0
	v_fma_f32 v98, v5, v243, 0
	ds_read_b128 v[240:243], v11 offset:14960
	s_waitcnt lgkmcnt(9)
	v_fmac_f32_e32 v79, v6, v244
	v_fmac_f32_e32 v96, v7, v245
	v_fmac_f32_e32 v97, v8, v246
	v_fmac_f32_e32 v98, v9, v247
	ds_read_b128 v[244:247], v11 offset:14976
	s_waitcnt lgkmcnt(9)
	v_fmac_f32_e32 v79, v10, v248
	v_fmac_f32_e32 v96, v12, v249
	v_fmac_f32_e32 v97, v13, v250
	v_fmac_f32_e32 v98, v14, v251
	ds_read_b128 v[248:251], v11 offset:14992
	s_waitcnt lgkmcnt(6)
	v_fmac_f32_e32 v79, v17, v80
	v_fmac_f32_e32 v96, v19, v81
	v_fmac_f32_e32 v97, v28, v82
	v_fmac_f32_e32 v98, v35, v83
	ds_read_b128 v[80:83], v11 offset:15008
	s_waitcnt lgkmcnt(6)
	v_fmac_f32_e32 v79, v36, v84
	v_fmac_f32_e32 v96, v37, v85
	v_fmac_f32_e32 v97, v38, v86
	v_fmac_f32_e32 v98, v39, v87
	ds_read_b128 v[84:87], v11 offset:15024
	s_waitcnt lgkmcnt(6)
	v_fmac_f32_e32 v79, v40, v88
	v_fmac_f32_e32 v96, v41, v89
	v_fmac_f32_e32 v97, v42, v90
	v_fmac_f32_e32 v98, v43, v91
	ds_read_b128 v[88:91], v11 offset:15040
	s_waitcnt lgkmcnt(6)
	v_fmac_f32_e32 v79, v44, v92
	v_fmac_f32_e32 v96, v45, v93
	v_fmac_f32_e32 v97, v46, v94
	v_fmac_f32_e32 v98, v47, v95
	ds_read_b128 v[92:95], v11 offset:15056
	s_waitcnt lgkmcnt(6)
	v_fmac_f32_e32 v79, v48, v240
	v_fmac_f32_e32 v96, v49, v241
	v_fmac_f32_e32 v97, v50, v242
	v_fmac_f32_e32 v98, v51, v243
	ds_read_b128 v[240:243], v11 offset:15072
	s_waitcnt lgkmcnt(6)
	v_fmac_f32_e32 v79, v52, v244
	v_fmac_f32_e32 v96, v53, v245
	v_fmac_f32_e32 v97, v54, v246
	v_fmac_f32_e32 v98, v55, v247
	s_waitcnt lgkmcnt(5)
	v_fmac_f32_e32 v79, v56, v248
	v_fmac_f32_e32 v96, v57, v249
	v_fmac_f32_e32 v97, v58, v250
	v_fmac_f32_e32 v98, v59, v251
	s_waitcnt lgkmcnt(4)
	v_fmac_f32_e32 v79, v60, v80
	v_fmac_f32_e32 v96, v61, v81
	v_fmac_f32_e32 v97, v62, v82
	v_fmac_f32_e32 v98, v63, v83
	s_waitcnt lgkmcnt(3)
	v_fmac_f32_e32 v79, v64, v84
	v_fmac_f32_e32 v96, v65, v85
	v_fmac_f32_e32 v97, v66, v86
	v_fmac_f32_e32 v98, v67, v87
	s_waitcnt lgkmcnt(2)
	v_fmac_f32_e32 v79, v68, v88
	v_fmac_f32_e32 v96, v69, v89
	v_fmac_f32_e32 v97, v70, v90
	v_fmac_f32_e32 v98, v71, v91
	s_waitcnt lgkmcnt(1)
	v_fmac_f32_e32 v79, v72, v92
	v_fmac_f32_e32 v96, v73, v93
	v_fmac_f32_e32 v97, v74, v94
	v_fmac_f32_e32 v98, v75, v95
	s_waitcnt lgkmcnt(0)
	v_fmac_f32_e32 v79, v76, v240
	v_fmac_f32_e32 v96, v77, v241
	ds_read_b128 v[240:243], v11 offset:15104
	ds_read_b128 v[244:247], v11 offset:15120
	ds_read_b128 v[248:251], v11 offset:15136
	v_add_f32_e32 v79, v79, v96
	v_add_f32_e32 v80, v97, v98
	v_add_f32_e32 v79, v80, v79
	v_sub_f32_e32 v78, v78, v79
	v_lshlrev_b32_e32 v79, 16, v238
	v_mul_f32_e32 v79, v239, v79
	s_and_saveexec_b64 s[0:1], s[16:17]
	s_cbranch_execz .LBB0_923
	v_mul_f32_e32 v79, v79, v254
.LBB0_923:
	s_or_b64 exec, exec, s[0:1]
	ds_read_u16 v238, v18 offset:16320
	ds_read_b32 v239, v16 offset:240
	ds_read_b32 v254, v15 offset:240
	ds_read_b128 v[80:83], v11 offset:15152
	ds_read_b128 v[84:87], v11 offset:15168
	ds_read_b128 v[88:91], v11 offset:15184
	ds_read_b128 v[92:95], v11 offset:15200
	s_waitcnt lgkmcnt(9)
	v_fma_f32 v96, v2, v240, 0
	v_fma_f32 v97, v3, v241, 0
	v_fma_f32 v98, v4, v242, 0
	v_fma_f32 v99, v5, v243, 0
	ds_read_b128 v[240:243], v11 offset:15216
	s_waitcnt lgkmcnt(9)
	v_fmac_f32_e32 v96, v6, v244
	v_fmac_f32_e32 v97, v7, v245
	v_fmac_f32_e32 v98, v8, v246
	v_fmac_f32_e32 v99, v9, v247
	ds_read_b128 v[244:247], v11 offset:15232
	s_waitcnt lgkmcnt(9)
	v_fmac_f32_e32 v96, v10, v248
	v_fmac_f32_e32 v97, v12, v249
	v_fmac_f32_e32 v98, v13, v250
	v_fmac_f32_e32 v99, v14, v251
	ds_read_b128 v[248:251], v11 offset:15248
	s_waitcnt lgkmcnt(6)
	v_fmac_f32_e32 v96, v17, v80
	v_fmac_f32_e32 v97, v19, v81
	v_fmac_f32_e32 v98, v28, v82
	v_fmac_f32_e32 v99, v35, v83
	ds_read_b128 v[80:83], v11 offset:15264
	s_waitcnt lgkmcnt(6)
	v_fmac_f32_e32 v96, v36, v84
	v_fmac_f32_e32 v97, v37, v85
	v_fmac_f32_e32 v98, v38, v86
	v_fmac_f32_e32 v99, v39, v87
	ds_read_b128 v[84:87], v11 offset:15280
	s_waitcnt lgkmcnt(6)
	v_fmac_f32_e32 v96, v40, v88
	v_fmac_f32_e32 v97, v41, v89
	v_fmac_f32_e32 v98, v42, v90
	v_fmac_f32_e32 v99, v43, v91
	ds_read_b128 v[88:91], v11 offset:15296
	s_waitcnt lgkmcnt(6)
	v_fmac_f32_e32 v96, v44, v92
	v_fmac_f32_e32 v97, v45, v93
	v_fmac_f32_e32 v98, v46, v94
	v_fmac_f32_e32 v99, v47, v95
	ds_read_b128 v[92:95], v11 offset:15312
	s_waitcnt lgkmcnt(6)
	v_fmac_f32_e32 v96, v48, v240
	v_fmac_f32_e32 v97, v49, v241
	v_fmac_f32_e32 v98, v50, v242
	v_fmac_f32_e32 v99, v51, v243
	ds_read_b128 v[240:243], v11 offset:15328
	s_waitcnt lgkmcnt(6)
	v_fmac_f32_e32 v96, v52, v244
	v_fmac_f32_e32 v97, v53, v245
	v_fmac_f32_e32 v98, v54, v246
	v_fmac_f32_e32 v99, v55, v247
	s_waitcnt lgkmcnt(5)
	v_fmac_f32_e32 v96, v56, v248
	v_fmac_f32_e32 v97, v57, v249
	v_fmac_f32_e32 v98, v58, v250
	v_fmac_f32_e32 v99, v59, v251
	s_waitcnt lgkmcnt(4)
	v_fmac_f32_e32 v96, v60, v80
	v_fmac_f32_e32 v97, v61, v81
	v_fmac_f32_e32 v98, v62, v82
	v_fmac_f32_e32 v99, v63, v83
	s_waitcnt lgkmcnt(3)
	v_fmac_f32_e32 v96, v64, v84
	v_fmac_f32_e32 v97, v65, v85
	v_fmac_f32_e32 v98, v66, v86
	v_fmac_f32_e32 v99, v67, v87
	s_waitcnt lgkmcnt(2)
	v_fmac_f32_e32 v96, v68, v88
	v_fmac_f32_e32 v97, v69, v89
	v_fmac_f32_e32 v98, v70, v90
	v_fmac_f32_e32 v99, v71, v91
	s_waitcnt lgkmcnt(1)
	v_fmac_f32_e32 v96, v72, v92
	v_fmac_f32_e32 v97, v73, v93
	v_fmac_f32_e32 v98, v74, v94
	v_fmac_f32_e32 v99, v75, v95
	s_waitcnt lgkmcnt(0)
	v_fmac_f32_e32 v96, v76, v240
	v_fmac_f32_e32 v97, v77, v241
	v_fmac_f32_e32 v98, v78, v242
	ds_read_b128 v[240:243], v11 offset:15360
	ds_read_b128 v[244:247], v11 offset:15376
	ds_read_b128 v[248:251], v11 offset:15392
	v_add_f32_e32 v80, v96, v97
	v_add_f32_e32 v81, v99, v98
	v_add_f32_e32 v80, v80, v81
	v_sub_f32_e32 v79, v79, v80
	v_lshlrev_b32_e32 v80, 16, v238
	v_mul_f32_e32 v80, v239, v80
	s_and_saveexec_b64 s[0:1], s[16:17]
	s_cbranch_execz .LBB0_925
	v_mul_f32_e32 v80, v80, v254
.LBB0_925:
	s_or_b64 exec, exec, s[0:1]
	ds_read_u16 v238, v18 offset:16592
	ds_read_b32 v239, v16 offset:244
	ds_read_b32 v254, v15 offset:244
	ds_read_b128 v[82:85], v11 offset:15408
	ds_read_b128 v[86:89], v11 offset:15424
	ds_read_b128 v[90:93], v11 offset:15440
	ds_read_b128 v[94:97], v11 offset:15456
	s_waitcnt lgkmcnt(9)
	v_fma_f32 v81, v2, v240, 0
	v_fma_f32 v98, v3, v241, 0
	v_fma_f32 v99, v4, v242, 0
	v_fma_f32 v100, v5, v243, 0
	ds_read_b128 v[240:243], v11 offset:15472
	s_waitcnt lgkmcnt(9)
	v_fmac_f32_e32 v81, v6, v244
	v_fmac_f32_e32 v98, v7, v245
	v_fmac_f32_e32 v99, v8, v246
	v_fmac_f32_e32 v100, v9, v247
	ds_read_b128 v[244:247], v11 offset:15488
	s_waitcnt lgkmcnt(9)
	v_fmac_f32_e32 v81, v10, v248
	v_fmac_f32_e32 v98, v12, v249
	v_fmac_f32_e32 v99, v13, v250
	v_fmac_f32_e32 v100, v14, v251
	ds_read_b128 v[248:251], v11 offset:15504
	s_waitcnt lgkmcnt(6)
	v_fmac_f32_e32 v81, v17, v82
	v_fmac_f32_e32 v98, v19, v83
	v_fmac_f32_e32 v99, v28, v84
	v_fmac_f32_e32 v100, v35, v85
	ds_read_b128 v[82:85], v11 offset:15520
	s_waitcnt lgkmcnt(6)
	v_fmac_f32_e32 v81, v36, v86
	v_fmac_f32_e32 v98, v37, v87
	v_fmac_f32_e32 v99, v38, v88
	v_fmac_f32_e32 v100, v39, v89
	ds_read_b128 v[86:89], v11 offset:15536
	s_waitcnt lgkmcnt(6)
	v_fmac_f32_e32 v81, v40, v90
	v_fmac_f32_e32 v98, v41, v91
	v_fmac_f32_e32 v99, v42, v92
	v_fmac_f32_e32 v100, v43, v93
	ds_read_b128 v[90:93], v11 offset:15552
	s_waitcnt lgkmcnt(6)
	v_fmac_f32_e32 v81, v44, v94
	v_fmac_f32_e32 v98, v45, v95
	v_fmac_f32_e32 v99, v46, v96
	v_fmac_f32_e32 v100, v47, v97
	ds_read_b128 v[94:97], v11 offset:15568
	s_waitcnt lgkmcnt(6)
	v_fmac_f32_e32 v81, v48, v240
	v_fmac_f32_e32 v98, v49, v241
	v_fmac_f32_e32 v99, v50, v242
	v_fmac_f32_e32 v100, v51, v243
	ds_read_b128 v[240:243], v11 offset:15584
	s_waitcnt lgkmcnt(6)
	v_fmac_f32_e32 v81, v52, v244
	v_fmac_f32_e32 v98, v53, v245
	v_fmac_f32_e32 v99, v54, v246
	v_fmac_f32_e32 v100, v55, v247
	s_waitcnt lgkmcnt(5)
	v_fmac_f32_e32 v81, v56, v248
	v_fmac_f32_e32 v98, v57, v249
	v_fmac_f32_e32 v99, v58, v250
	v_fmac_f32_e32 v100, v59, v251
	s_waitcnt lgkmcnt(4)
	v_fmac_f32_e32 v81, v60, v82
	v_fmac_f32_e32 v98, v61, v83
	v_fmac_f32_e32 v99, v62, v84
	v_fmac_f32_e32 v100, v63, v85
	s_waitcnt lgkmcnt(3)
	v_fmac_f32_e32 v81, v64, v86
	v_fmac_f32_e32 v98, v65, v87
	v_fmac_f32_e32 v99, v66, v88
	v_fmac_f32_e32 v100, v67, v89
	s_waitcnt lgkmcnt(2)
	v_fmac_f32_e32 v81, v68, v90
	v_fmac_f32_e32 v98, v69, v91
	v_fmac_f32_e32 v99, v70, v92
	v_fmac_f32_e32 v100, v71, v93
	s_waitcnt lgkmcnt(1)
	v_fmac_f32_e32 v81, v72, v94
	v_fmac_f32_e32 v98, v73, v95
	v_fmac_f32_e32 v99, v74, v96
	v_fmac_f32_e32 v100, v75, v97
	s_waitcnt lgkmcnt(0)
	v_fmac_f32_e32 v81, v76, v240
	v_fmac_f32_e32 v98, v77, v241
	v_fmac_f32_e32 v99, v78, v242
	v_fmac_f32_e32 v100, v79, v243
	ds_read_b128 v[240:243], v11 offset:15616
	ds_read_b128 v[244:247], v11 offset:15632
	ds_read_b128 v[248:251], v11 offset:15648
	v_add_f32_e32 v81, v81, v98
	v_add_f32_e32 v82, v99, v100
	v_add_f32_e32 v81, v81, v82
	v_sub_f32_e32 v80, v80, v81
	v_lshlrev_b32_e32 v81, 16, v238
	v_mul_f32_e32 v81, v239, v81
	s_and_saveexec_b64 s[0:1], s[16:17]
	s_cbranch_execz .LBB0_927
	v_mul_f32_e32 v81, v81, v254
.LBB0_927:
	s_or_b64 exec, exec, s[0:1]
	ds_read_u16 v238, v18 offset:16864
	ds_read_b32 v239, v16 offset:248
	ds_read_b32 v254, v15 offset:248
	ds_read_b128 v[82:85], v11 offset:15664
	ds_read_b128 v[86:89], v11 offset:15680
	ds_read_b128 v[90:93], v11 offset:15696
	ds_read_b128 v[94:97], v11 offset:15712
	s_waitcnt lgkmcnt(9)
	v_fma_f32 v98, v2, v240, 0
	v_fma_f32 v99, v3, v241, 0
	v_fma_f32 v100, v4, v242, 0
	v_fma_f32 v101, v5, v243, 0
	ds_read_b128 v[240:243], v11 offset:15728
	s_waitcnt lgkmcnt(9)
	v_fmac_f32_e32 v98, v6, v244
	v_fmac_f32_e32 v99, v7, v245
	v_fmac_f32_e32 v100, v8, v246
	v_fmac_f32_e32 v101, v9, v247
	ds_read_b128 v[244:247], v11 offset:15744
	s_waitcnt lgkmcnt(9)
	v_fmac_f32_e32 v98, v10, v248
	v_fmac_f32_e32 v99, v12, v249
	v_fmac_f32_e32 v100, v13, v250
	v_fmac_f32_e32 v101, v14, v251
	ds_read_b128 v[248:251], v11 offset:15760
	s_waitcnt lgkmcnt(6)
	v_fmac_f32_e32 v98, v17, v82
	v_fmac_f32_e32 v99, v19, v83
	v_fmac_f32_e32 v100, v28, v84
	v_fmac_f32_e32 v101, v35, v85
	ds_read_b128 v[82:85], v11 offset:15776
	s_waitcnt lgkmcnt(6)
	v_fmac_f32_e32 v98, v36, v86
	v_fmac_f32_e32 v99, v37, v87
	v_fmac_f32_e32 v100, v38, v88
	v_fmac_f32_e32 v101, v39, v89
	ds_read_b128 v[86:89], v11 offset:15792
	s_waitcnt lgkmcnt(6)
	v_fmac_f32_e32 v98, v40, v90
	v_fmac_f32_e32 v99, v41, v91
	v_fmac_f32_e32 v100, v42, v92
	v_fmac_f32_e32 v101, v43, v93
	ds_read_b128 v[90:93], v11 offset:15808
	s_waitcnt lgkmcnt(6)
	v_fmac_f32_e32 v98, v44, v94
	v_fmac_f32_e32 v99, v45, v95
	v_fmac_f32_e32 v100, v46, v96
	v_fmac_f32_e32 v101, v47, v97
	ds_read_b128 v[94:97], v11 offset:15824
	s_waitcnt lgkmcnt(6)
	v_fmac_f32_e32 v98, v48, v240
	v_fmac_f32_e32 v99, v49, v241
	v_fmac_f32_e32 v100, v50, v242
	v_fmac_f32_e32 v101, v51, v243
	ds_read_b128 v[240:243], v11 offset:15840
	s_waitcnt lgkmcnt(6)
	v_fmac_f32_e32 v98, v52, v244
	v_fmac_f32_e32 v99, v53, v245
	v_fmac_f32_e32 v100, v54, v246
	v_fmac_f32_e32 v101, v55, v247
	ds_read_b128 v[244:247], v11 offset:15856
	s_waitcnt lgkmcnt(6)
	v_fmac_f32_e32 v98, v56, v248
	v_fmac_f32_e32 v99, v57, v249
	v_fmac_f32_e32 v100, v58, v250
	v_fmac_f32_e32 v101, v59, v251
	s_waitcnt lgkmcnt(5)
	v_fmac_f32_e32 v98, v60, v82
	v_fmac_f32_e32 v99, v61, v83
	v_fmac_f32_e32 v100, v62, v84
	v_fmac_f32_e32 v101, v63, v85
	s_waitcnt lgkmcnt(4)
	v_fmac_f32_e32 v98, v64, v86
	v_fmac_f32_e32 v99, v65, v87
	v_fmac_f32_e32 v100, v66, v88
	v_fmac_f32_e32 v101, v67, v89
	s_waitcnt lgkmcnt(3)
	v_fmac_f32_e32 v98, v68, v90
	v_fmac_f32_e32 v99, v69, v91
	v_fmac_f32_e32 v100, v70, v92
	v_fmac_f32_e32 v101, v71, v93
	s_waitcnt lgkmcnt(2)
	v_fmac_f32_e32 v98, v72, v94
	v_fmac_f32_e32 v99, v73, v95
	v_fmac_f32_e32 v100, v74, v96
	v_fmac_f32_e32 v101, v75, v97
	s_waitcnt lgkmcnt(1)
	v_fmac_f32_e32 v98, v76, v240
	v_fmac_f32_e32 v99, v77, v241
	v_fmac_f32_e32 v100, v78, v242
	v_fmac_f32_e32 v101, v79, v243
	s_waitcnt lgkmcnt(0)
	v_fmac_f32_e32 v98, v80, v244
	ds_read_b128 v[240:243], v11 offset:15872
	ds_read_b128 v[244:247], v11 offset:15888
	ds_read_b128 v[248:251], v11 offset:15904
	v_add_f32_e32 v82, v99, v98
	v_add_f32_e32 v83, v100, v101
	v_add_f32_e32 v82, v83, v82
	v_sub_f32_e32 v81, v81, v82
	v_lshlrev_b32_e32 v82, 16, v238
	v_mul_f32_e32 v82, v239, v82
	s_and_saveexec_b64 s[0:1], s[16:17]
	s_cbranch_execz .LBB0_929
	v_mul_f32_e32 v82, v82, v254
.LBB0_929:
	s_or_b64 exec, exec, s[0:1]
	ds_read_u16 v238, v18 offset:17136
	ds_read_b32 v239, v16 offset:252
	ds_read_b32 v254, v15 offset:252
	ds_read_b128 v[84:87], v11 offset:15920
	ds_read_b128 v[88:91], v11 offset:15936
	ds_read_b128 v[92:95], v11 offset:15952
	ds_read_b128 v[96:99], v11 offset:15968
	s_waitcnt lgkmcnt(9)
	v_fma_f32 v83, v2, v240, 0
	v_fma_f32 v100, v3, v241, 0
	v_fma_f32 v101, v4, v242, 0
	v_fma_f32 v102, v5, v243, 0
	ds_read_b128 v[240:243], v11 offset:15984
	s_waitcnt lgkmcnt(9)
	v_fmac_f32_e32 v83, v6, v244
	v_fmac_f32_e32 v100, v7, v245
	v_fmac_f32_e32 v101, v8, v246
	v_fmac_f32_e32 v102, v9, v247
	ds_read_b128 v[244:247], v11 offset:16000
	s_waitcnt lgkmcnt(9)
	v_fmac_f32_e32 v83, v10, v248
	v_fmac_f32_e32 v100, v12, v249
	v_fmac_f32_e32 v101, v13, v250
	v_fmac_f32_e32 v102, v14, v251
	ds_read_b128 v[248:251], v11 offset:16016
	s_waitcnt lgkmcnt(6)
	v_fmac_f32_e32 v83, v17, v84
	v_fmac_f32_e32 v100, v19, v85
	v_fmac_f32_e32 v101, v28, v86
	v_fmac_f32_e32 v102, v35, v87
	ds_read_b128 v[84:87], v11 offset:16032
	s_waitcnt lgkmcnt(6)
	v_fmac_f32_e32 v83, v36, v88
	v_fmac_f32_e32 v100, v37, v89
	v_fmac_f32_e32 v101, v38, v90
	v_fmac_f32_e32 v102, v39, v91
	ds_read_b128 v[88:91], v11 offset:16048
	s_waitcnt lgkmcnt(6)
	v_fmac_f32_e32 v83, v40, v92
	v_fmac_f32_e32 v100, v41, v93
	v_fmac_f32_e32 v101, v42, v94
	v_fmac_f32_e32 v102, v43, v95
	ds_read_b128 v[92:95], v11 offset:16064
	s_waitcnt lgkmcnt(6)
	v_fmac_f32_e32 v83, v44, v96
	v_fmac_f32_e32 v100, v45, v97
	v_fmac_f32_e32 v101, v46, v98
	v_fmac_f32_e32 v102, v47, v99
	ds_read_b128 v[96:99], v11 offset:16080
	s_waitcnt lgkmcnt(6)
	v_fmac_f32_e32 v83, v48, v240
	v_fmac_f32_e32 v100, v49, v241
	v_fmac_f32_e32 v101, v50, v242
	v_fmac_f32_e32 v102, v51, v243
	ds_read_b128 v[240:243], v11 offset:16096
	s_waitcnt lgkmcnt(6)
	v_fmac_f32_e32 v83, v52, v244
	v_fmac_f32_e32 v100, v53, v245
	v_fmac_f32_e32 v101, v54, v246
	v_fmac_f32_e32 v102, v55, v247
	ds_read_b128 v[244:247], v11 offset:16112
	s_waitcnt lgkmcnt(6)
	v_fmac_f32_e32 v83, v56, v248
	v_fmac_f32_e32 v100, v57, v249
	v_fmac_f32_e32 v101, v58, v250
	v_fmac_f32_e32 v102, v59, v251
	s_waitcnt lgkmcnt(5)
	v_fmac_f32_e32 v83, v60, v84
	v_fmac_f32_e32 v100, v61, v85
	v_fmac_f32_e32 v101, v62, v86
	v_fmac_f32_e32 v102, v63, v87
	s_waitcnt lgkmcnt(4)
	v_fmac_f32_e32 v83, v64, v88
	v_fmac_f32_e32 v100, v65, v89
	v_fmac_f32_e32 v101, v66, v90
	v_fmac_f32_e32 v102, v67, v91
	s_waitcnt lgkmcnt(3)
	v_fmac_f32_e32 v83, v68, v92
	v_fmac_f32_e32 v100, v69, v93
	v_fmac_f32_e32 v101, v70, v94
	v_fmac_f32_e32 v102, v71, v95
	s_waitcnt lgkmcnt(2)
	v_fmac_f32_e32 v83, v72, v96
	v_fmac_f32_e32 v100, v73, v97
	v_fmac_f32_e32 v101, v74, v98
	v_fmac_f32_e32 v102, v75, v99
	s_waitcnt lgkmcnt(1)
	v_fmac_f32_e32 v83, v76, v240
	v_fmac_f32_e32 v100, v77, v241
	v_fmac_f32_e32 v101, v78, v242
	v_fmac_f32_e32 v102, v79, v243
	s_waitcnt lgkmcnt(0)
	v_fmac_f32_e32 v83, v80, v244
	v_fmac_f32_e32 v100, v81, v245
	ds_read_b128 v[240:243], v11 offset:16128
	ds_read_b128 v[244:247], v11 offset:16144
	ds_read_b128 v[248:251], v11 offset:16160
	v_add_f32_e32 v83, v83, v100
	v_add_f32_e32 v84, v101, v102
	v_add_f32_e32 v83, v84, v83
	v_sub_f32_e32 v82, v82, v83
	v_lshlrev_b32_e32 v18, 16, v238
	v_mul_f32_e32 v16, v239, v18
	s_and_saveexec_b64 s[0:1], s[16:17]
	s_cbranch_execz .LBB0_931
	v_mul_f32_e32 v16, v16, v254
.LBB0_931:
	s_or_b64 exec, exec, s[0:1]
	ds_read_b128 v[84:87], v11 offset:16176
	ds_read_b128 v[88:91], v11 offset:16192
	ds_read_b128 v[92:95], v11 offset:16208
	ds_read_b128 v[96:99], v11 offset:16224
	s_waitcnt lgkmcnt(6)
	v_fma_f32 v15, v2, v240, 0
	v_fma_f32 v18, v3, v241, 0
	v_fma_f32 v83, v4, v242, 0
	v_fma_f32 v100, v5, v243, 0
	ds_read_b128 v[240:243], v11 offset:16240
	s_waitcnt lgkmcnt(6)
	v_fmac_f32_e32 v15, v6, v244
	v_fmac_f32_e32 v18, v7, v245
	v_fmac_f32_e32 v83, v8, v246
	v_fmac_f32_e32 v100, v9, v247
	ds_read_b128 v[244:247], v11 offset:16256
	s_waitcnt lgkmcnt(6)
	v_fmac_f32_e32 v15, v10, v248
	v_fmac_f32_e32 v18, v12, v249
	v_fmac_f32_e32 v83, v13, v250
	v_fmac_f32_e32 v100, v14, v251
	ds_read_b128 v[248:251], v11 offset:16272
	s_waitcnt lgkmcnt(6)
	v_fmac_f32_e32 v15, v17, v84
	v_fmac_f32_e32 v18, v19, v85
	v_fmac_f32_e32 v83, v28, v86
	v_fmac_f32_e32 v100, v35, v87
	ds_read_b128 v[84:87], v11 offset:16288
	s_waitcnt lgkmcnt(6)
	v_fmac_f32_e32 v15, v36, v88
	v_fmac_f32_e32 v18, v37, v89
	v_fmac_f32_e32 v83, v38, v90
	v_fmac_f32_e32 v100, v39, v91
	ds_read_b128 v[88:91], v11 offset:16304
	s_waitcnt lgkmcnt(6)
	v_fmac_f32_e32 v15, v40, v92
	v_fmac_f32_e32 v18, v41, v93
	v_fmac_f32_e32 v83, v42, v94
	v_fmac_f32_e32 v100, v43, v95
	ds_read_b128 v[92:95], v11 offset:16320
	s_waitcnt lgkmcnt(6)
	v_fmac_f32_e32 v15, v44, v96
	v_fmac_f32_e32 v18, v45, v97
	v_fmac_f32_e32 v83, v46, v98
	v_fmac_f32_e32 v100, v47, v99
	ds_read_b128 v[96:99], v11 offset:16336
	s_waitcnt lgkmcnt(6)
	v_fmac_f32_e32 v15, v48, v240
	v_fmac_f32_e32 v18, v49, v241
	v_fmac_f32_e32 v83, v50, v242
	v_fmac_f32_e32 v100, v51, v243
	ds_read_b128 v[240:243], v11 offset:16352
	s_waitcnt lgkmcnt(6)
	v_fmac_f32_e32 v15, v52, v244
	v_fmac_f32_e32 v18, v53, v245
	v_fmac_f32_e32 v83, v54, v246
	v_fmac_f32_e32 v100, v55, v247
	ds_read_b128 v[244:247], v11 offset:16368
	s_waitcnt lgkmcnt(6)
	v_fmac_f32_e32 v15, v56, v248
	v_fmac_f32_e32 v18, v57, v249
	v_fmac_f32_e32 v83, v58, v250
	v_fmac_f32_e32 v100, v59, v251
	s_waitcnt lgkmcnt(5)
	v_fmac_f32_e32 v15, v60, v84
	v_fmac_f32_e32 v18, v61, v85
	v_fmac_f32_e32 v83, v62, v86
	v_fmac_f32_e32 v100, v63, v87
	s_waitcnt lgkmcnt(4)
	v_fmac_f32_e32 v15, v64, v88
	v_fmac_f32_e32 v18, v65, v89
	v_fmac_f32_e32 v83, v66, v90
	v_fmac_f32_e32 v100, v67, v91
	s_waitcnt lgkmcnt(3)
	v_fmac_f32_e32 v15, v68, v92
	v_fmac_f32_e32 v18, v69, v93
	v_fmac_f32_e32 v83, v70, v94
	v_fmac_f32_e32 v100, v71, v95
	s_waitcnt lgkmcnt(2)
	v_fmac_f32_e32 v15, v72, v96
	v_fmac_f32_e32 v18, v73, v97
	v_fmac_f32_e32 v83, v74, v98
	v_fmac_f32_e32 v100, v75, v99
	s_waitcnt lgkmcnt(1)
	v_fmac_f32_e32 v15, v76, v240
	v_fmac_f32_e32 v18, v77, v241
	v_fmac_f32_e32 v83, v78, v242
	v_fmac_f32_e32 v100, v79, v243
	s_waitcnt lgkmcnt(0)
	v_fmac_f32_e32 v15, v80, v244
	v_fmac_f32_e32 v18, v81, v245
	v_fmac_f32_e32 v83, v82, v246
	v_add_f32_e32 v11, v15, v18
	v_add_f32_e32 v15, v100, v83
	v_add_f32_e32 v11, v11, v15
	v_sub_f32_e32 v11, v16, v11
	s_and_saveexec_b64 s[0:1], s[16:17]
	s_xor_b64 s[0:1], exec, s[0:1]
	s_cbranch_execz .LBB0_941
	v_lshl_add_u64 v[84:85], v[22:23], 1, s[70:71]
	v_add_co_u32_e32 v88, vcc, 0x4000, v84
	v_cvt_pk_bf16_f32 v2, v2, s0
	s_mov_b64 s[24:25], 0x4000
	v_addc_co_u32_e32 v89, vcc, 0, v85, vcc
	v_lshl_add_u64 v[86:87], v[84:85], 0, s[24:25]
	global_store_short v[88:89], v2, off
	v_cvt_pk_bf16_f32 v2, v3, s0
	global_store_short v[86:87], v2, off offset:256
	v_cvt_pk_bf16_f32 v2, v4, s0
	global_store_short v[86:87], v2, off offset:512
	v_cvt_pk_bf16_f32 v2, v5, s0
	global_store_short v[86:87], v2, off offset:768
	v_cvt_pk_bf16_f32 v2, v6, s0
	global_store_short v[86:87], v2, off offset:1024
	v_cvt_pk_bf16_f32 v2, v7, s0
	global_store_short v[86:87], v2, off offset:1280
	v_cvt_pk_bf16_f32 v2, v8, s0
	global_store_short v[86:87], v2, off offset:1536
	v_cvt_pk_bf16_f32 v2, v9, s0
	global_store_short v[86:87], v2, off offset:1792
	v_cvt_pk_bf16_f32 v2, v10, s0
	global_store_short v[86:87], v2, off offset:2048
	v_cvt_pk_bf16_f32 v2, v12, s0
	global_store_short v[86:87], v2, off offset:2304
	v_cvt_pk_bf16_f32 v2, v13, s0
	global_store_short v[86:87], v2, off offset:2560
	v_cvt_pk_bf16_f32 v2, v14, s0
	global_store_short v[86:87], v2, off offset:2816
	v_cvt_pk_bf16_f32 v2, v17, s0
	global_store_short v[86:87], v2, off offset:3072
	v_cvt_pk_bf16_f32 v2, v19, s0
	global_store_short v[86:87], v2, off offset:3328
	v_cvt_pk_bf16_f32 v2, v28, s0
	global_store_short v[86:87], v2, off offset:3584
	v_cvt_pk_bf16_f32 v2, v35, s0
	s_movk_i32 s24, 0x5000
	global_store_short v[86:87], v2, off offset:3840
	v_add_co_u32_e32 v2, vcc, s24, v84
	s_movk_i32 s24, 0x6000
	s_nop 0
	v_addc_co_u32_e32 v3, vcc, 0, v85, vcc
	v_add_co_u32_e32 v4, vcc, s24, v84
	v_cvt_pk_bf16_f32 v6, v36, s0
	s_nop 0
	v_addc_co_u32_e32 v5, vcc, 0, v85, vcc
	global_store_short v[4:5], v6, off offset:-4096
	v_cvt_pk_bf16_f32 v6, v37, s0
	global_store_short v[2:3], v6, off offset:256
	v_cvt_pk_bf16_f32 v6, v38, s0
	global_store_short v[2:3], v6, off offset:512
	v_cvt_pk_bf16_f32 v6, v39, s0
	global_store_short v[2:3], v6, off offset:768
	v_cvt_pk_bf16_f32 v6, v40, s0
	global_store_short v[2:3], v6, off offset:1024
	v_cvt_pk_bf16_f32 v6, v41, s0
	global_store_short v[2:3], v6, off offset:1280
	v_cvt_pk_bf16_f32 v6, v42, s0
	global_store_short v[2:3], v6, off offset:1536
	v_cvt_pk_bf16_f32 v6, v43, s0
	global_store_short v[2:3], v6, off offset:1792
	v_cvt_pk_bf16_f32 v6, v44, s0
	global_store_short v[2:3], v6, off offset:2048
	v_cvt_pk_bf16_f32 v6, v45, s0
	global_store_short v[2:3], v6, off offset:2304
	v_cvt_pk_bf16_f32 v6, v46, s0
	global_store_short v[2:3], v6, off offset:2560
	v_cvt_pk_bf16_f32 v6, v47, s0
	global_store_short v[2:3], v6, off offset:2816
	v_cvt_pk_bf16_f32 v6, v48, s0
	global_store_short v[2:3], v6, off offset:3072
	v_cvt_pk_bf16_f32 v6, v49, s0
	global_store_short v[2:3], v6, off offset:3328
	v_cvt_pk_bf16_f32 v6, v50, s0
	global_store_short v[2:3], v6, off offset:3584
	v_cvt_pk_bf16_f32 v6, v51, s0
	global_store_short v[2:3], v6, off offset:3840
	v_cvt_pk_bf16_f32 v2, v52, s0
	global_store_short v[4:5], v2, off
	v_cvt_pk_bf16_f32 v2, v53, s0
	global_store_short v[4:5], v2, off offset:256
	v_cvt_pk_bf16_f32 v2, v54, s0
	global_store_short v[4:5], v2, off offset:512
	v_cvt_pk_bf16_f32 v2, v55, s0
	global_store_short v[4:5], v2, off offset:768
	v_cvt_pk_bf16_f32 v2, v56, s0
	global_store_short v[4:5], v2, off offset:1024
	v_cvt_pk_bf16_f32 v2, v57, s0
	global_store_short v[4:5], v2, off offset:1280
	v_cvt_pk_bf16_f32 v2, v58, s0
	global_store_short v[4:5], v2, off offset:1536
	v_cvt_pk_bf16_f32 v2, v59, s0
	global_store_short v[4:5], v2, off offset:1792
	v_cvt_pk_bf16_f32 v2, v60, s0
	global_store_short v[4:5], v2, off offset:2048
	v_cvt_pk_bf16_f32 v2, v61, s0
	global_store_short v[4:5], v2, off offset:2304
	v_cvt_pk_bf16_f32 v2, v62, s0
	global_store_short v[4:5], v2, off offset:2560
	v_cvt_pk_bf16_f32 v2, v63, s0
	global_store_short v[4:5], v2, off offset:2816
	v_cvt_pk_bf16_f32 v2, v64, s0
	global_store_short v[4:5], v2, off offset:3072
	v_cvt_pk_bf16_f32 v2, v65, s0
	global_store_short v[4:5], v2, off offset:3328
	v_cvt_pk_bf16_f32 v2, v66, s0
	global_store_short v[4:5], v2, off offset:3584
	v_cvt_pk_bf16_f32 v2, v67, s0
	s_movk_i32 s24, 0x7000
	global_store_short v[4:5], v2, off offset:3840
	v_add_co_u32_e32 v2, vcc, s24, v84
	v_cvt_pk_bf16_f32 v4, v68, s0
	s_nop 0
	v_addc_co_u32_e32 v3, vcc, 0, v85, vcc
	global_store_short v[2:3], v4, off
	v_cvt_pk_bf16_f32 v4, v69, s0
	global_store_short v[2:3], v4, off offset:256
	v_cvt_pk_bf16_f32 v4, v70, s0
	global_store_short v[2:3], v4, off offset:512
	v_cvt_pk_bf16_f32 v4, v71, s0
	global_store_short v[2:3], v4, off offset:768
	v_cvt_pk_bf16_f32 v4, v72, s0
	global_store_short v[2:3], v4, off offset:1024
	v_cvt_pk_bf16_f32 v4, v73, s0
	global_store_short v[2:3], v4, off offset:1280
	v_cvt_pk_bf16_f32 v4, v74, s0
	global_store_short v[2:3], v4, off offset:1536
	v_cvt_pk_bf16_f32 v4, v75, s0
	global_store_short v[2:3], v4, off offset:1792
	v_cvt_pk_bf16_f32 v4, v76, s0
	global_store_short v[2:3], v4, off offset:2048
	v_cvt_pk_bf16_f32 v4, v77, s0
	global_store_short v[2:3], v4, off offset:2304
	v_cvt_pk_bf16_f32 v4, v78, s0
	global_store_short v[2:3], v4, off offset:2560
	v_cvt_pk_bf16_f32 v4, v79, s0
	global_store_short v[2:3], v4, off offset:2816
	v_cvt_pk_bf16_f32 v4, v80, s0
	global_store_short v[2:3], v4, off offset:3072
	v_cvt_pk_bf16_f32 v4, v81, s0
	global_store_short v[2:3], v4, off offset:3328
	v_cvt_pk_bf16_f32 v4, v82, s0
	global_store_short v[2:3], v4, off offset:3584
	v_cvt_pk_bf16_f32 v4, v11, s0
	global_store_short v[2:3], v4, off offset:3840
	s_andn2_saveexec_b64 s[0:1], s[0:1]
	s_cbranch_execnz .LBB0_942
